# MFMA block heads in the GEMM K-loops: s_setprio 1 moved in front of the barrier and the redundant s_waitcnt lgkmcnt(0) after it removed, so the first MFMA issues right at barrier release (on top of pe
# speedup vs baseline: 1.0281x; 1.0028x over previous
.LBB0_179:
	ds_read_b128 v[144:147], v153
	ds_read_b128 v[156:159], v153 offset:1024
	ds_read_b128 v[162:165], v153 offset:2048
	ds_read_b128 v[166:169], v153 offset:3072
	ds_read_b128 v[170:173], v154
	ds_read_b128 v[174:177], v154 offset:1024
	ds_read_b128 v[178:181], v154 offset:2048
	ds_read_b128 v[182:185], v154 offset:3072
	s_add_u32 s70, s68, 0xfff80080
	s_addc_u32 s71, s69, -1
	s_cmp_eq_u32 s88, 28
	s_cselect_b32 s73, s1, s71
	s_cselect_b32 s72, s3, s70
	s_cselect_b32 s71, s59, s87
	s_cselect_b32 s70, s61, s86
	v_lshl_add_u64 v[148:149], s[68:69], 0, v[136:137]
	s_add_i32 m0, s29, 0xc000
	ds_read_b128 v[186:189], v155
	ds_read_b128 v[190:193], v155 offset:1024
	ds_read_b128 v[194:197], v155 offset:2048
	ds_read_b128 v[198:201], v155 offset:3072
	ds_read_b128 v[202:205], v155 offset:4096
	ds_read_b128 v[206:209], v155 offset:5120
	ds_read_b128 v[214:217], v155 offset:6144
	ds_read_b128 v[218:221], v155 offset:7168
	global_load_lds_dwordx4 v[148:149], off
	v_lshl_add_u64 v[148:149], s[68:69], 0, v[138:139]
	s_add_i32 m0, s29, 0xe000
	s_nop 0
	global_load_lds_dwordx4 v[148:149], off
	s_waitcnt vmcnt(8)
	s_waitcnt lgkmcnt(0)
	s_setprio 1
	s_barrier
	v_mfma_f32_16x16x32_bf16 v[124:127], v[144:147], v[186:189], v[124:127]
	v_mfma_f32_16x16x32_bf16 v[120:123], v[162:165], v[186:189], v[120:123]
	v_mfma_f32_16x16x32_bf16 v[108:111], v[144:147], v[194:197], v[108:111]
	v_mfma_f32_16x16x32_bf16 v[104:107], v[162:165], v[194:197], v[104:107]
	v_mfma_f32_16x16x32_bf16 v[92:95], v[144:147], v[202:205], v[92:95]
	v_mfma_f32_16x16x32_bf16 v[88:91], v[162:165], v[202:205], v[88:91]
	v_mfma_f32_16x16x32_bf16 v[76:79], v[144:147], v[214:217], v[76:79]
	v_mfma_f32_16x16x32_bf16 v[72:75], v[162:165], v[214:217], v[72:75]
	v_mfma_f32_16x16x32_bf16 v[124:127], v[156:159], v[190:193], v[124:127]
	v_mfma_f32_16x16x32_bf16 v[120:123], v[166:169], v[190:193], v[120:123]
	v_mfma_f32_16x16x32_bf16 v[108:111], v[156:159], v[198:201], v[108:111]
	v_mfma_f32_16x16x32_bf16 v[104:107], v[166:169], v[198:201], v[104:107]
	v_mfma_f32_16x16x32_bf16 v[92:95], v[156:159], v[206:209], v[92:95]
	v_mfma_f32_16x16x32_bf16 v[88:91], v[166:169], v[206:209], v[88:91]
	v_mfma_f32_16x16x32_bf16 v[76:79], v[156:159], v[218:221], v[76:79]
	v_mfma_f32_16x16x32_bf16 v[72:75], v[166:169], v[218:221], v[72:75]
	s_setprio 0
	s_setprio 1
	v_mfma_f32_16x16x32_bf16 v[116:119], v[170:173], v[186:189], v[116:119]
	v_mfma_f32_16x16x32_bf16 v[112:115], v[178:181], v[186:189], v[112:115]
	v_mfma_f32_16x16x32_bf16 v[100:103], v[170:173], v[194:197], v[100:103]
	v_mfma_f32_16x16x32_bf16 v[96:99], v[178:181], v[194:197], v[96:99]
	v_mfma_f32_16x16x32_bf16 v[84:87], v[170:173], v[202:205], v[84:87]
	v_mfma_f32_16x16x32_bf16 v[80:83], v[178:181], v[202:205], v[80:83]
	v_mfma_f32_16x16x32_bf16 v[68:71], v[170:173], v[214:217], v[68:71]
	v_mfma_f32_16x16x32_bf16 v[64:67], v[178:181], v[214:217], v[64:67]
	v_mfma_f32_16x16x32_bf16 v[116:119], v[174:177], v[190:193], v[116:119]
	v_mfma_f32_16x16x32_bf16 v[112:115], v[182:185], v[190:193], v[112:115]
	v_mfma_f32_16x16x32_bf16 v[100:103], v[174:177], v[198:201], v[100:103]
	v_mfma_f32_16x16x32_bf16 v[96:99], v[182:185], v[198:201], v[96:99]
	v_mfma_f32_16x16x32_bf16 v[84:87], v[174:177], v[206:209], v[84:87]
	v_mfma_f32_16x16x32_bf16 v[80:83], v[182:185], v[206:209], v[80:83]
	v_mfma_f32_16x16x32_bf16 v[68:71], v[174:177], v[218:221], v[68:71]
	v_mfma_f32_16x16x32_bf16 v[64:67], v[182:185], v[218:221], v[64:67]
	s_setprio 0
	s_barrier
	s_add_i32 s89, s79, s28
	v_lshl_add_u64 v[148:149], s[70:71], 0, v[132:133]
	s_mov_b32 m0, s89
	ds_read_b128 v[186:189], v155 offset:16384
	ds_read_b128 v[190:193], v155 offset:17408
	ds_read_b128 v[194:197], v155 offset:18432
	ds_read_b128 v[198:201], v155 offset:19456
	ds_read_b128 v[202:205], v155 offset:20480
	ds_read_b128 v[206:209], v155 offset:21504
	ds_read_b128 v[214:217], v155 offset:22528
	ds_read_b128 v[218:221], v155 offset:23552
	global_load_lds_dwordx4 v[148:149], off
	s_add_i32 m0, s89, 0x2000
	s_add_u32 s90, s70, 0x80000
	v_lshl_add_u64 v[210:211], s[70:71], 0, v[128:129]
	s_addc_u32 s91, s71, 0
	s_add_i32 s89, s80, s28
	global_load_lds_dwordx4 v[210:211], off
	v_lshl_add_u64 v[222:223], s[90:91], 0, v[132:133]
	s_mov_b32 m0, s89
	v_lshl_add_u64 v[224:225], s[72:73], 0, v[130:131]
	global_load_lds_dwordx4 v[222:223], off
	v_lshl_add_u64 v[222:223], s[90:91], 0, v[128:129]
	s_add_i32 m0, s89, 0x2000
	s_nop 0
	global_load_lds_dwordx4 v[222:223], off
	v_lshl_add_u64 v[222:223], s[72:73], 0, v[134:135]
	s_mov_b32 m0, s29
	s_nop 0
	global_load_lds_dwordx4 v[222:223], off
	s_mov_b32 m0, s30
	s_nop 0
	global_load_lds_dwordx4 v[224:225], off
	s_waitcnt vmcnt(8)
	s_waitcnt lgkmcnt(0)
	s_setprio 1
	s_barrier
	v_mfma_f32_16x16x32_bf16 v[60:63], v[144:147], v[186:189], v[60:63]
	v_mfma_f32_16x16x32_bf16 v[56:59], v[162:165], v[186:189], v[56:59]
	v_mfma_f32_16x16x32_bf16 v[44:47], v[144:147], v[194:197], v[44:47]
	v_mfma_f32_16x16x32_bf16 v[40:43], v[162:165], v[194:197], v[40:43]
	v_mfma_f32_16x16x32_bf16 v[28:31], v[144:147], v[202:205], v[28:31]
	v_mfma_f32_16x16x32_bf16 v[24:27], v[162:165], v[202:205], v[24:27]
	v_mfma_f32_16x16x32_bf16 v[12:15], v[144:147], v[214:217], v[12:15]
	v_mfma_f32_16x16x32_bf16 v[8:11], v[162:165], v[214:217], v[8:11]
	v_mfma_f32_16x16x32_bf16 v[60:63], v[156:159], v[190:193], v[60:63]
	v_mfma_f32_16x16x32_bf16 v[56:59], v[166:169], v[190:193], v[56:59]
	v_mfma_f32_16x16x32_bf16 v[44:47], v[156:159], v[198:201], v[44:47]
	v_mfma_f32_16x16x32_bf16 v[40:43], v[166:169], v[198:201], v[40:43]
	v_mfma_f32_16x16x32_bf16 v[28:31], v[156:159], v[206:209], v[28:31]
	v_mfma_f32_16x16x32_bf16 v[24:27], v[166:169], v[206:209], v[24:27]
	v_mfma_f32_16x16x32_bf16 v[12:15], v[156:159], v[218:221], v[12:15]
	v_mfma_f32_16x16x32_bf16 v[8:11], v[166:169], v[218:221], v[8:11]
	s_setprio 0
	s_setprio 1
	v_mfma_f32_16x16x32_bf16 v[52:55], v[170:173], v[186:189], v[52:55]
	v_mfma_f32_16x16x32_bf16 v[48:51], v[178:181], v[186:189], v[48:51]
	v_mfma_f32_16x16x32_bf16 v[36:39], v[170:173], v[194:197], v[36:39]
	v_mfma_f32_16x16x32_bf16 v[32:35], v[178:181], v[194:197], v[32:35]
	v_mfma_f32_16x16x32_bf16 v[20:23], v[170:173], v[202:205], v[20:23]
	v_mfma_f32_16x16x32_bf16 v[16:19], v[178:181], v[202:205], v[16:19]
	v_mfma_f32_16x16x32_bf16 v[4:7], v[170:173], v[214:217], v[4:7]
	v_mfma_f32_16x16x32_bf16 v[0:3], v[178:181], v[214:217], v[0:3]
	v_mfma_f32_16x16x32_bf16 v[52:55], v[174:177], v[190:193], v[52:55]
	v_mfma_f32_16x16x32_bf16 v[48:51], v[182:185], v[190:193], v[48:51]
	v_mfma_f32_16x16x32_bf16 v[36:39], v[174:177], v[198:201], v[36:39]
	v_mfma_f32_16x16x32_bf16 v[32:35], v[182:185], v[198:201], v[32:35]
	v_mfma_f32_16x16x32_bf16 v[20:23], v[174:177], v[206:209], v[20:23]
	v_mfma_f32_16x16x32_bf16 v[16:19], v[182:185], v[206:209], v[16:19]
	v_mfma_f32_16x16x32_bf16 v[4:7], v[174:177], v[218:221], v[4:7]
	v_mfma_f32_16x16x32_bf16 v[0:3], v[182:185], v[218:221], v[0:3]
	s_setprio 0
	s_barrier
	s_add_i32 s89, 0, 0x18000
	v_add_u32_e32 v161, s89, v151
	s_add_i32 s90, 0, 0x1c000
	ds_read_b128 v[144:147], v161
	ds_read_b128 v[156:159], v161 offset:1024
	ds_read_b128 v[162:165], v161 offset:2048
	ds_read_b128 v[166:169], v161 offset:3072
	v_add_u32_e32 v161, s90, v151
	ds_read_b128 v[170:173], v161
	ds_read_b128 v[174:177], v161 offset:1024
	ds_read_b128 v[178:181], v161 offset:2048
	ds_read_b128 v[182:185], v161 offset:3072
	s_add_u32 s72, s72, 0x80000
	s_addc_u32 s73, s73, 0
	s_mov_b32 m0, s31
	v_lshl_add_u64 v[226:227], s[72:73], 0, v[134:135]
	ds_read_b128 v[186:189], v155 offset:32768
	ds_read_b128 v[190:193], v155 offset:33792
	ds_read_b128 v[194:197], v155 offset:34816
	ds_read_b128 v[198:201], v155 offset:35840
	ds_read_b128 v[202:205], v155 offset:36864
	ds_read_b128 v[206:209], v155 offset:37888
	ds_read_b128 v[214:217], v155 offset:38912
	ds_read_b128 v[218:221], v155 offset:39936
	global_load_lds_dwordx4 v[226:227], off
	v_lshl_add_u64 v[226:227], s[72:73], 0, v[130:131]
	s_mov_b32 m0, s37
	s_nop 0
	global_load_lds_dwordx4 v[226:227], off
	s_waitcnt vmcnt(8)
	s_waitcnt lgkmcnt(0)
	s_setprio 1
	s_barrier
	v_mfma_f32_16x16x32_bf16 v[124:127], v[144:147], v[186:189], v[124:127]
	v_mfma_f32_16x16x32_bf16 v[120:123], v[162:165], v[186:189], v[120:123]
	v_mfma_f32_16x16x32_bf16 v[108:111], v[144:147], v[194:197], v[108:111]
	v_mfma_f32_16x16x32_bf16 v[104:107], v[162:165], v[194:197], v[104:107]
	v_mfma_f32_16x16x32_bf16 v[92:95], v[144:147], v[202:205], v[92:95]
	v_mfma_f32_16x16x32_bf16 v[88:91], v[162:165], v[202:205], v[88:91]
	v_mfma_f32_16x16x32_bf16 v[76:79], v[144:147], v[214:217], v[76:79]
	v_mfma_f32_16x16x32_bf16 v[72:75], v[162:165], v[214:217], v[72:75]
	v_mfma_f32_16x16x32_bf16 v[124:127], v[156:159], v[190:193], v[124:127]
	v_mfma_f32_16x16x32_bf16 v[120:123], v[166:169], v[190:193], v[120:123]
	v_mfma_f32_16x16x32_bf16 v[108:111], v[156:159], v[198:201], v[108:111]
	v_mfma_f32_16x16x32_bf16 v[104:107], v[166:169], v[198:201], v[104:107]
	v_mfma_f32_16x16x32_bf16 v[92:95], v[156:159], v[206:209], v[92:95]
	v_mfma_f32_16x16x32_bf16 v[88:91], v[166:169], v[206:209], v[88:91]
	v_mfma_f32_16x16x32_bf16 v[76:79], v[156:159], v[218:221], v[76:79]
	v_mfma_f32_16x16x32_bf16 v[72:75], v[166:169], v[218:221], v[72:75]
	s_setprio 0
	s_setprio 1
	v_mfma_f32_16x16x32_bf16 v[116:119], v[170:173], v[186:189], v[116:119]
	v_mfma_f32_16x16x32_bf16 v[112:115], v[178:181], v[186:189], v[112:115]
	v_mfma_f32_16x16x32_bf16 v[100:103], v[170:173], v[194:197], v[100:103]
	v_mfma_f32_16x16x32_bf16 v[96:99], v[178:181], v[194:197], v[96:99]
	v_mfma_f32_16x16x32_bf16 v[84:87], v[170:173], v[202:205], v[84:87]
	v_mfma_f32_16x16x32_bf16 v[80:83], v[178:181], v[202:205], v[80:83]
	v_mfma_f32_16x16x32_bf16 v[68:71], v[170:173], v[214:217], v[68:71]
	v_mfma_f32_16x16x32_bf16 v[64:67], v[178:181], v[214:217], v[64:67]
	v_mfma_f32_16x16x32_bf16 v[116:119], v[174:177], v[190:193], v[116:119]
	v_mfma_f32_16x16x32_bf16 v[112:115], v[182:185], v[190:193], v[112:115]
	v_mfma_f32_16x16x32_bf16 v[100:103], v[174:177], v[198:201], v[100:103]
	v_mfma_f32_16x16x32_bf16 v[96:99], v[182:185], v[198:201], v[96:99]
	v_mfma_f32_16x16x32_bf16 v[84:87], v[174:177], v[206:209], v[84:87]
	v_mfma_f32_16x16x32_bf16 v[80:83], v[182:185], v[206:209], v[80:83]
	v_mfma_f32_16x16x32_bf16 v[68:71], v[174:177], v[218:221], v[68:71]
	v_mfma_f32_16x16x32_bf16 v[64:67], v[182:185], v[218:221], v[64:67]
	s_setprio 0
	s_barrier
	s_add_i32 s72, s89, s28
	v_lshl_add_u64 v[148:149], v[148:149], 0, s[26:27]
	s_mov_b32 m0, s72
	ds_read_b128 v[186:189], v155 offset:49152
	ds_read_b128 v[190:193], v155 offset:50176
	ds_read_b128 v[194:197], v155 offset:51200
	ds_read_b128 v[198:201], v155 offset:52224
	ds_read_b128 v[202:205], v155 offset:53248
	ds_read_b128 v[206:209], v155 offset:54272
	ds_read_b128 v[214:217], v155 offset:55296
	ds_read_b128 v[218:221], v155 offset:56320
	global_load_lds_dwordx4 v[148:149], off
	s_add_i32 m0, s72, 0x2000
	s_add_u32 s70, s70, 0x80080
	v_lshl_add_u64 v[148:149], v[210:211], 0, s[26:27]
	s_addc_u32 s71, s71, 0
	s_add_i32 s72, s90, s28
	global_load_lds_dwordx4 v[148:149], off
	v_lshl_add_u64 v[148:149], s[70:71], 0, v[132:133]
	s_mov_b32 m0, s72
	s_nop 0
	global_load_lds_dwordx4 v[148:149], off
	v_lshl_add_u64 v[148:149], s[70:71], 0, v[128:129]
	s_add_i32 m0, s72, 0x2000
	s_nop 0
	global_load_lds_dwordx4 v[148:149], off
	v_lshl_add_u64 v[148:149], v[222:223], 0, s[26:27]
	s_mov_b32 m0, s76
	s_nop 0
	global_load_lds_dwordx4 v[148:149], off
	v_lshl_add_u64 v[148:149], v[224:225], 0, s[26:27]
	s_mov_b32 m0, s77
	s_nop 0
	global_load_lds_dwordx4 v[148:149], off
	s_waitcnt vmcnt(8)
	s_waitcnt lgkmcnt(0)
	s_setprio 1
	s_barrier
	v_mfma_f32_16x16x32_bf16 v[60:63], v[144:147], v[186:189], v[60:63]
	v_mfma_f32_16x16x32_bf16 v[56:59], v[162:165], v[186:189], v[56:59]
	v_mfma_f32_16x16x32_bf16 v[44:47], v[144:147], v[194:197], v[44:47]
	v_mfma_f32_16x16x32_bf16 v[40:43], v[162:165], v[194:197], v[40:43]
	v_mfma_f32_16x16x32_bf16 v[28:31], v[144:147], v[202:205], v[28:31]
	v_mfma_f32_16x16x32_bf16 v[24:27], v[162:165], v[202:205], v[24:27]
	v_mfma_f32_16x16x32_bf16 v[12:15], v[144:147], v[214:217], v[12:15]
	v_mfma_f32_16x16x32_bf16 v[8:11], v[162:165], v[214:217], v[8:11]
	v_mfma_f32_16x16x32_bf16 v[60:63], v[156:159], v[190:193], v[60:63]
	v_mfma_f32_16x16x32_bf16 v[56:59], v[166:169], v[190:193], v[56:59]
	v_mfma_f32_16x16x32_bf16 v[44:47], v[156:159], v[198:201], v[44:47]
	v_mfma_f32_16x16x32_bf16 v[40:43], v[166:169], v[198:201], v[40:43]
	v_mfma_f32_16x16x32_bf16 v[28:31], v[156:159], v[206:209], v[28:31]
	v_mfma_f32_16x16x32_bf16 v[24:27], v[166:169], v[206:209], v[24:27]
	v_mfma_f32_16x16x32_bf16 v[12:15], v[156:159], v[218:221], v[12:15]
	v_mfma_f32_16x16x32_bf16 v[8:11], v[166:169], v[218:221], v[8:11]
	s_setprio 0
	s_setprio 1
	v_mfma_f32_16x16x32_bf16 v[52:55], v[170:173], v[186:189], v[52:55]
	v_mfma_f32_16x16x32_bf16 v[48:51], v[178:181], v[186:189], v[48:51]
	v_mfma_f32_16x16x32_bf16 v[36:39], v[170:173], v[194:197], v[36:39]
	v_mfma_f32_16x16x32_bf16 v[32:35], v[178:181], v[194:197], v[32:35]
	v_mfma_f32_16x16x32_bf16 v[20:23], v[170:173], v[202:205], v[20:23]
	v_mfma_f32_16x16x32_bf16 v[16:19], v[178:181], v[202:205], v[16:19]
	v_mfma_f32_16x16x32_bf16 v[4:7], v[170:173], v[214:217], v[4:7]
	v_mfma_f32_16x16x32_bf16 v[0:3], v[178:181], v[214:217], v[0:3]
	v_mfma_f32_16x16x32_bf16 v[52:55], v[174:177], v[190:193], v[52:55]
	v_mfma_f32_16x16x32_bf16 v[48:51], v[182:185], v[190:193], v[48:51]
	v_mfma_f32_16x16x32_bf16 v[36:39], v[174:177], v[198:201], v[36:39]
	v_mfma_f32_16x16x32_bf16 v[32:35], v[182:185], v[198:201], v[32:35]
	v_mfma_f32_16x16x32_bf16 v[20:23], v[174:177], v[206:209], v[20:23]
	v_mfma_f32_16x16x32_bf16 v[16:19], v[182:185], v[206:209], v[16:19]
	v_mfma_f32_16x16x32_bf16 v[4:7], v[174:177], v[218:221], v[4:7]
	v_mfma_f32_16x16x32_bf16 v[0:3], v[182:185], v[218:221], v[0:3]
	s_setprio 0
	s_barrier
	s_add_i32 s88, s88, 2
	s_add_u32 s68, s68, 0x100
	s_addc_u32 s69, s69, 0
	s_add_u32 s86, s86, 0x100
	s_addc_u32 s87, s87, 0
	s_cmp_gt_u32 s88, 29
	s_cbranch_scc0 .LBB0_179
	s_and_b64 vcc, exec, s[34:35]
	s_cbranch_vccz .LBB0_182
	s_barrier

.LBB0_208:
	ds_read_b128 v[144:147], v164
	ds_read_b128 v[148:151], v164 offset:1024
	ds_read_b128 v[152:155], v164 offset:2048
	ds_read_b128 v[156:159], v164 offset:3072
	ds_read_b128 v[168:171], v165
	ds_read_b128 v[172:175], v165 offset:1024
	ds_read_b128 v[176:179], v165 offset:2048
	ds_read_b128 v[180:183], v165 offset:3072
	s_add_u32 s70, s68, 0xfff80080
	s_addc_u32 s71, s69, -1
	s_cmp_eq_u32 s67, 28
	s_cselect_b32 s73, s0, s71
	s_cselect_b32 s72, s1, s70
	s_cselect_b32 s71, s3, s65
	s_cselect_b32 s70, s57, s59
	v_lshl_add_u64 v[218:219], s[68:69], 0, v[136:137]
	s_add_i32 m0, s31, 0xc000
	ds_read_b128 v[184:187], v166
	ds_read_b128 v[188:191], v166 offset:1024
	ds_read_b128 v[192:195], v166 offset:2048
	ds_read_b128 v[196:199], v166 offset:3072
	ds_read_b128 v[200:203], v166 offset:4096
	ds_read_b128 v[204:207], v166 offset:5120
	ds_read_b128 v[208:211], v166 offset:6144
	ds_read_b128 v[214:217], v166 offset:7168
	global_load_lds_dwordx4 v[218:219], off
	v_lshl_add_u64 v[218:219], s[68:69], 0, v[138:139]
	s_add_i32 m0, s31, 0xe000
	s_nop 0
	global_load_lds_dwordx4 v[218:219], off
	s_waitcnt vmcnt(8)
	s_waitcnt lgkmcnt(0)
	s_setprio 1
	s_barrier
	v_mfma_f32_16x16x32_bf16 v[124:127], v[144:147], v[184:187], v[124:127]
	v_mfma_f32_16x16x32_bf16 v[120:123], v[152:155], v[184:187], v[120:123]
	v_mfma_f32_16x16x32_bf16 v[108:111], v[144:147], v[192:195], v[108:111]
	v_mfma_f32_16x16x32_bf16 v[104:107], v[152:155], v[192:195], v[104:107]
	v_mfma_f32_16x16x32_bf16 v[92:95], v[144:147], v[200:203], v[92:95]
	v_mfma_f32_16x16x32_bf16 v[88:91], v[152:155], v[200:203], v[88:91]
	v_mfma_f32_16x16x32_bf16 v[76:79], v[144:147], v[208:211], v[76:79]
	v_mfma_f32_16x16x32_bf16 v[72:75], v[152:155], v[208:211], v[72:75]
	v_mfma_f32_16x16x32_bf16 v[124:127], v[148:151], v[188:191], v[124:127]
	v_mfma_f32_16x16x32_bf16 v[120:123], v[156:159], v[188:191], v[120:123]
	v_mfma_f32_16x16x32_bf16 v[108:111], v[148:151], v[196:199], v[108:111]
	v_mfma_f32_16x16x32_bf16 v[104:107], v[156:159], v[196:199], v[104:107]
	v_mfma_f32_16x16x32_bf16 v[92:95], v[148:151], v[204:207], v[92:95]
	v_mfma_f32_16x16x32_bf16 v[88:91], v[156:159], v[204:207], v[88:91]
	v_mfma_f32_16x16x32_bf16 v[76:79], v[148:151], v[214:217], v[76:79]
	v_mfma_f32_16x16x32_bf16 v[72:75], v[156:159], v[214:217], v[72:75]
	s_setprio 0
	s_setprio 1
	v_mfma_f32_16x16x32_bf16 v[116:119], v[168:171], v[184:187], v[116:119]
	v_mfma_f32_16x16x32_bf16 v[112:115], v[176:179], v[184:187], v[112:115]
	v_mfma_f32_16x16x32_bf16 v[100:103], v[168:171], v[192:195], v[100:103]
	v_mfma_f32_16x16x32_bf16 v[96:99], v[176:179], v[192:195], v[96:99]
	v_mfma_f32_16x16x32_bf16 v[84:87], v[168:171], v[200:203], v[84:87]
	v_mfma_f32_16x16x32_bf16 v[80:83], v[176:179], v[200:203], v[80:83]
	v_mfma_f32_16x16x32_bf16 v[68:71], v[168:171], v[208:211], v[68:71]
	v_mfma_f32_16x16x32_bf16 v[64:67], v[176:179], v[208:211], v[64:67]
	v_mfma_f32_16x16x32_bf16 v[116:119], v[172:175], v[188:191], v[116:119]
	v_mfma_f32_16x16x32_bf16 v[112:115], v[180:183], v[188:191], v[112:115]
	v_mfma_f32_16x16x32_bf16 v[100:103], v[172:175], v[196:199], v[100:103]
	v_mfma_f32_16x16x32_bf16 v[96:99], v[180:183], v[196:199], v[96:99]
	v_mfma_f32_16x16x32_bf16 v[84:87], v[172:175], v[204:207], v[84:87]
	v_mfma_f32_16x16x32_bf16 v[80:83], v[180:183], v[204:207], v[80:83]
	v_mfma_f32_16x16x32_bf16 v[68:71], v[172:175], v[214:217], v[68:71]
	v_mfma_f32_16x16x32_bf16 v[64:67], v[180:183], v[214:217], v[64:67]
	s_setprio 0
	s_barrier
	s_add_i32 s90, s84, s30
	v_lshl_add_u64 v[218:219], s[70:71], 0, v[130:131]
	s_mov_b32 m0, s90
	ds_read_b128 v[184:187], v166 offset:16384
	ds_read_b128 v[188:191], v166 offset:17408
	ds_read_b128 v[192:195], v166 offset:18432
	ds_read_b128 v[196:199], v166 offset:19456
	ds_read_b128 v[200:203], v166 offset:20480
	ds_read_b128 v[204:207], v166 offset:21504
	ds_read_b128 v[208:211], v166 offset:22528
	ds_read_b128 v[214:217], v166 offset:23552
	global_load_lds_dwordx4 v[218:219], off
	s_add_i32 m0, s90, 0x2000
	s_add_u32 s90, s70, 0x80000
	v_lshl_add_u64 v[220:221], s[70:71], 0, v[134:135]
	s_addc_u32 s91, s71, 0
	s_add_i32 s92, s85, s30
	global_load_lds_dwordx4 v[220:221], off
	v_lshl_add_u64 v[222:223], s[90:91], 0, v[130:131]
	s_mov_b32 m0, s92
	v_lshl_add_u64 v[224:225], s[72:73], 0, v[132:133]
	global_load_lds_dwordx4 v[222:223], off
	v_lshl_add_u64 v[222:223], s[90:91], 0, v[134:135]
	s_add_i32 m0, s92, 0x2000
	s_nop 0
	global_load_lds_dwordx4 v[222:223], off
	v_lshl_add_u64 v[222:223], s[72:73], 0, v[128:129]
	s_mov_b32 m0, s31
	s_nop 0
	global_load_lds_dwordx4 v[222:223], off
	s_mov_b32 m0, s76
	s_nop 0
	global_load_lds_dwordx4 v[224:225], off
	s_waitcnt vmcnt(8)
	s_waitcnt lgkmcnt(0)
	s_setprio 1
	s_barrier
	v_mfma_f32_16x16x32_bf16 v[60:63], v[144:147], v[184:187], v[60:63]
	v_mfma_f32_16x16x32_bf16 v[56:59], v[152:155], v[184:187], v[56:59]
	v_mfma_f32_16x16x32_bf16 v[44:47], v[144:147], v[192:195], v[44:47]
	v_mfma_f32_16x16x32_bf16 v[40:43], v[152:155], v[192:195], v[40:43]
	v_mfma_f32_16x16x32_bf16 v[28:31], v[144:147], v[200:203], v[28:31]
	v_mfma_f32_16x16x32_bf16 v[24:27], v[152:155], v[200:203], v[24:27]
	v_mfma_f32_16x16x32_bf16 v[12:15], v[144:147], v[208:211], v[12:15]
	v_mfma_f32_16x16x32_bf16 v[8:11], v[152:155], v[208:211], v[8:11]
	v_mfma_f32_16x16x32_bf16 v[60:63], v[148:151], v[188:191], v[60:63]
	v_mfma_f32_16x16x32_bf16 v[56:59], v[156:159], v[188:191], v[56:59]
	v_mfma_f32_16x16x32_bf16 v[44:47], v[148:151], v[196:199], v[44:47]
	v_mfma_f32_16x16x32_bf16 v[40:43], v[156:159], v[196:199], v[40:43]
	v_mfma_f32_16x16x32_bf16 v[28:31], v[148:151], v[204:207], v[28:31]
	v_mfma_f32_16x16x32_bf16 v[24:27], v[156:159], v[204:207], v[24:27]
	v_mfma_f32_16x16x32_bf16 v[12:15], v[148:151], v[214:217], v[12:15]
	v_mfma_f32_16x16x32_bf16 v[8:11], v[156:159], v[214:217], v[8:11]
	s_setprio 0
	s_setprio 1
	v_mfma_f32_16x16x32_bf16 v[52:55], v[168:171], v[184:187], v[52:55]
	v_mfma_f32_16x16x32_bf16 v[48:51], v[176:179], v[184:187], v[48:51]
	v_mfma_f32_16x16x32_bf16 v[36:39], v[168:171], v[192:195], v[36:39]
	v_mfma_f32_16x16x32_bf16 v[32:35], v[176:179], v[192:195], v[32:35]
	v_mfma_f32_16x16x32_bf16 v[20:23], v[168:171], v[200:203], v[20:23]
	v_mfma_f32_16x16x32_bf16 v[16:19], v[176:179], v[200:203], v[16:19]
	v_mfma_f32_16x16x32_bf16 v[4:7], v[168:171], v[208:211], v[4:7]
	v_mfma_f32_16x16x32_bf16 v[0:3], v[176:179], v[208:211], v[0:3]
	v_mfma_f32_16x16x32_bf16 v[52:55], v[172:175], v[188:191], v[52:55]
	v_mfma_f32_16x16x32_bf16 v[48:51], v[180:183], v[188:191], v[48:51]
	v_mfma_f32_16x16x32_bf16 v[36:39], v[172:175], v[196:199], v[36:39]
	v_mfma_f32_16x16x32_bf16 v[32:35], v[180:183], v[196:199], v[32:35]
	v_mfma_f32_16x16x32_bf16 v[20:23], v[172:175], v[204:207], v[20:23]
	v_mfma_f32_16x16x32_bf16 v[16:19], v[180:183], v[204:207], v[16:19]
	v_mfma_f32_16x16x32_bf16 v[4:7], v[172:175], v[214:217], v[4:7]
	v_mfma_f32_16x16x32_bf16 v[0:3], v[180:183], v[214:217], v[0:3]
	s_setprio 0
	s_barrier
	s_add_i32 s90, 0, 0x18000
	s_add_i32 s91, 0, 0x1c000
	v_add_u32_e32 v156, s90, v162
	v_add_u32_e32 v167, s91, v162
	ds_read_b128 v[144:147], v156
	ds_read_b128 v[148:151], v156 offset:1024
	ds_read_b128 v[152:155], v156 offset:2048
	ds_read_b128 v[156:159], v156 offset:3072
	ds_read_b128 v[168:171], v167
	ds_read_b128 v[172:175], v167 offset:1024
	ds_read_b128 v[176:179], v167 offset:2048
	ds_read_b128 v[180:183], v167 offset:3072
	s_add_u32 s72, s72, 0x80000
	s_addc_u32 s73, s73, 0
	s_mov_b32 m0, s77
	v_lshl_add_u64 v[226:227], s[72:73], 0, v[128:129]
	ds_read_b128 v[184:187], v166 offset:32768
	ds_read_b128 v[188:191], v166 offset:33792
	ds_read_b128 v[192:195], v166 offset:34816
	ds_read_b128 v[196:199], v166 offset:35840
	ds_read_b128 v[200:203], v166 offset:36864
	ds_read_b128 v[204:207], v166 offset:37888
	ds_read_b128 v[208:211], v166 offset:38912
	ds_read_b128 v[214:217], v166 offset:39936
	global_load_lds_dwordx4 v[226:227], off
	v_lshl_add_u64 v[226:227], s[72:73], 0, v[132:133]
	s_mov_b32 m0, s78
	s_nop 0
	global_load_lds_dwordx4 v[226:227], off
	s_waitcnt vmcnt(8)
	s_waitcnt lgkmcnt(0)
	s_setprio 1
	s_barrier
	v_mfma_f32_16x16x32_bf16 v[124:127], v[144:147], v[184:187], v[124:127]
	v_mfma_f32_16x16x32_bf16 v[120:123], v[152:155], v[184:187], v[120:123]
	v_mfma_f32_16x16x32_bf16 v[108:111], v[144:147], v[192:195], v[108:111]
	v_mfma_f32_16x16x32_bf16 v[104:107], v[152:155], v[192:195], v[104:107]
	v_mfma_f32_16x16x32_bf16 v[92:95], v[144:147], v[200:203], v[92:95]
	v_mfma_f32_16x16x32_bf16 v[88:91], v[152:155], v[200:203], v[88:91]
	v_mfma_f32_16x16x32_bf16 v[76:79], v[144:147], v[208:211], v[76:79]
	v_mfma_f32_16x16x32_bf16 v[72:75], v[152:155], v[208:211], v[72:75]
	v_mfma_f32_16x16x32_bf16 v[124:127], v[148:151], v[188:191], v[124:127]
	v_mfma_f32_16x16x32_bf16 v[120:123], v[156:159], v[188:191], v[120:123]
	v_mfma_f32_16x16x32_bf16 v[108:111], v[148:151], v[196:199], v[108:111]
	v_mfma_f32_16x16x32_bf16 v[104:107], v[156:159], v[196:199], v[104:107]
	v_mfma_f32_16x16x32_bf16 v[92:95], v[148:151], v[204:207], v[92:95]
	v_mfma_f32_16x16x32_bf16 v[88:91], v[156:159], v[204:207], v[88:91]
	v_mfma_f32_16x16x32_bf16 v[76:79], v[148:151], v[214:217], v[76:79]
	v_mfma_f32_16x16x32_bf16 v[72:75], v[156:159], v[214:217], v[72:75]
	s_setprio 0
	s_setprio 1
	v_mfma_f32_16x16x32_bf16 v[116:119], v[168:171], v[184:187], v[116:119]
	v_mfma_f32_16x16x32_bf16 v[112:115], v[176:179], v[184:187], v[112:115]
	v_mfma_f32_16x16x32_bf16 v[100:103], v[168:171], v[192:195], v[100:103]
	v_mfma_f32_16x16x32_bf16 v[96:99], v[176:179], v[192:195], v[96:99]
	v_mfma_f32_16x16x32_bf16 v[84:87], v[168:171], v[200:203], v[84:87]
	v_mfma_f32_16x16x32_bf16 v[80:83], v[176:179], v[200:203], v[80:83]
	v_mfma_f32_16x16x32_bf16 v[68:71], v[168:171], v[208:211], v[68:71]
	v_mfma_f32_16x16x32_bf16 v[64:67], v[176:179], v[208:211], v[64:67]
	v_mfma_f32_16x16x32_bf16 v[116:119], v[172:175], v[188:191], v[116:119]
	v_mfma_f32_16x16x32_bf16 v[112:115], v[180:183], v[188:191], v[112:115]
	v_mfma_f32_16x16x32_bf16 v[100:103], v[172:175], v[196:199], v[100:103]
	v_mfma_f32_16x16x32_bf16 v[96:99], v[180:183], v[196:199], v[96:99]
	v_mfma_f32_16x16x32_bf16 v[84:87], v[172:175], v[204:207], v[84:87]
	v_mfma_f32_16x16x32_bf16 v[80:83], v[180:183], v[204:207], v[80:83]
	v_mfma_f32_16x16x32_bf16 v[68:71], v[172:175], v[214:217], v[68:71]
	v_mfma_f32_16x16x32_bf16 v[64:67], v[180:183], v[214:217], v[64:67]
	s_setprio 0
	s_barrier
	s_add_i32 s72, s90, s30
	v_lshl_add_u64 v[218:219], v[218:219], 0, s[34:35]
	s_mov_b32 m0, s72
	ds_read_b128 v[184:187], v166 offset:49152
	ds_read_b128 v[188:191], v166 offset:50176
	ds_read_b128 v[192:195], v166 offset:51200
	ds_read_b128 v[196:199], v166 offset:52224
	ds_read_b128 v[200:203], v166 offset:53248
	ds_read_b128 v[204:207], v166 offset:54272
	ds_read_b128 v[208:211], v166 offset:55296
	ds_read_b128 v[214:217], v166 offset:56320
	global_load_lds_dwordx4 v[218:219], off
	s_add_i32 m0, s72, 0x2000
	s_add_u32 s70, s70, 0x80080
	v_lshl_add_u64 v[218:219], v[220:221], 0, s[34:35]
	s_addc_u32 s71, s71, 0
	s_add_i32 s72, s91, s30
	global_load_lds_dwordx4 v[218:219], off
	v_lshl_add_u64 v[218:219], s[70:71], 0, v[130:131]
	s_mov_b32 m0, s72
	s_nop 0
	global_load_lds_dwordx4 v[218:219], off
	v_lshl_add_u64 v[218:219], s[70:71], 0, v[134:135]
	s_add_i32 m0, s72, 0x2000
	s_nop 0
	global_load_lds_dwordx4 v[218:219], off
	v_lshl_add_u64 v[218:219], v[222:223], 0, s[34:35]
	s_mov_b32 m0, s80
	s_nop 0
	global_load_lds_dwordx4 v[218:219], off
	v_lshl_add_u64 v[218:219], v[224:225], 0, s[34:35]
	s_mov_b32 m0, s81
	s_nop 0
	global_load_lds_dwordx4 v[218:219], off
	s_waitcnt vmcnt(8)
	s_waitcnt lgkmcnt(0)
	s_setprio 1
	s_barrier
	v_mfma_f32_16x16x32_bf16 v[60:63], v[144:147], v[184:187], v[60:63]
	v_mfma_f32_16x16x32_bf16 v[56:59], v[152:155], v[184:187], v[56:59]
	v_mfma_f32_16x16x32_bf16 v[44:47], v[144:147], v[192:195], v[44:47]
	v_mfma_f32_16x16x32_bf16 v[40:43], v[152:155], v[192:195], v[40:43]
	v_mfma_f32_16x16x32_bf16 v[28:31], v[144:147], v[200:203], v[28:31]
	v_mfma_f32_16x16x32_bf16 v[24:27], v[152:155], v[200:203], v[24:27]
	v_mfma_f32_16x16x32_bf16 v[12:15], v[144:147], v[208:211], v[12:15]
	v_mfma_f32_16x16x32_bf16 v[8:11], v[152:155], v[208:211], v[8:11]
	v_mfma_f32_16x16x32_bf16 v[60:63], v[148:151], v[188:191], v[60:63]
	v_mfma_f32_16x16x32_bf16 v[56:59], v[156:159], v[188:191], v[56:59]
	v_mfma_f32_16x16x32_bf16 v[44:47], v[148:151], v[196:199], v[44:47]
	v_mfma_f32_16x16x32_bf16 v[40:43], v[156:159], v[196:199], v[40:43]
	v_mfma_f32_16x16x32_bf16 v[28:31], v[148:151], v[204:207], v[28:31]
	v_mfma_f32_16x16x32_bf16 v[24:27], v[156:159], v[204:207], v[24:27]
	v_mfma_f32_16x16x32_bf16 v[12:15], v[148:151], v[214:217], v[12:15]
	v_mfma_f32_16x16x32_bf16 v[8:11], v[156:159], v[214:217], v[8:11]
	s_setprio 0
	s_setprio 1
	v_mfma_f32_16x16x32_bf16 v[52:55], v[168:171], v[184:187], v[52:55]
	v_mfma_f32_16x16x32_bf16 v[48:51], v[176:179], v[184:187], v[48:51]
	v_mfma_f32_16x16x32_bf16 v[36:39], v[168:171], v[192:195], v[36:39]
	v_mfma_f32_16x16x32_bf16 v[32:35], v[176:179], v[192:195], v[32:35]
	v_mfma_f32_16x16x32_bf16 v[20:23], v[168:171], v[200:203], v[20:23]
	v_mfma_f32_16x16x32_bf16 v[16:19], v[176:179], v[200:203], v[16:19]
	v_mfma_f32_16x16x32_bf16 v[4:7], v[168:171], v[208:211], v[4:7]
	v_mfma_f32_16x16x32_bf16 v[0:3], v[176:179], v[208:211], v[0:3]
	v_mfma_f32_16x16x32_bf16 v[52:55], v[172:175], v[188:191], v[52:55]
	v_mfma_f32_16x16x32_bf16 v[48:51], v[180:183], v[188:191], v[48:51]
	v_mfma_f32_16x16x32_bf16 v[36:39], v[172:175], v[196:199], v[36:39]
	v_mfma_f32_16x16x32_bf16 v[32:35], v[180:183], v[196:199], v[32:35]
	v_mfma_f32_16x16x32_bf16 v[20:23], v[172:175], v[204:207], v[20:23]
	v_mfma_f32_16x16x32_bf16 v[16:19], v[180:183], v[204:207], v[16:19]
	v_mfma_f32_16x16x32_bf16 v[4:7], v[172:175], v[214:217], v[4:7]
	v_mfma_f32_16x16x32_bf16 v[0:3], v[180:183], v[214:217], v[0:3]
	s_setprio 0
	s_barrier
	s_add_i32 s67, s67, 2
	s_add_u32 s68, s68, 0x100
	s_addc_u32 s69, s69, 0
	s_add_u32 s59, s59, 0x100
	s_addc_u32 s65, s65, 0
	s_cmp_gt_u32 s67, 29
	s_cbranch_scc0 .LBB0_208
	s_and_b64 vcc, exec, s[36:37]
	s_cbranch_vccz .LBB0_211
	s_barrier

.LBB0_271:
	s_ashr_i32 s63, s62, 31
	s_lshl_b64 s[0:1], s[62:63], 20
	s_add_u32 s66, s49, s0
	s_addc_u32 s67, s82, s1
	s_and_b64 s[0:1], s[4:5], exec
	s_cselect_b32 s0, s67, s75
	s_cselect_b32 s1, s66, s74
	s_ashr_i32 s65, s64, 31
	s_lshl_b64 s[68:69], s[64:65], 20
	s_add_u32 s68, s45, s68
	s_addc_u32 s69, s47, s69
	s_and_b64 s[78:79], s[4:5], exec
	s_cselect_b32 s3, s69, s77
	s_cselect_b32 s63, s68, s76
	s_add_u32 s74, s74, 0x80080
	s_addc_u32 s75, s75, 0
	s_add_u32 s65, s76, 0x100
	s_addc_u32 s71, s77, 0
	s_mov_b32 s90, -2
	s_waitcnt vmcnt(0)
	ds_read_b128 v[146:149], v166
	ds_read_b128 v[150:153], v166 offset:1024
	ds_read_b128 v[154:157], v166 offset:2048
	ds_read_b128 v[170:173], v166 offset:3072
	ds_read_b128 v[174:177], v167
	ds_read_b128 v[178:181], v167 offset:1024
	ds_read_b128 v[182:185], v167 offset:2048
	ds_read_b128 v[186:189], v167 offset:3072
	s_add_u32 s76, s74, 0xfff80080
	s_addc_u32 s77, s75, -1
	s_cmp_eq_u32 s90, 28
	s_cselect_b32 s79, s0, s77
	s_cselect_b32 s78, s1, s76
	s_cselect_b32 s77, s3, s71
	s_cselect_b32 s76, s63, s65
	v_lshl_add_u64 v[158:159], s[74:75], 0, v[138:139]
	s_add_i32 m0, s31, 0xc000
	ds_read_b128 v[190:193], v168
	ds_read_b128 v[194:197], v168 offset:1024
	ds_read_b128 v[198:201], v168 offset:2048
	ds_read_b128 v[202:205], v168 offset:3072
	ds_read_b128 v[206:209], v168 offset:4096
	ds_read_b128 v[214:217], v168 offset:5120
	ds_read_b128 v[218:221], v168 offset:6144
	ds_read_b128 v[222:225], v168 offset:7168
	global_load_lds_dwordx4 v[158:159], off
	v_lshl_add_u64 v[158:159], s[74:75], 0, v[140:141]
	s_add_i32 m0, s31, 0xe000
	s_nop 0
	global_load_lds_dwordx4 v[158:159], off
	s_waitcnt vmcnt(8)
	s_waitcnt lgkmcnt(0)
	s_setprio 1
	s_barrier
	v_mfma_f32_16x16x32_bf16 v[124:127], v[146:149], v[190:193], 0
	v_mfma_f32_16x16x32_bf16 v[120:123], v[154:157], v[190:193], 0
	v_mfma_f32_16x16x32_bf16 v[108:111], v[146:149], v[198:201], 0
	v_mfma_f32_16x16x32_bf16 v[104:107], v[154:157], v[198:201], 0
	v_mfma_f32_16x16x32_bf16 v[92:95], v[146:149], v[206:209], 0
	v_mfma_f32_16x16x32_bf16 v[88:91], v[154:157], v[206:209], 0
	v_mfma_f32_16x16x32_bf16 v[76:79], v[146:149], v[218:221], 0
	v_mfma_f32_16x16x32_bf16 v[72:75], v[154:157], v[218:221], 0
	v_mfma_f32_16x16x32_bf16 v[124:127], v[150:153], v[194:197], v[124:127]
	v_mfma_f32_16x16x32_bf16 v[120:123], v[170:173], v[194:197], v[120:123]
	v_mfma_f32_16x16x32_bf16 v[108:111], v[150:153], v[202:205], v[108:111]
	v_mfma_f32_16x16x32_bf16 v[104:107], v[170:173], v[202:205], v[104:107]
	v_mfma_f32_16x16x32_bf16 v[92:95], v[150:153], v[214:217], v[92:95]
	v_mfma_f32_16x16x32_bf16 v[88:91], v[170:173], v[214:217], v[88:91]
	v_mfma_f32_16x16x32_bf16 v[76:79], v[150:153], v[222:225], v[76:79]
	v_mfma_f32_16x16x32_bf16 v[72:75], v[170:173], v[222:225], v[72:75]
	s_setprio 0
	s_setprio 1
	v_mfma_f32_16x16x32_bf16 v[116:119], v[174:177], v[190:193], 0
	v_mfma_f32_16x16x32_bf16 v[112:115], v[182:185], v[190:193], 0
	v_mfma_f32_16x16x32_bf16 v[100:103], v[174:177], v[198:201], 0
	v_mfma_f32_16x16x32_bf16 v[96:99], v[182:185], v[198:201], 0
	v_mfma_f32_16x16x32_bf16 v[84:87], v[174:177], v[206:209], 0
	v_mfma_f32_16x16x32_bf16 v[80:83], v[182:185], v[206:209], 0
	v_mfma_f32_16x16x32_bf16 v[68:71], v[174:177], v[218:221], 0
	v_mfma_f32_16x16x32_bf16 v[64:67], v[182:185], v[218:221], 0
	v_mfma_f32_16x16x32_bf16 v[116:119], v[178:181], v[194:197], v[116:119]
	v_mfma_f32_16x16x32_bf16 v[112:115], v[186:189], v[194:197], v[112:115]
	v_mfma_f32_16x16x32_bf16 v[100:103], v[178:181], v[202:205], v[100:103]
	v_mfma_f32_16x16x32_bf16 v[96:99], v[186:189], v[202:205], v[96:99]
	v_mfma_f32_16x16x32_bf16 v[84:87], v[178:181], v[214:217], v[84:87]
	v_mfma_f32_16x16x32_bf16 v[80:83], v[186:189], v[214:217], v[80:83]
	v_mfma_f32_16x16x32_bf16 v[68:71], v[178:181], v[222:225], v[68:71]
	v_mfma_f32_16x16x32_bf16 v[64:67], v[186:189], v[222:225], v[64:67]
	s_setprio 0
	s_barrier
	s_add_i32 s91, s81, s30
	v_lshl_add_u64 v[158:159], s[76:77], 0, v[130:131]
	s_mov_b32 m0, s91
	ds_read_b128 v[190:193], v168 offset:16384
	ds_read_b128 v[194:197], v168 offset:17408
	ds_read_b128 v[198:201], v168 offset:18432
	ds_read_b128 v[202:205], v168 offset:19456
	ds_read_b128 v[206:209], v168 offset:20480
	ds_read_b128 v[214:217], v168 offset:21504
	ds_read_b128 v[218:221], v168 offset:22528
	ds_read_b128 v[222:225], v168 offset:23552
	global_load_lds_dwordx4 v[158:159], off
	s_add_i32 m0, s91, 0x2000
	s_add_u32 s92, s76, 0x80000
	v_lshl_add_u64 v[210:211], s[76:77], 0, v[134:135]
	s_addc_u32 s93, s77, 0
	s_add_i32 s91, s83, s30
	global_load_lds_dwordx4 v[210:211], off
	v_lshl_add_u64 v[226:227], s[92:93], 0, v[130:131]
	s_mov_b32 m0, s91
	v_lshl_add_u64 v[228:229], s[78:79], 0, v[132:133]
	global_load_lds_dwordx4 v[226:227], off
	v_lshl_add_u64 v[226:227], s[92:93], 0, v[134:135]
	s_add_i32 m0, s91, 0x2000
	s_nop 0
	global_load_lds_dwordx4 v[226:227], off
	v_lshl_add_u64 v[226:227], s[78:79], 0, v[128:129]
	s_mov_b32 m0, s31
	s_nop 0
	global_load_lds_dwordx4 v[226:227], off
	s_mov_b32 m0, s51
	s_nop 0
	global_load_lds_dwordx4 v[228:229], off
	s_waitcnt vmcnt(8)
	s_waitcnt lgkmcnt(0)
	s_setprio 1
	s_barrier
	v_mfma_f32_16x16x32_bf16 v[60:63], v[146:149], v[190:193], 0
	v_mfma_f32_16x16x32_bf16 v[56:59], v[154:157], v[190:193], 0
	v_mfma_f32_16x16x32_bf16 v[44:47], v[146:149], v[198:201], 0
	v_mfma_f32_16x16x32_bf16 v[40:43], v[154:157], v[198:201], 0
	v_mfma_f32_16x16x32_bf16 v[28:31], v[146:149], v[206:209], 0
	v_mfma_f32_16x16x32_bf16 v[24:27], v[154:157], v[206:209], 0
	v_mfma_f32_16x16x32_bf16 v[12:15], v[146:149], v[218:221], 0
	v_mfma_f32_16x16x32_bf16 v[8:11], v[154:157], v[218:221], 0
	v_mfma_f32_16x16x32_bf16 v[60:63], v[150:153], v[194:197], v[60:63]
	v_mfma_f32_16x16x32_bf16 v[56:59], v[170:173], v[194:197], v[56:59]
	v_mfma_f32_16x16x32_bf16 v[44:47], v[150:153], v[202:205], v[44:47]
	v_mfma_f32_16x16x32_bf16 v[40:43], v[170:173], v[202:205], v[40:43]
	v_mfma_f32_16x16x32_bf16 v[28:31], v[150:153], v[214:217], v[28:31]
	v_mfma_f32_16x16x32_bf16 v[24:27], v[170:173], v[214:217], v[24:27]
	v_mfma_f32_16x16x32_bf16 v[12:15], v[150:153], v[222:225], v[12:15]
	v_mfma_f32_16x16x32_bf16 v[8:11], v[170:173], v[222:225], v[8:11]
	s_setprio 0
	s_setprio 1
	v_mfma_f32_16x16x32_bf16 v[52:55], v[174:177], v[190:193], 0
	v_mfma_f32_16x16x32_bf16 v[48:51], v[182:185], v[190:193], 0
	v_mfma_f32_16x16x32_bf16 v[36:39], v[174:177], v[198:201], 0
	v_mfma_f32_16x16x32_bf16 v[32:35], v[182:185], v[198:201], 0
	v_mfma_f32_16x16x32_bf16 v[20:23], v[174:177], v[206:209], 0
	v_mfma_f32_16x16x32_bf16 v[16:19], v[182:185], v[206:209], 0
	v_mfma_f32_16x16x32_bf16 v[4:7], v[174:177], v[218:221], 0
	v_mfma_f32_16x16x32_bf16 v[0:3], v[182:185], v[218:221], 0
	v_mfma_f32_16x16x32_bf16 v[52:55], v[178:181], v[194:197], v[52:55]
	v_mfma_f32_16x16x32_bf16 v[48:51], v[186:189], v[194:197], v[48:51]
	v_mfma_f32_16x16x32_bf16 v[36:39], v[178:181], v[202:205], v[36:39]
	v_mfma_f32_16x16x32_bf16 v[32:35], v[186:189], v[202:205], v[32:35]
	v_mfma_f32_16x16x32_bf16 v[20:23], v[178:181], v[214:217], v[20:23]
	v_mfma_f32_16x16x32_bf16 v[16:19], v[186:189], v[214:217], v[16:19]
	v_mfma_f32_16x16x32_bf16 v[4:7], v[178:181], v[222:225], v[4:7]
	v_mfma_f32_16x16x32_bf16 v[0:3], v[186:189], v[222:225], v[0:3]
	s_setprio 0
	s_barrier
	s_add_i32 s91, 0, 0x18000
	v_add_u32_e32 v136, s91, v162
	s_add_i32 s92, 0, 0x1c000
	ds_read_b128 v[146:149], v136
	ds_read_b128 v[150:153], v136 offset:1024
	ds_read_b128 v[154:157], v136 offset:2048
	ds_read_b128 v[170:173], v136 offset:3072
	v_add_u32_e32 v136, s92, v162
	ds_read_b128 v[174:177], v136
	ds_read_b128 v[178:181], v136 offset:1024
	ds_read_b128 v[182:185], v136 offset:2048
	ds_read_b128 v[186:189], v136 offset:3072
	s_add_u32 s78, s78, 0x80000
	s_addc_u32 s79, s79, 0
	s_mov_b32 m0, s28
	v_lshl_add_u64 v[230:231], s[78:79], 0, v[128:129]
	ds_read_b128 v[190:193], v168 offset:32768
	ds_read_b128 v[194:197], v168 offset:33792
	ds_read_b128 v[198:201], v168 offset:34816
	ds_read_b128 v[202:205], v168 offset:35840
	ds_read_b128 v[206:209], v168 offset:36864
	ds_read_b128 v[214:217], v168 offset:37888
	ds_read_b128 v[218:221], v168 offset:38912
	ds_read_b128 v[222:225], v168 offset:39936
	global_load_lds_dwordx4 v[230:231], off
	v_lshl_add_u64 v[230:231], s[78:79], 0, v[132:133]
	s_mov_b32 m0, s29
	s_nop 0
	global_load_lds_dwordx4 v[230:231], off
	s_waitcnt vmcnt(8)
	s_waitcnt lgkmcnt(0)
	s_setprio 1
	s_barrier
	v_mfma_f32_16x16x32_bf16 v[124:127], v[146:149], v[190:193], v[124:127]
	v_mfma_f32_16x16x32_bf16 v[120:123], v[154:157], v[190:193], v[120:123]
	v_mfma_f32_16x16x32_bf16 v[108:111], v[146:149], v[198:201], v[108:111]
	v_mfma_f32_16x16x32_bf16 v[104:107], v[154:157], v[198:201], v[104:107]
	v_mfma_f32_16x16x32_bf16 v[92:95], v[146:149], v[206:209], v[92:95]
	v_mfma_f32_16x16x32_bf16 v[88:91], v[154:157], v[206:209], v[88:91]
	v_mfma_f32_16x16x32_bf16 v[76:79], v[146:149], v[218:221], v[76:79]
	v_mfma_f32_16x16x32_bf16 v[72:75], v[154:157], v[218:221], v[72:75]
	v_mfma_f32_16x16x32_bf16 v[124:127], v[150:153], v[194:197], v[124:127]
	v_mfma_f32_16x16x32_bf16 v[120:123], v[170:173], v[194:197], v[120:123]
	v_mfma_f32_16x16x32_bf16 v[108:111], v[150:153], v[202:205], v[108:111]
	v_mfma_f32_16x16x32_bf16 v[104:107], v[170:173], v[202:205], v[104:107]
	v_mfma_f32_16x16x32_bf16 v[92:95], v[150:153], v[214:217], v[92:95]
	v_mfma_f32_16x16x32_bf16 v[88:91], v[170:173], v[214:217], v[88:91]
	v_mfma_f32_16x16x32_bf16 v[76:79], v[150:153], v[222:225], v[76:79]
	v_mfma_f32_16x16x32_bf16 v[72:75], v[170:173], v[222:225], v[72:75]
	s_setprio 0
	s_setprio 1
	v_mfma_f32_16x16x32_bf16 v[116:119], v[174:177], v[190:193], v[116:119]
	v_mfma_f32_16x16x32_bf16 v[112:115], v[182:185], v[190:193], v[112:115]
	v_mfma_f32_16x16x32_bf16 v[100:103], v[174:177], v[198:201], v[100:103]
	v_mfma_f32_16x16x32_bf16 v[96:99], v[182:185], v[198:201], v[96:99]
	v_mfma_f32_16x16x32_bf16 v[84:87], v[174:177], v[206:209], v[84:87]
	v_mfma_f32_16x16x32_bf16 v[80:83], v[182:185], v[206:209], v[80:83]
	v_mfma_f32_16x16x32_bf16 v[68:71], v[174:177], v[218:221], v[68:71]
	v_mfma_f32_16x16x32_bf16 v[64:67], v[182:185], v[218:221], v[64:67]
	v_mfma_f32_16x16x32_bf16 v[116:119], v[178:181], v[194:197], v[116:119]
	v_mfma_f32_16x16x32_bf16 v[112:115], v[186:189], v[194:197], v[112:115]
	v_mfma_f32_16x16x32_bf16 v[100:103], v[178:181], v[202:205], v[100:103]
	v_mfma_f32_16x16x32_bf16 v[96:99], v[186:189], v[202:205], v[96:99]
	v_mfma_f32_16x16x32_bf16 v[84:87], v[178:181], v[214:217], v[84:87]
	v_mfma_f32_16x16x32_bf16 v[80:83], v[186:189], v[214:217], v[80:83]
	v_mfma_f32_16x16x32_bf16 v[68:71], v[178:181], v[222:225], v[68:71]
	v_mfma_f32_16x16x32_bf16 v[64:67], v[186:189], v[222:225], v[64:67]
	s_setprio 0
	s_barrier
	s_add_i32 s78, s91, s30
	v_lshl_add_u64 v[158:159], v[158:159], 0, s[34:35]
	s_mov_b32 m0, s78
	ds_read_b128 v[190:193], v168 offset:49152
	ds_read_b128 v[194:197], v168 offset:50176
	ds_read_b128 v[198:201], v168 offset:51200
	ds_read_b128 v[202:205], v168 offset:52224
	ds_read_b128 v[206:209], v168 offset:53248
	ds_read_b128 v[214:217], v168 offset:54272
	ds_read_b128 v[218:221], v168 offset:55296
	ds_read_b128 v[222:225], v168 offset:56320
	global_load_lds_dwordx4 v[158:159], off
	s_add_i32 m0, s78, 0x2000
	s_add_u32 s76, s76, 0x80080
	v_lshl_add_u64 v[158:159], v[210:211], 0, s[34:35]
	s_addc_u32 s77, s77, 0
	s_add_i32 s78, s92, s30
	global_load_lds_dwordx4 v[158:159], off
	v_lshl_add_u64 v[158:159], s[76:77], 0, v[130:131]
	s_mov_b32 m0, s78
	s_nop 0
	global_load_lds_dwordx4 v[158:159], off
	v_lshl_add_u64 v[158:159], s[76:77], 0, v[134:135]
	s_add_i32 m0, s78, 0x2000
	s_nop 0
	global_load_lds_dwordx4 v[158:159], off
	v_lshl_add_u64 v[158:159], v[226:227], 0, s[34:35]
	s_mov_b32 m0, s73
	s_nop 0
	global_load_lds_dwordx4 v[158:159], off
	v_lshl_add_u64 v[158:159], v[228:229], 0, s[34:35]
	s_mov_b32 m0, s80
	s_nop 0
	global_load_lds_dwordx4 v[158:159], off
	s_waitcnt vmcnt(8)
	s_waitcnt lgkmcnt(0)
	s_setprio 1
	s_barrier
	v_mfma_f32_16x16x32_bf16 v[60:63], v[146:149], v[190:193], v[60:63]
	v_mfma_f32_16x16x32_bf16 v[56:59], v[154:157], v[190:193], v[56:59]
	v_mfma_f32_16x16x32_bf16 v[44:47], v[146:149], v[198:201], v[44:47]
	v_mfma_f32_16x16x32_bf16 v[40:43], v[154:157], v[198:201], v[40:43]
	v_mfma_f32_16x16x32_bf16 v[28:31], v[146:149], v[206:209], v[28:31]
	v_mfma_f32_16x16x32_bf16 v[24:27], v[154:157], v[206:209], v[24:27]
	v_mfma_f32_16x16x32_bf16 v[12:15], v[146:149], v[218:221], v[12:15]
	v_mfma_f32_16x16x32_bf16 v[8:11], v[154:157], v[218:221], v[8:11]
	v_mfma_f32_16x16x32_bf16 v[60:63], v[150:153], v[194:197], v[60:63]
	v_mfma_f32_16x16x32_bf16 v[56:59], v[170:173], v[194:197], v[56:59]
	v_mfma_f32_16x16x32_bf16 v[44:47], v[150:153], v[202:205], v[44:47]
	v_mfma_f32_16x16x32_bf16 v[40:43], v[170:173], v[202:205], v[40:43]
	v_mfma_f32_16x16x32_bf16 v[28:31], v[150:153], v[214:217], v[28:31]
	v_mfma_f32_16x16x32_bf16 v[24:27], v[170:173], v[214:217], v[24:27]
	v_mfma_f32_16x16x32_bf16 v[12:15], v[150:153], v[222:225], v[12:15]
	v_mfma_f32_16x16x32_bf16 v[8:11], v[170:173], v[222:225], v[8:11]
	s_setprio 0
	s_setprio 1
	v_mfma_f32_16x16x32_bf16 v[52:55], v[174:177], v[190:193], v[52:55]
	v_mfma_f32_16x16x32_bf16 v[48:51], v[182:185], v[190:193], v[48:51]
	v_mfma_f32_16x16x32_bf16 v[36:39], v[174:177], v[198:201], v[36:39]
	v_mfma_f32_16x16x32_bf16 v[32:35], v[182:185], v[198:201], v[32:35]
	v_mfma_f32_16x16x32_bf16 v[20:23], v[174:177], v[206:209], v[20:23]
	v_mfma_f32_16x16x32_bf16 v[16:19], v[182:185], v[206:209], v[16:19]
	v_mfma_f32_16x16x32_bf16 v[4:7], v[174:177], v[218:221], v[4:7]
	v_mfma_f32_16x16x32_bf16 v[0:3], v[182:185], v[218:221], v[0:3]
	v_mfma_f32_16x16x32_bf16 v[52:55], v[178:181], v[194:197], v[52:55]
	v_mfma_f32_16x16x32_bf16 v[48:51], v[186:189], v[194:197], v[48:51]
	v_mfma_f32_16x16x32_bf16 v[36:39], v[178:181], v[202:205], v[36:39]
	v_mfma_f32_16x16x32_bf16 v[32:35], v[186:189], v[202:205], v[32:35]
	v_mfma_f32_16x16x32_bf16 v[20:23], v[178:181], v[214:217], v[20:23]
	v_mfma_f32_16x16x32_bf16 v[16:19], v[186:189], v[214:217], v[16:19]
	v_mfma_f32_16x16x32_bf16 v[4:7], v[178:181], v[222:225], v[4:7]
	v_mfma_f32_16x16x32_bf16 v[0:3], v[186:189], v[222:225], v[0:3]
	s_setprio 0
	s_barrier
	s_add_i32 s90, s90, 2
	s_add_u32 s74, s74, 0x100
	s_addc_u32 s75, s75, 0
	s_add_u32 s65, s65, 0x100
	s_addc_u32 s71, s71, 0
	s_cmp_gt_u32 s90, 29
.LBB0_272:
	ds_read_b128 v[146:149], v166
	ds_read_b128 v[150:153], v166 offset:1024
	ds_read_b128 v[154:157], v166 offset:2048
	ds_read_b128 v[170:173], v166 offset:3072
	ds_read_b128 v[174:177], v167
	ds_read_b128 v[178:181], v167 offset:1024
	ds_read_b128 v[182:185], v167 offset:2048
	ds_read_b128 v[186:189], v167 offset:3072
	s_add_u32 s76, s74, 0xfff80080
	s_addc_u32 s77, s75, -1
	s_cmp_eq_u32 s90, 28
	s_cselect_b32 s79, s0, s77
	s_cselect_b32 s78, s1, s76
	s_cselect_b32 s77, s3, s71
	s_cselect_b32 s76, s63, s65
	v_lshl_add_u64 v[158:159], s[74:75], 0, v[138:139]
	s_add_i32 m0, s31, 0xc000
	ds_read_b128 v[190:193], v168
	ds_read_b128 v[194:197], v168 offset:1024
	ds_read_b128 v[198:201], v168 offset:2048
	ds_read_b128 v[202:205], v168 offset:3072
	ds_read_b128 v[206:209], v168 offset:4096
	ds_read_b128 v[214:217], v168 offset:5120
	ds_read_b128 v[218:221], v168 offset:6144
	ds_read_b128 v[222:225], v168 offset:7168
	global_load_lds_dwordx4 v[158:159], off
	v_lshl_add_u64 v[158:159], s[74:75], 0, v[140:141]
	s_add_i32 m0, s31, 0xe000
	s_nop 0
	global_load_lds_dwordx4 v[158:159], off
	s_waitcnt vmcnt(8)
	s_waitcnt lgkmcnt(0)
	s_setprio 1
	s_barrier
	v_mfma_f32_16x16x32_bf16 v[124:127], v[146:149], v[190:193], v[124:127]
	v_mfma_f32_16x16x32_bf16 v[120:123], v[154:157], v[190:193], v[120:123]
	v_mfma_f32_16x16x32_bf16 v[108:111], v[146:149], v[198:201], v[108:111]
	v_mfma_f32_16x16x32_bf16 v[104:107], v[154:157], v[198:201], v[104:107]
	v_mfma_f32_16x16x32_bf16 v[92:95], v[146:149], v[206:209], v[92:95]
	v_mfma_f32_16x16x32_bf16 v[88:91], v[154:157], v[206:209], v[88:91]
	v_mfma_f32_16x16x32_bf16 v[76:79], v[146:149], v[218:221], v[76:79]
	v_mfma_f32_16x16x32_bf16 v[72:75], v[154:157], v[218:221], v[72:75]
	v_mfma_f32_16x16x32_bf16 v[124:127], v[150:153], v[194:197], v[124:127]
	v_mfma_f32_16x16x32_bf16 v[120:123], v[170:173], v[194:197], v[120:123]
	v_mfma_f32_16x16x32_bf16 v[108:111], v[150:153], v[202:205], v[108:111]
	v_mfma_f32_16x16x32_bf16 v[104:107], v[170:173], v[202:205], v[104:107]
	v_mfma_f32_16x16x32_bf16 v[92:95], v[150:153], v[214:217], v[92:95]
	v_mfma_f32_16x16x32_bf16 v[88:91], v[170:173], v[214:217], v[88:91]
	v_mfma_f32_16x16x32_bf16 v[76:79], v[150:153], v[222:225], v[76:79]
	v_mfma_f32_16x16x32_bf16 v[72:75], v[170:173], v[222:225], v[72:75]
	s_setprio 0
	s_setprio 1
	v_mfma_f32_16x16x32_bf16 v[116:119], v[174:177], v[190:193], v[116:119]
	v_mfma_f32_16x16x32_bf16 v[112:115], v[182:185], v[190:193], v[112:115]
	v_mfma_f32_16x16x32_bf16 v[100:103], v[174:177], v[198:201], v[100:103]
	v_mfma_f32_16x16x32_bf16 v[96:99], v[182:185], v[198:201], v[96:99]
	v_mfma_f32_16x16x32_bf16 v[84:87], v[174:177], v[206:209], v[84:87]
	v_mfma_f32_16x16x32_bf16 v[80:83], v[182:185], v[206:209], v[80:83]
	v_mfma_f32_16x16x32_bf16 v[68:71], v[174:177], v[218:221], v[68:71]
	v_mfma_f32_16x16x32_bf16 v[64:67], v[182:185], v[218:221], v[64:67]
	v_mfma_f32_16x16x32_bf16 v[116:119], v[178:181], v[194:197], v[116:119]
	v_mfma_f32_16x16x32_bf16 v[112:115], v[186:189], v[194:197], v[112:115]
	v_mfma_f32_16x16x32_bf16 v[100:103], v[178:181], v[202:205], v[100:103]
	v_mfma_f32_16x16x32_bf16 v[96:99], v[186:189], v[202:205], v[96:99]
	v_mfma_f32_16x16x32_bf16 v[84:87], v[178:181], v[214:217], v[84:87]
	v_mfma_f32_16x16x32_bf16 v[80:83], v[186:189], v[214:217], v[80:83]
	v_mfma_f32_16x16x32_bf16 v[68:71], v[178:181], v[222:225], v[68:71]
	v_mfma_f32_16x16x32_bf16 v[64:67], v[186:189], v[222:225], v[64:67]
	s_setprio 0
	s_barrier
	s_add_i32 s91, s81, s30
	v_lshl_add_u64 v[158:159], s[76:77], 0, v[130:131]
	s_mov_b32 m0, s91
	ds_read_b128 v[190:193], v168 offset:16384
	ds_read_b128 v[194:197], v168 offset:17408
	ds_read_b128 v[198:201], v168 offset:18432
	ds_read_b128 v[202:205], v168 offset:19456
	ds_read_b128 v[206:209], v168 offset:20480
	ds_read_b128 v[214:217], v168 offset:21504
	ds_read_b128 v[218:221], v168 offset:22528
	ds_read_b128 v[222:225], v168 offset:23552
	global_load_lds_dwordx4 v[158:159], off
	s_add_i32 m0, s91, 0x2000
	s_add_u32 s92, s76, 0x80000
	v_lshl_add_u64 v[210:211], s[76:77], 0, v[134:135]
	s_addc_u32 s93, s77, 0
	s_add_i32 s91, s83, s30
	global_load_lds_dwordx4 v[210:211], off
	v_lshl_add_u64 v[226:227], s[92:93], 0, v[130:131]
	s_mov_b32 m0, s91
	v_lshl_add_u64 v[228:229], s[78:79], 0, v[132:133]
	global_load_lds_dwordx4 v[226:227], off
	v_lshl_add_u64 v[226:227], s[92:93], 0, v[134:135]
	s_add_i32 m0, s91, 0x2000
	s_nop 0
	global_load_lds_dwordx4 v[226:227], off
	v_lshl_add_u64 v[226:227], s[78:79], 0, v[128:129]
	s_mov_b32 m0, s31
	s_nop 0
	global_load_lds_dwordx4 v[226:227], off
	s_mov_b32 m0, s51
	s_nop 0
	global_load_lds_dwordx4 v[228:229], off
	s_waitcnt vmcnt(8)
	s_waitcnt lgkmcnt(0)
	s_setprio 1
	s_barrier
	v_mfma_f32_16x16x32_bf16 v[60:63], v[146:149], v[190:193], v[60:63]
	v_mfma_f32_16x16x32_bf16 v[56:59], v[154:157], v[190:193], v[56:59]
	v_mfma_f32_16x16x32_bf16 v[44:47], v[146:149], v[198:201], v[44:47]
	v_mfma_f32_16x16x32_bf16 v[40:43], v[154:157], v[198:201], v[40:43]
	v_mfma_f32_16x16x32_bf16 v[28:31], v[146:149], v[206:209], v[28:31]
	v_mfma_f32_16x16x32_bf16 v[24:27], v[154:157], v[206:209], v[24:27]
	v_mfma_f32_16x16x32_bf16 v[12:15], v[146:149], v[218:221], v[12:15]
	v_mfma_f32_16x16x32_bf16 v[8:11], v[154:157], v[218:221], v[8:11]
	v_mfma_f32_16x16x32_bf16 v[60:63], v[150:153], v[194:197], v[60:63]
	v_mfma_f32_16x16x32_bf16 v[56:59], v[170:173], v[194:197], v[56:59]
	v_mfma_f32_16x16x32_bf16 v[44:47], v[150:153], v[202:205], v[44:47]
	v_mfma_f32_16x16x32_bf16 v[40:43], v[170:173], v[202:205], v[40:43]
	v_mfma_f32_16x16x32_bf16 v[28:31], v[150:153], v[214:217], v[28:31]
	v_mfma_f32_16x16x32_bf16 v[24:27], v[170:173], v[214:217], v[24:27]
	v_mfma_f32_16x16x32_bf16 v[12:15], v[150:153], v[222:225], v[12:15]
	v_mfma_f32_16x16x32_bf16 v[8:11], v[170:173], v[222:225], v[8:11]
	s_setprio 0
	s_setprio 1
	v_mfma_f32_16x16x32_bf16 v[52:55], v[174:177], v[190:193], v[52:55]
	v_mfma_f32_16x16x32_bf16 v[48:51], v[182:185], v[190:193], v[48:51]
	v_mfma_f32_16x16x32_bf16 v[36:39], v[174:177], v[198:201], v[36:39]
	v_mfma_f32_16x16x32_bf16 v[32:35], v[182:185], v[198:201], v[32:35]
	v_mfma_f32_16x16x32_bf16 v[20:23], v[174:177], v[206:209], v[20:23]
	v_mfma_f32_16x16x32_bf16 v[16:19], v[182:185], v[206:209], v[16:19]
	v_mfma_f32_16x16x32_bf16 v[4:7], v[174:177], v[218:221], v[4:7]
	v_mfma_f32_16x16x32_bf16 v[0:3], v[182:185], v[218:221], v[0:3]
	v_mfma_f32_16x16x32_bf16 v[52:55], v[178:181], v[194:197], v[52:55]
	v_mfma_f32_16x16x32_bf16 v[48:51], v[186:189], v[194:197], v[48:51]
	v_mfma_f32_16x16x32_bf16 v[36:39], v[178:181], v[202:205], v[36:39]
	v_mfma_f32_16x16x32_bf16 v[32:35], v[186:189], v[202:205], v[32:35]
	v_mfma_f32_16x16x32_bf16 v[20:23], v[178:181], v[214:217], v[20:23]
	v_mfma_f32_16x16x32_bf16 v[16:19], v[186:189], v[214:217], v[16:19]
	v_mfma_f32_16x16x32_bf16 v[4:7], v[178:181], v[222:225], v[4:7]
	v_mfma_f32_16x16x32_bf16 v[0:3], v[186:189], v[222:225], v[0:3]
	s_setprio 0
	s_barrier
	s_add_i32 s91, 0, 0x18000
	v_add_u32_e32 v136, s91, v162
	s_add_i32 s92, 0, 0x1c000
	ds_read_b128 v[146:149], v136
	ds_read_b128 v[150:153], v136 offset:1024
	ds_read_b128 v[154:157], v136 offset:2048
	ds_read_b128 v[170:173], v136 offset:3072
	v_add_u32_e32 v136, s92, v162
	ds_read_b128 v[174:177], v136
	ds_read_b128 v[178:181], v136 offset:1024
	ds_read_b128 v[182:185], v136 offset:2048
	ds_read_b128 v[186:189], v136 offset:3072
	s_add_u32 s78, s78, 0x80000
	s_addc_u32 s79, s79, 0
	s_mov_b32 m0, s28
	v_lshl_add_u64 v[230:231], s[78:79], 0, v[128:129]
	ds_read_b128 v[190:193], v168 offset:32768
	ds_read_b128 v[194:197], v168 offset:33792
	ds_read_b128 v[198:201], v168 offset:34816
	ds_read_b128 v[202:205], v168 offset:35840
	ds_read_b128 v[206:209], v168 offset:36864
	ds_read_b128 v[214:217], v168 offset:37888
	ds_read_b128 v[218:221], v168 offset:38912
	ds_read_b128 v[222:225], v168 offset:39936
	global_load_lds_dwordx4 v[230:231], off
	v_lshl_add_u64 v[230:231], s[78:79], 0, v[132:133]
	s_mov_b32 m0, s29
	s_nop 0
	global_load_lds_dwordx4 v[230:231], off
	s_waitcnt vmcnt(8)
	s_waitcnt lgkmcnt(0)
	s_setprio 1
	s_barrier
	v_mfma_f32_16x16x32_bf16 v[124:127], v[146:149], v[190:193], v[124:127]
	v_mfma_f32_16x16x32_bf16 v[120:123], v[154:157], v[190:193], v[120:123]
	v_mfma_f32_16x16x32_bf16 v[108:111], v[146:149], v[198:201], v[108:111]
	v_mfma_f32_16x16x32_bf16 v[104:107], v[154:157], v[198:201], v[104:107]
	v_mfma_f32_16x16x32_bf16 v[92:95], v[146:149], v[206:209], v[92:95]
	v_mfma_f32_16x16x32_bf16 v[88:91], v[154:157], v[206:209], v[88:91]
	v_mfma_f32_16x16x32_bf16 v[76:79], v[146:149], v[218:221], v[76:79]
	v_mfma_f32_16x16x32_bf16 v[72:75], v[154:157], v[218:221], v[72:75]
	v_mfma_f32_16x16x32_bf16 v[124:127], v[150:153], v[194:197], v[124:127]
	v_mfma_f32_16x16x32_bf16 v[120:123], v[170:173], v[194:197], v[120:123]
	v_mfma_f32_16x16x32_bf16 v[108:111], v[150:153], v[202:205], v[108:111]
	v_mfma_f32_16x16x32_bf16 v[104:107], v[170:173], v[202:205], v[104:107]
	v_mfma_f32_16x16x32_bf16 v[92:95], v[150:153], v[214:217], v[92:95]
	v_mfma_f32_16x16x32_bf16 v[88:91], v[170:173], v[214:217], v[88:91]
	v_mfma_f32_16x16x32_bf16 v[76:79], v[150:153], v[222:225], v[76:79]
	v_mfma_f32_16x16x32_bf16 v[72:75], v[170:173], v[222:225], v[72:75]
	s_setprio 0
	s_setprio 1
	v_mfma_f32_16x16x32_bf16 v[116:119], v[174:177], v[190:193], v[116:119]
	v_mfma_f32_16x16x32_bf16 v[112:115], v[182:185], v[190:193], v[112:115]
	v_mfma_f32_16x16x32_bf16 v[100:103], v[174:177], v[198:201], v[100:103]
	v_mfma_f32_16x16x32_bf16 v[96:99], v[182:185], v[198:201], v[96:99]
	v_mfma_f32_16x16x32_bf16 v[84:87], v[174:177], v[206:209], v[84:87]
	v_mfma_f32_16x16x32_bf16 v[80:83], v[182:185], v[206:209], v[80:83]
	v_mfma_f32_16x16x32_bf16 v[68:71], v[174:177], v[218:221], v[68:71]
	v_mfma_f32_16x16x32_bf16 v[64:67], v[182:185], v[218:221], v[64:67]
	v_mfma_f32_16x16x32_bf16 v[116:119], v[178:181], v[194:197], v[116:119]
	v_mfma_f32_16x16x32_bf16 v[112:115], v[186:189], v[194:197], v[112:115]
	v_mfma_f32_16x16x32_bf16 v[100:103], v[178:181], v[202:205], v[100:103]
	v_mfma_f32_16x16x32_bf16 v[96:99], v[186:189], v[202:205], v[96:99]
	v_mfma_f32_16x16x32_bf16 v[84:87], v[178:181], v[214:217], v[84:87]
	v_mfma_f32_16x16x32_bf16 v[80:83], v[186:189], v[214:217], v[80:83]
	v_mfma_f32_16x16x32_bf16 v[68:71], v[178:181], v[222:225], v[68:71]
	v_mfma_f32_16x16x32_bf16 v[64:67], v[186:189], v[222:225], v[64:67]
	s_setprio 0
	s_barrier
	s_add_i32 s78, s91, s30
	v_lshl_add_u64 v[158:159], v[158:159], 0, s[34:35]
	s_mov_b32 m0, s78
	ds_read_b128 v[190:193], v168 offset:49152
	ds_read_b128 v[194:197], v168 offset:50176
	ds_read_b128 v[198:201], v168 offset:51200
	ds_read_b128 v[202:205], v168 offset:52224
	ds_read_b128 v[206:209], v168 offset:53248
	ds_read_b128 v[214:217], v168 offset:54272
	ds_read_b128 v[218:221], v168 offset:55296
	ds_read_b128 v[222:225], v168 offset:56320
	global_load_lds_dwordx4 v[158:159], off
	s_add_i32 m0, s78, 0x2000
	s_add_u32 s76, s76, 0x80080
	v_lshl_add_u64 v[158:159], v[210:211], 0, s[34:35]
	s_addc_u32 s77, s77, 0
	s_add_i32 s78, s92, s30
	global_load_lds_dwordx4 v[158:159], off
	v_lshl_add_u64 v[158:159], s[76:77], 0, v[130:131]
	s_mov_b32 m0, s78
	s_nop 0
	global_load_lds_dwordx4 v[158:159], off
	v_lshl_add_u64 v[158:159], s[76:77], 0, v[134:135]
	s_add_i32 m0, s78, 0x2000
	s_nop 0
	global_load_lds_dwordx4 v[158:159], off
	v_lshl_add_u64 v[158:159], v[226:227], 0, s[34:35]
	s_mov_b32 m0, s73
	s_nop 0
	global_load_lds_dwordx4 v[158:159], off
	v_lshl_add_u64 v[158:159], v[228:229], 0, s[34:35]
	s_mov_b32 m0, s80
	s_nop 0
	global_load_lds_dwordx4 v[158:159], off
	s_waitcnt vmcnt(8)
	s_waitcnt lgkmcnt(0)
	s_setprio 1
	s_barrier
	v_mfma_f32_16x16x32_bf16 v[60:63], v[146:149], v[190:193], v[60:63]
	v_mfma_f32_16x16x32_bf16 v[56:59], v[154:157], v[190:193], v[56:59]
	v_mfma_f32_16x16x32_bf16 v[44:47], v[146:149], v[198:201], v[44:47]
	v_mfma_f32_16x16x32_bf16 v[40:43], v[154:157], v[198:201], v[40:43]
	v_mfma_f32_16x16x32_bf16 v[28:31], v[146:149], v[206:209], v[28:31]
	v_mfma_f32_16x16x32_bf16 v[24:27], v[154:157], v[206:209], v[24:27]
	v_mfma_f32_16x16x32_bf16 v[12:15], v[146:149], v[218:221], v[12:15]
	v_mfma_f32_16x16x32_bf16 v[8:11], v[154:157], v[218:221], v[8:11]
	v_mfma_f32_16x16x32_bf16 v[60:63], v[150:153], v[194:197], v[60:63]
	v_mfma_f32_16x16x32_bf16 v[56:59], v[170:173], v[194:197], v[56:59]
	v_mfma_f32_16x16x32_bf16 v[44:47], v[150:153], v[202:205], v[44:47]
	v_mfma_f32_16x16x32_bf16 v[40:43], v[170:173], v[202:205], v[40:43]
	v_mfma_f32_16x16x32_bf16 v[28:31], v[150:153], v[214:217], v[28:31]
	v_mfma_f32_16x16x32_bf16 v[24:27], v[170:173], v[214:217], v[24:27]
	v_mfma_f32_16x16x32_bf16 v[12:15], v[150:153], v[222:225], v[12:15]
	v_mfma_f32_16x16x32_bf16 v[8:11], v[170:173], v[222:225], v[8:11]
	s_setprio 0
	s_setprio 1
	v_mfma_f32_16x16x32_bf16 v[52:55], v[174:177], v[190:193], v[52:55]
	v_mfma_f32_16x16x32_bf16 v[48:51], v[182:185], v[190:193], v[48:51]
	v_mfma_f32_16x16x32_bf16 v[36:39], v[174:177], v[198:201], v[36:39]
	v_mfma_f32_16x16x32_bf16 v[32:35], v[182:185], v[198:201], v[32:35]
	v_mfma_f32_16x16x32_bf16 v[20:23], v[174:177], v[206:209], v[20:23]
	v_mfma_f32_16x16x32_bf16 v[16:19], v[182:185], v[206:209], v[16:19]
	v_mfma_f32_16x16x32_bf16 v[4:7], v[174:177], v[218:221], v[4:7]
	v_mfma_f32_16x16x32_bf16 v[0:3], v[182:185], v[218:221], v[0:3]
	v_mfma_f32_16x16x32_bf16 v[52:55], v[178:181], v[194:197], v[52:55]
	v_mfma_f32_16x16x32_bf16 v[48:51], v[186:189], v[194:197], v[48:51]
	v_mfma_f32_16x16x32_bf16 v[36:39], v[178:181], v[202:205], v[36:39]
	v_mfma_f32_16x16x32_bf16 v[32:35], v[186:189], v[202:205], v[32:35]
	v_mfma_f32_16x16x32_bf16 v[20:23], v[178:181], v[214:217], v[20:23]
	v_mfma_f32_16x16x32_bf16 v[16:19], v[186:189], v[214:217], v[16:19]
	v_mfma_f32_16x16x32_bf16 v[4:7], v[178:181], v[222:225], v[4:7]
	v_mfma_f32_16x16x32_bf16 v[0:3], v[186:189], v[222:225], v[0:3]
	s_setprio 0
	s_barrier
	s_add_i32 s90, s90, 2
	s_add_u32 s74, s74, 0x100
	s_addc_u32 s75, s75, 0
	s_add_u32 s65, s65, 0x100
	s_addc_u32 s71, s71, 0
	s_cmp_gt_u32 s90, 29
	s_cbranch_scc0 .LBB0_272
	s_and_b64 vcc, exec, s[36:37]
	s_cbranch_vccz .LBB0_275
	s_barrier

.LBB0_542:
	s_ashr_i32 s35, s34, 31
	s_lshl_b64 s[0:1], s[34:35], 20
	s_add_u32 s36, s29, s0
	s_addc_u32 s37, s30, s1
	s_and_b64 s[0:1], s[6:7], exec
	s_cselect_b32 s0, s37, s43
	s_cselect_b32 s1, s36, s42
	s_ashr_i32 s25, s24, 31
	s_lshl_b64 s[38:39], s[24:25], 20
	s_add_u32 s38, s27, s38
	s_addc_u32 s39, s28, s39
	s_and_b64 s[46:47], s[6:7], exec
	s_cselect_b32 s3, s39, s45
	s_cselect_b32 s9, s38, s44
	s_add_u32 s42, s42, 0x80080
	s_addc_u32 s43, s43, 0
	s_add_u32 s25, s44, 0x100
	s_addc_u32 s35, s45, 0
	s_mov_b32 s58, -2
	s_waitcnt lgkmcnt(0)
	s_waitcnt vmcnt(0)
	ds_read_b128 v[128:131], v216
	ds_read_b128 v[132:135], v216 offset:1024
	ds_read_b128 v[136:139], v216 offset:2048
	ds_read_b128 v[140:143], v216 offset:3072
	ds_read_b128 v[144:147], v217
	ds_read_b128 v[148:151], v217 offset:1024
	ds_read_b128 v[152:155], v217 offset:2048
	ds_read_b128 v[156:159], v217 offset:3072
	s_add_u32 s44, s42, 0xfff80080
	s_addc_u32 s45, s43, -1
	s_cmp_eq_u32 s58, 28
	s_cselect_b32 s47, s0, s45
	s_cselect_b32 s46, s1, s44
	s_cselect_b32 s45, s3, s35
	s_cselect_b32 s44, s9, s25
	v_lshl_add_u64 v[208:209], s[42:43], 0, v[184:185]
	s_add_i32 m0, s41, 0xc000
	ds_read_b128 v[160:163], v218
	ds_read_b128 v[164:167], v218 offset:1024
	ds_read_b128 v[168:171], v218 offset:2048
	ds_read_b128 v[172:175], v218 offset:3072
	ds_read_b128 v[192:195], v218 offset:4096
	ds_read_b128 v[196:199], v218 offset:5120
	ds_read_b128 v[200:203], v218 offset:6144
	ds_read_b128 v[204:207], v218 offset:7168
	global_load_lds_dwordx4 v[208:209], off
	v_lshl_add_u64 v[208:209], s[42:43], 0, v[186:187]
	s_add_i32 m0, s41, 0xe000
	s_nop 0
	global_load_lds_dwordx4 v[208:209], off
	s_waitcnt vmcnt(8)
	s_waitcnt lgkmcnt(0)
	s_setprio 1
	s_barrier
	v_mfma_f32_16x16x32_bf16 v[124:127], v[128:131], v[160:163], 0
	v_mfma_f32_16x16x32_bf16 v[120:123], v[136:139], v[160:163], 0
	v_mfma_f32_16x16x32_bf16 v[108:111], v[128:131], v[168:171], 0
	v_mfma_f32_16x16x32_bf16 v[104:107], v[136:139], v[168:171], 0
	v_mfma_f32_16x16x32_bf16 v[92:95], v[128:131], v[192:195], 0
	v_mfma_f32_16x16x32_bf16 v[88:91], v[136:139], v[192:195], 0
	v_mfma_f32_16x16x32_bf16 v[76:79], v[128:131], v[200:203], 0
	v_mfma_f32_16x16x32_bf16 v[72:75], v[136:139], v[200:203], 0
	v_mfma_f32_16x16x32_bf16 v[124:127], v[132:135], v[164:167], v[124:127]
	v_mfma_f32_16x16x32_bf16 v[120:123], v[140:143], v[164:167], v[120:123]
	v_mfma_f32_16x16x32_bf16 v[108:111], v[132:135], v[172:175], v[108:111]
	v_mfma_f32_16x16x32_bf16 v[104:107], v[140:143], v[172:175], v[104:107]
	v_mfma_f32_16x16x32_bf16 v[92:95], v[132:135], v[196:199], v[92:95]
	v_mfma_f32_16x16x32_bf16 v[88:91], v[140:143], v[196:199], v[88:91]
	v_mfma_f32_16x16x32_bf16 v[76:79], v[132:135], v[204:207], v[76:79]
	v_mfma_f32_16x16x32_bf16 v[72:75], v[140:143], v[204:207], v[72:75]
	s_setprio 0
	s_setprio 1
	v_mfma_f32_16x16x32_bf16 v[116:119], v[144:147], v[160:163], 0
	v_mfma_f32_16x16x32_bf16 v[112:115], v[152:155], v[160:163], 0
	v_mfma_f32_16x16x32_bf16 v[100:103], v[144:147], v[168:171], 0
	v_mfma_f32_16x16x32_bf16 v[96:99], v[152:155], v[168:171], 0
	v_mfma_f32_16x16x32_bf16 v[84:87], v[144:147], v[192:195], 0
	v_mfma_f32_16x16x32_bf16 v[80:83], v[152:155], v[192:195], 0
	v_mfma_f32_16x16x32_bf16 v[68:71], v[144:147], v[200:203], 0
	v_mfma_f32_16x16x32_bf16 v[64:67], v[152:155], v[200:203], 0
	v_mfma_f32_16x16x32_bf16 v[116:119], v[148:151], v[164:167], v[116:119]
	v_mfma_f32_16x16x32_bf16 v[112:115], v[156:159], v[164:167], v[112:115]
	v_mfma_f32_16x16x32_bf16 v[100:103], v[148:151], v[172:175], v[100:103]
	v_mfma_f32_16x16x32_bf16 v[96:99], v[156:159], v[172:175], v[96:99]
	v_mfma_f32_16x16x32_bf16 v[84:87], v[148:151], v[196:199], v[84:87]
	v_mfma_f32_16x16x32_bf16 v[80:83], v[156:159], v[196:199], v[80:83]
	v_mfma_f32_16x16x32_bf16 v[68:71], v[148:151], v[204:207], v[68:71]
	v_mfma_f32_16x16x32_bf16 v[64:67], v[156:159], v[204:207], v[64:67]
	s_setprio 0
	s_barrier
	s_add_i32 s59, s55, s31
	v_lshl_add_u64 v[208:209], s[44:45], 0, v[178:179]
	s_mov_b32 m0, s59
	ds_read_b128 v[160:163], v218 offset:16384
	ds_read_b128 v[164:167], v218 offset:17408
	ds_read_b128 v[168:171], v218 offset:18432
	ds_read_b128 v[172:175], v218 offset:19456
	ds_read_b128 v[192:195], v218 offset:20480
	ds_read_b128 v[196:199], v218 offset:21504
	ds_read_b128 v[200:203], v218 offset:22528
	ds_read_b128 v[204:207], v218 offset:23552
	global_load_lds_dwordx4 v[208:209], off
	s_add_i32 m0, s59, 0x2000
	s_add_u32 s60, s44, 0x80000
	v_lshl_add_u64 v[210:211], s[44:45], 0, v[182:183]
	s_addc_u32 s61, s45, 0
	s_add_i32 s59, s56, s31
	global_load_lds_dwordx4 v[210:211], off
	v_lshl_add_u64 v[222:223], s[60:61], 0, v[178:179]
	s_mov_b32 m0, s59
	v_lshl_add_u64 v[224:225], s[46:47], 0, v[180:181]
	global_load_lds_dwordx4 v[222:223], off
	v_lshl_add_u64 v[222:223], s[60:61], 0, v[182:183]
	s_add_i32 m0, s59, 0x2000
	s_nop 0
	global_load_lds_dwordx4 v[222:223], off
	v_lshl_add_u64 v[222:223], s[46:47], 0, v[176:177]
	s_mov_b32 m0, s41
	s_nop 0
	global_load_lds_dwordx4 v[222:223], off
	s_mov_b32 m0, s48
	s_nop 0
	global_load_lds_dwordx4 v[224:225], off
	s_waitcnt vmcnt(8)
	s_waitcnt lgkmcnt(0)
	s_setprio 1
	s_barrier
	v_mfma_f32_16x16x32_bf16 v[60:63], v[128:131], v[160:163], 0
	v_mfma_f32_16x16x32_bf16 v[56:59], v[136:139], v[160:163], 0
	v_mfma_f32_16x16x32_bf16 v[44:47], v[128:131], v[168:171], 0
	v_mfma_f32_16x16x32_bf16 v[40:43], v[136:139], v[168:171], 0
	v_mfma_f32_16x16x32_bf16 v[28:31], v[128:131], v[192:195], 0
	v_mfma_f32_16x16x32_bf16 v[24:27], v[136:139], v[192:195], 0
	v_mfma_f32_16x16x32_bf16 v[12:15], v[128:131], v[200:203], 0
	v_mfma_f32_16x16x32_bf16 v[8:11], v[136:139], v[200:203], 0
	v_mfma_f32_16x16x32_bf16 v[60:63], v[132:135], v[164:167], v[60:63]
	v_mfma_f32_16x16x32_bf16 v[56:59], v[140:143], v[164:167], v[56:59]
	v_mfma_f32_16x16x32_bf16 v[44:47], v[132:135], v[172:175], v[44:47]
	v_mfma_f32_16x16x32_bf16 v[40:43], v[140:143], v[172:175], v[40:43]
	v_mfma_f32_16x16x32_bf16 v[28:31], v[132:135], v[196:199], v[28:31]
	v_mfma_f32_16x16x32_bf16 v[24:27], v[140:143], v[196:199], v[24:27]
	v_mfma_f32_16x16x32_bf16 v[12:15], v[132:135], v[204:207], v[12:15]
	v_mfma_f32_16x16x32_bf16 v[8:11], v[140:143], v[204:207], v[8:11]
	s_setprio 0
	s_setprio 1
	v_mfma_f32_16x16x32_bf16 v[52:55], v[144:147], v[160:163], 0
	v_mfma_f32_16x16x32_bf16 v[48:51], v[152:155], v[160:163], 0
	v_mfma_f32_16x16x32_bf16 v[36:39], v[144:147], v[168:171], 0
	v_mfma_f32_16x16x32_bf16 v[32:35], v[152:155], v[168:171], 0
	v_mfma_f32_16x16x32_bf16 v[20:23], v[144:147], v[192:195], 0
	v_mfma_f32_16x16x32_bf16 v[16:19], v[152:155], v[192:195], 0
	v_mfma_f32_16x16x32_bf16 v[4:7], v[144:147], v[200:203], 0
	v_mfma_f32_16x16x32_bf16 v[0:3], v[152:155], v[200:203], 0
	v_mfma_f32_16x16x32_bf16 v[52:55], v[148:151], v[164:167], v[52:55]
	v_mfma_f32_16x16x32_bf16 v[48:51], v[156:159], v[164:167], v[48:51]
	v_mfma_f32_16x16x32_bf16 v[36:39], v[148:151], v[172:175], v[36:39]
	v_mfma_f32_16x16x32_bf16 v[32:35], v[156:159], v[172:175], v[32:35]
	v_mfma_f32_16x16x32_bf16 v[20:23], v[148:151], v[196:199], v[20:23]
	v_mfma_f32_16x16x32_bf16 v[16:19], v[156:159], v[196:199], v[16:19]
	v_mfma_f32_16x16x32_bf16 v[4:7], v[148:151], v[204:207], v[4:7]
	v_mfma_f32_16x16x32_bf16 v[0:3], v[156:159], v[204:207], v[0:3]
	s_setprio 0
	s_barrier
	s_add_i32 s59, 0, 0x18000
	s_add_i32 s60, 0, 0x1c000
	v_add_u32_e32 v140, s59, v214
	v_add_u32_e32 v156, s60, v214
	ds_read_b128 v[128:131], v140
	ds_read_b128 v[132:135], v140 offset:1024
	ds_read_b128 v[136:139], v140 offset:2048
	ds_read_b128 v[140:143], v140 offset:3072
	ds_read_b128 v[144:147], v156
	ds_read_b128 v[148:151], v156 offset:1024
	ds_read_b128 v[152:155], v156 offset:2048
	ds_read_b128 v[156:159], v156 offset:3072
	s_add_u32 s46, s46, 0x80000
	s_addc_u32 s47, s47, 0
	s_mov_b32 m0, s49
	v_lshl_add_u64 v[226:227], s[46:47], 0, v[176:177]
	ds_read_b128 v[160:163], v218 offset:32768
	ds_read_b128 v[164:167], v218 offset:33792
	ds_read_b128 v[168:171], v218 offset:34816
	ds_read_b128 v[172:175], v218 offset:35840
	ds_read_b128 v[192:195], v218 offset:36864
	ds_read_b128 v[196:199], v218 offset:37888
	ds_read_b128 v[200:203], v218 offset:38912
	ds_read_b128 v[204:207], v218 offset:39936
	global_load_lds_dwordx4 v[226:227], off
	v_lshl_add_u64 v[226:227], s[46:47], 0, v[180:181]
	s_mov_b32 m0, s50
	s_nop 0
	global_load_lds_dwordx4 v[226:227], off
	s_waitcnt vmcnt(8)
	s_waitcnt lgkmcnt(0)
	s_setprio 1
	s_barrier
	v_mfma_f32_16x16x32_bf16 v[124:127], v[128:131], v[160:163], v[124:127]
	v_mfma_f32_16x16x32_bf16 v[120:123], v[136:139], v[160:163], v[120:123]
	v_mfma_f32_16x16x32_bf16 v[108:111], v[128:131], v[168:171], v[108:111]
	v_mfma_f32_16x16x32_bf16 v[104:107], v[136:139], v[168:171], v[104:107]
	v_mfma_f32_16x16x32_bf16 v[92:95], v[128:131], v[192:195], v[92:95]
	v_mfma_f32_16x16x32_bf16 v[88:91], v[136:139], v[192:195], v[88:91]
	v_mfma_f32_16x16x32_bf16 v[76:79], v[128:131], v[200:203], v[76:79]
	v_mfma_f32_16x16x32_bf16 v[72:75], v[136:139], v[200:203], v[72:75]
	v_mfma_f32_16x16x32_bf16 v[124:127], v[132:135], v[164:167], v[124:127]
	v_mfma_f32_16x16x32_bf16 v[120:123], v[140:143], v[164:167], v[120:123]
	v_mfma_f32_16x16x32_bf16 v[108:111], v[132:135], v[172:175], v[108:111]
	v_mfma_f32_16x16x32_bf16 v[104:107], v[140:143], v[172:175], v[104:107]
	v_mfma_f32_16x16x32_bf16 v[92:95], v[132:135], v[196:199], v[92:95]
	v_mfma_f32_16x16x32_bf16 v[88:91], v[140:143], v[196:199], v[88:91]
	v_mfma_f32_16x16x32_bf16 v[76:79], v[132:135], v[204:207], v[76:79]
	v_mfma_f32_16x16x32_bf16 v[72:75], v[140:143], v[204:207], v[72:75]
	s_setprio 0
	s_setprio 1
	v_mfma_f32_16x16x32_bf16 v[116:119], v[144:147], v[160:163], v[116:119]
	v_mfma_f32_16x16x32_bf16 v[112:115], v[152:155], v[160:163], v[112:115]
	v_mfma_f32_16x16x32_bf16 v[100:103], v[144:147], v[168:171], v[100:103]
	v_mfma_f32_16x16x32_bf16 v[96:99], v[152:155], v[168:171], v[96:99]
	v_mfma_f32_16x16x32_bf16 v[84:87], v[144:147], v[192:195], v[84:87]
	v_mfma_f32_16x16x32_bf16 v[80:83], v[152:155], v[192:195], v[80:83]
	v_mfma_f32_16x16x32_bf16 v[68:71], v[144:147], v[200:203], v[68:71]
	v_mfma_f32_16x16x32_bf16 v[64:67], v[152:155], v[200:203], v[64:67]
	v_mfma_f32_16x16x32_bf16 v[116:119], v[148:151], v[164:167], v[116:119]
	v_mfma_f32_16x16x32_bf16 v[112:115], v[156:159], v[164:167], v[112:115]
	v_mfma_f32_16x16x32_bf16 v[100:103], v[148:151], v[172:175], v[100:103]
	v_mfma_f32_16x16x32_bf16 v[96:99], v[156:159], v[172:175], v[96:99]
	v_mfma_f32_16x16x32_bf16 v[84:87], v[148:151], v[196:199], v[84:87]
	v_mfma_f32_16x16x32_bf16 v[80:83], v[156:159], v[196:199], v[80:83]
	v_mfma_f32_16x16x32_bf16 v[68:71], v[148:151], v[204:207], v[68:71]
	v_mfma_f32_16x16x32_bf16 v[64:67], v[156:159], v[204:207], v[64:67]
	s_setprio 0
	s_barrier
	s_add_i32 s46, s59, s31
	v_lshl_add_u64 v[208:209], v[208:209], 0, s[20:21]
	s_mov_b32 m0, s46
	ds_read_b128 v[160:163], v218 offset:49152
	ds_read_b128 v[164:167], v218 offset:50176
	ds_read_b128 v[168:171], v218 offset:51200
	ds_read_b128 v[172:175], v218 offset:52224
	ds_read_b128 v[192:195], v218 offset:53248
	ds_read_b128 v[196:199], v218 offset:54272
	ds_read_b128 v[200:203], v218 offset:55296
	ds_read_b128 v[204:207], v218 offset:56320
	global_load_lds_dwordx4 v[208:209], off
	s_add_i32 m0, s46, 0x2000
	s_add_u32 s44, s44, 0x80080
	v_lshl_add_u64 v[208:209], v[210:211], 0, s[20:21]
	s_addc_u32 s45, s45, 0
	s_add_i32 s46, s60, s31
	global_load_lds_dwordx4 v[208:209], off
	v_lshl_add_u64 v[208:209], s[44:45], 0, v[178:179]
	s_mov_b32 m0, s46
	s_nop 0
	global_load_lds_dwordx4 v[208:209], off
	v_lshl_add_u64 v[208:209], s[44:45], 0, v[182:183]
	s_add_i32 m0, s46, 0x2000
	s_nop 0
	global_load_lds_dwordx4 v[208:209], off
	v_lshl_add_u64 v[208:209], v[222:223], 0, s[20:21]
	s_mov_b32 m0, s52
	s_nop 0
	global_load_lds_dwordx4 v[208:209], off
	v_lshl_add_u64 v[208:209], v[224:225], 0, s[20:21]
	s_mov_b32 m0, s53
	s_nop 0
	global_load_lds_dwordx4 v[208:209], off
	s_waitcnt vmcnt(8)
	s_waitcnt lgkmcnt(0)
	s_setprio 1
	s_barrier
	v_mfma_f32_16x16x32_bf16 v[60:63], v[128:131], v[160:163], v[60:63]
	v_mfma_f32_16x16x32_bf16 v[56:59], v[136:139], v[160:163], v[56:59]
	v_mfma_f32_16x16x32_bf16 v[44:47], v[128:131], v[168:171], v[44:47]
	v_mfma_f32_16x16x32_bf16 v[40:43], v[136:139], v[168:171], v[40:43]
	v_mfma_f32_16x16x32_bf16 v[28:31], v[128:131], v[192:195], v[28:31]
	v_mfma_f32_16x16x32_bf16 v[24:27], v[136:139], v[192:195], v[24:27]
	v_mfma_f32_16x16x32_bf16 v[12:15], v[128:131], v[200:203], v[12:15]
	v_mfma_f32_16x16x32_bf16 v[8:11], v[136:139], v[200:203], v[8:11]
	v_mfma_f32_16x16x32_bf16 v[60:63], v[132:135], v[164:167], v[60:63]
	v_mfma_f32_16x16x32_bf16 v[56:59], v[140:143], v[164:167], v[56:59]
	v_mfma_f32_16x16x32_bf16 v[44:47], v[132:135], v[172:175], v[44:47]
	v_mfma_f32_16x16x32_bf16 v[40:43], v[140:143], v[172:175], v[40:43]
	v_mfma_f32_16x16x32_bf16 v[28:31], v[132:135], v[196:199], v[28:31]
	v_mfma_f32_16x16x32_bf16 v[24:27], v[140:143], v[196:199], v[24:27]
	v_mfma_f32_16x16x32_bf16 v[12:15], v[132:135], v[204:207], v[12:15]
	v_mfma_f32_16x16x32_bf16 v[8:11], v[140:143], v[204:207], v[8:11]
	s_setprio 0
	s_setprio 1
	v_mfma_f32_16x16x32_bf16 v[52:55], v[144:147], v[160:163], v[52:55]
	v_mfma_f32_16x16x32_bf16 v[48:51], v[152:155], v[160:163], v[48:51]
	v_mfma_f32_16x16x32_bf16 v[36:39], v[144:147], v[168:171], v[36:39]
	v_mfma_f32_16x16x32_bf16 v[32:35], v[152:155], v[168:171], v[32:35]
	v_mfma_f32_16x16x32_bf16 v[20:23], v[144:147], v[192:195], v[20:23]
	v_mfma_f32_16x16x32_bf16 v[16:19], v[152:155], v[192:195], v[16:19]
	v_mfma_f32_16x16x32_bf16 v[4:7], v[144:147], v[200:203], v[4:7]
	v_mfma_f32_16x16x32_bf16 v[0:3], v[152:155], v[200:203], v[0:3]
	v_mfma_f32_16x16x32_bf16 v[52:55], v[148:151], v[164:167], v[52:55]
	v_mfma_f32_16x16x32_bf16 v[48:51], v[156:159], v[164:167], v[48:51]
	v_mfma_f32_16x16x32_bf16 v[36:39], v[148:151], v[172:175], v[36:39]
	v_mfma_f32_16x16x32_bf16 v[32:35], v[156:159], v[172:175], v[32:35]
	v_mfma_f32_16x16x32_bf16 v[20:23], v[148:151], v[196:199], v[20:23]
	v_mfma_f32_16x16x32_bf16 v[16:19], v[156:159], v[196:199], v[16:19]
	v_mfma_f32_16x16x32_bf16 v[4:7], v[148:151], v[204:207], v[4:7]
	v_mfma_f32_16x16x32_bf16 v[0:3], v[156:159], v[204:207], v[0:3]
	s_setprio 0
	s_barrier
	s_add_i32 s58, s58, 2
	s_add_u32 s42, s42, 0x100
	s_addc_u32 s43, s43, 0
	s_add_u32 s25, s25, 0x100
	s_addc_u32 s35, s35, 0
	s_cmp_gt_u32 s58, 29
.LBB0_543:
	ds_read_b128 v[128:131], v216
	ds_read_b128 v[132:135], v216 offset:1024
	ds_read_b128 v[136:139], v216 offset:2048
	ds_read_b128 v[140:143], v216 offset:3072
	ds_read_b128 v[144:147], v217
	ds_read_b128 v[148:151], v217 offset:1024
	ds_read_b128 v[152:155], v217 offset:2048
	ds_read_b128 v[156:159], v217 offset:3072
	s_add_u32 s44, s42, 0xfff80080
	s_addc_u32 s45, s43, -1
	s_cmp_eq_u32 s58, 28
	s_cselect_b32 s47, s0, s45
	s_cselect_b32 s46, s1, s44
	s_cselect_b32 s45, s3, s35
	s_cselect_b32 s44, s9, s25
	v_lshl_add_u64 v[208:209], s[42:43], 0, v[184:185]
	s_add_i32 m0, s41, 0xc000
	ds_read_b128 v[160:163], v218
	ds_read_b128 v[164:167], v218 offset:1024
	ds_read_b128 v[168:171], v218 offset:2048
	ds_read_b128 v[172:175], v218 offset:3072
	ds_read_b128 v[192:195], v218 offset:4096
	ds_read_b128 v[196:199], v218 offset:5120
	ds_read_b128 v[200:203], v218 offset:6144
	ds_read_b128 v[204:207], v218 offset:7168
	global_load_lds_dwordx4 v[208:209], off
	v_lshl_add_u64 v[208:209], s[42:43], 0, v[186:187]
	s_add_i32 m0, s41, 0xe000
	s_nop 0
	global_load_lds_dwordx4 v[208:209], off
	s_waitcnt vmcnt(8)
	s_waitcnt lgkmcnt(0)
	s_setprio 1
	s_barrier
	v_mfma_f32_16x16x32_bf16 v[124:127], v[128:131], v[160:163], v[124:127]
	v_mfma_f32_16x16x32_bf16 v[120:123], v[136:139], v[160:163], v[120:123]
	v_mfma_f32_16x16x32_bf16 v[108:111], v[128:131], v[168:171], v[108:111]
	v_mfma_f32_16x16x32_bf16 v[104:107], v[136:139], v[168:171], v[104:107]
	v_mfma_f32_16x16x32_bf16 v[92:95], v[128:131], v[192:195], v[92:95]
	v_mfma_f32_16x16x32_bf16 v[88:91], v[136:139], v[192:195], v[88:91]
	v_mfma_f32_16x16x32_bf16 v[76:79], v[128:131], v[200:203], v[76:79]
	v_mfma_f32_16x16x32_bf16 v[72:75], v[136:139], v[200:203], v[72:75]
	v_mfma_f32_16x16x32_bf16 v[124:127], v[132:135], v[164:167], v[124:127]
	v_mfma_f32_16x16x32_bf16 v[120:123], v[140:143], v[164:167], v[120:123]
	v_mfma_f32_16x16x32_bf16 v[108:111], v[132:135], v[172:175], v[108:111]
	v_mfma_f32_16x16x32_bf16 v[104:107], v[140:143], v[172:175], v[104:107]
	v_mfma_f32_16x16x32_bf16 v[92:95], v[132:135], v[196:199], v[92:95]
	v_mfma_f32_16x16x32_bf16 v[88:91], v[140:143], v[196:199], v[88:91]
	v_mfma_f32_16x16x32_bf16 v[76:79], v[132:135], v[204:207], v[76:79]
	v_mfma_f32_16x16x32_bf16 v[72:75], v[140:143], v[204:207], v[72:75]
	s_setprio 0
	s_setprio 1
	v_mfma_f32_16x16x32_bf16 v[116:119], v[144:147], v[160:163], v[116:119]
	v_mfma_f32_16x16x32_bf16 v[112:115], v[152:155], v[160:163], v[112:115]
	v_mfma_f32_16x16x32_bf16 v[100:103], v[144:147], v[168:171], v[100:103]
	v_mfma_f32_16x16x32_bf16 v[96:99], v[152:155], v[168:171], v[96:99]
	v_mfma_f32_16x16x32_bf16 v[84:87], v[144:147], v[192:195], v[84:87]
	v_mfma_f32_16x16x32_bf16 v[80:83], v[152:155], v[192:195], v[80:83]
	v_mfma_f32_16x16x32_bf16 v[68:71], v[144:147], v[200:203], v[68:71]
	v_mfma_f32_16x16x32_bf16 v[64:67], v[152:155], v[200:203], v[64:67]
	v_mfma_f32_16x16x32_bf16 v[116:119], v[148:151], v[164:167], v[116:119]
	v_mfma_f32_16x16x32_bf16 v[112:115], v[156:159], v[164:167], v[112:115]
	v_mfma_f32_16x16x32_bf16 v[100:103], v[148:151], v[172:175], v[100:103]
	v_mfma_f32_16x16x32_bf16 v[96:99], v[156:159], v[172:175], v[96:99]
	v_mfma_f32_16x16x32_bf16 v[84:87], v[148:151], v[196:199], v[84:87]
	v_mfma_f32_16x16x32_bf16 v[80:83], v[156:159], v[196:199], v[80:83]
	v_mfma_f32_16x16x32_bf16 v[68:71], v[148:151], v[204:207], v[68:71]
	v_mfma_f32_16x16x32_bf16 v[64:67], v[156:159], v[204:207], v[64:67]
	s_setprio 0
	s_barrier
	s_add_i32 s59, s55, s31
	v_lshl_add_u64 v[208:209], s[44:45], 0, v[178:179]
	s_mov_b32 m0, s59
	ds_read_b128 v[160:163], v218 offset:16384
	ds_read_b128 v[164:167], v218 offset:17408
	ds_read_b128 v[168:171], v218 offset:18432
	ds_read_b128 v[172:175], v218 offset:19456
	ds_read_b128 v[192:195], v218 offset:20480
	ds_read_b128 v[196:199], v218 offset:21504
	ds_read_b128 v[200:203], v218 offset:22528
	ds_read_b128 v[204:207], v218 offset:23552
	global_load_lds_dwordx4 v[208:209], off
	s_add_i32 m0, s59, 0x2000
	s_add_u32 s60, s44, 0x80000
	v_lshl_add_u64 v[210:211], s[44:45], 0, v[182:183]
	s_addc_u32 s61, s45, 0
	s_add_i32 s59, s56, s31
	global_load_lds_dwordx4 v[210:211], off
	v_lshl_add_u64 v[222:223], s[60:61], 0, v[178:179]
	s_mov_b32 m0, s59
	v_lshl_add_u64 v[224:225], s[46:47], 0, v[180:181]
	global_load_lds_dwordx4 v[222:223], off
	v_lshl_add_u64 v[222:223], s[60:61], 0, v[182:183]
	s_add_i32 m0, s59, 0x2000
	s_nop 0
	global_load_lds_dwordx4 v[222:223], off
	v_lshl_add_u64 v[222:223], s[46:47], 0, v[176:177]
	s_mov_b32 m0, s41
	s_nop 0
	global_load_lds_dwordx4 v[222:223], off
	s_mov_b32 m0, s48
	s_nop 0
	global_load_lds_dwordx4 v[224:225], off
	s_waitcnt vmcnt(8)
	s_waitcnt lgkmcnt(0)
	s_setprio 1
	s_barrier
	v_mfma_f32_16x16x32_bf16 v[60:63], v[128:131], v[160:163], v[60:63]
	v_mfma_f32_16x16x32_bf16 v[56:59], v[136:139], v[160:163], v[56:59]
	v_mfma_f32_16x16x32_bf16 v[44:47], v[128:131], v[168:171], v[44:47]
	v_mfma_f32_16x16x32_bf16 v[40:43], v[136:139], v[168:171], v[40:43]
	v_mfma_f32_16x16x32_bf16 v[28:31], v[128:131], v[192:195], v[28:31]
	v_mfma_f32_16x16x32_bf16 v[24:27], v[136:139], v[192:195], v[24:27]
	v_mfma_f32_16x16x32_bf16 v[12:15], v[128:131], v[200:203], v[12:15]
	v_mfma_f32_16x16x32_bf16 v[8:11], v[136:139], v[200:203], v[8:11]
	v_mfma_f32_16x16x32_bf16 v[60:63], v[132:135], v[164:167], v[60:63]
	v_mfma_f32_16x16x32_bf16 v[56:59], v[140:143], v[164:167], v[56:59]
	v_mfma_f32_16x16x32_bf16 v[44:47], v[132:135], v[172:175], v[44:47]
	v_mfma_f32_16x16x32_bf16 v[40:43], v[140:143], v[172:175], v[40:43]
	v_mfma_f32_16x16x32_bf16 v[28:31], v[132:135], v[196:199], v[28:31]
	v_mfma_f32_16x16x32_bf16 v[24:27], v[140:143], v[196:199], v[24:27]
	v_mfma_f32_16x16x32_bf16 v[12:15], v[132:135], v[204:207], v[12:15]
	v_mfma_f32_16x16x32_bf16 v[8:11], v[140:143], v[204:207], v[8:11]
	s_setprio 0
	s_setprio 1
	v_mfma_f32_16x16x32_bf16 v[52:55], v[144:147], v[160:163], v[52:55]
	v_mfma_f32_16x16x32_bf16 v[48:51], v[152:155], v[160:163], v[48:51]
	v_mfma_f32_16x16x32_bf16 v[36:39], v[144:147], v[168:171], v[36:39]
	v_mfma_f32_16x16x32_bf16 v[32:35], v[152:155], v[168:171], v[32:35]
	v_mfma_f32_16x16x32_bf16 v[20:23], v[144:147], v[192:195], v[20:23]
	v_mfma_f32_16x16x32_bf16 v[16:19], v[152:155], v[192:195], v[16:19]
	v_mfma_f32_16x16x32_bf16 v[4:7], v[144:147], v[200:203], v[4:7]
	v_mfma_f32_16x16x32_bf16 v[0:3], v[152:155], v[200:203], v[0:3]
	v_mfma_f32_16x16x32_bf16 v[52:55], v[148:151], v[164:167], v[52:55]
	v_mfma_f32_16x16x32_bf16 v[48:51], v[156:159], v[164:167], v[48:51]
	v_mfma_f32_16x16x32_bf16 v[36:39], v[148:151], v[172:175], v[36:39]
	v_mfma_f32_16x16x32_bf16 v[32:35], v[156:159], v[172:175], v[32:35]
	v_mfma_f32_16x16x32_bf16 v[20:23], v[148:151], v[196:199], v[20:23]
	v_mfma_f32_16x16x32_bf16 v[16:19], v[156:159], v[196:199], v[16:19]
	v_mfma_f32_16x16x32_bf16 v[4:7], v[148:151], v[204:207], v[4:7]
	v_mfma_f32_16x16x32_bf16 v[0:3], v[156:159], v[204:207], v[0:3]
	s_setprio 0
	s_barrier
	s_add_i32 s59, 0, 0x18000
	s_add_i32 s60, 0, 0x1c000
	v_add_u32_e32 v140, s59, v214
	v_add_u32_e32 v156, s60, v214
	ds_read_b128 v[128:131], v140
	ds_read_b128 v[132:135], v140 offset:1024
	ds_read_b128 v[136:139], v140 offset:2048
	ds_read_b128 v[140:143], v140 offset:3072
	ds_read_b128 v[144:147], v156
	ds_read_b128 v[148:151], v156 offset:1024
	ds_read_b128 v[152:155], v156 offset:2048
	ds_read_b128 v[156:159], v156 offset:3072
	s_add_u32 s46, s46, 0x80000
	s_addc_u32 s47, s47, 0
	s_mov_b32 m0, s49
	v_lshl_add_u64 v[226:227], s[46:47], 0, v[176:177]
	ds_read_b128 v[160:163], v218 offset:32768
	ds_read_b128 v[164:167], v218 offset:33792
	ds_read_b128 v[168:171], v218 offset:34816
	ds_read_b128 v[172:175], v218 offset:35840
	ds_read_b128 v[192:195], v218 offset:36864
	ds_read_b128 v[196:199], v218 offset:37888
	ds_read_b128 v[200:203], v218 offset:38912
	ds_read_b128 v[204:207], v218 offset:39936
	global_load_lds_dwordx4 v[226:227], off
	v_lshl_add_u64 v[226:227], s[46:47], 0, v[180:181]
	s_mov_b32 m0, s50
	s_nop 0
	global_load_lds_dwordx4 v[226:227], off
	s_waitcnt vmcnt(8)
	s_waitcnt lgkmcnt(0)
	s_setprio 1
	s_barrier
	v_mfma_f32_16x16x32_bf16 v[124:127], v[128:131], v[160:163], v[124:127]
	v_mfma_f32_16x16x32_bf16 v[120:123], v[136:139], v[160:163], v[120:123]
	v_mfma_f32_16x16x32_bf16 v[108:111], v[128:131], v[168:171], v[108:111]
	v_mfma_f32_16x16x32_bf16 v[104:107], v[136:139], v[168:171], v[104:107]
	v_mfma_f32_16x16x32_bf16 v[92:95], v[128:131], v[192:195], v[92:95]
	v_mfma_f32_16x16x32_bf16 v[88:91], v[136:139], v[192:195], v[88:91]
	v_mfma_f32_16x16x32_bf16 v[76:79], v[128:131], v[200:203], v[76:79]
	v_mfma_f32_16x16x32_bf16 v[72:75], v[136:139], v[200:203], v[72:75]
	v_mfma_f32_16x16x32_bf16 v[124:127], v[132:135], v[164:167], v[124:127]
	v_mfma_f32_16x16x32_bf16 v[120:123], v[140:143], v[164:167], v[120:123]
	v_mfma_f32_16x16x32_bf16 v[108:111], v[132:135], v[172:175], v[108:111]
	v_mfma_f32_16x16x32_bf16 v[104:107], v[140:143], v[172:175], v[104:107]
	v_mfma_f32_16x16x32_bf16 v[92:95], v[132:135], v[196:199], v[92:95]
	v_mfma_f32_16x16x32_bf16 v[88:91], v[140:143], v[196:199], v[88:91]
	v_mfma_f32_16x16x32_bf16 v[76:79], v[132:135], v[204:207], v[76:79]
	v_mfma_f32_16x16x32_bf16 v[72:75], v[140:143], v[204:207], v[72:75]
	s_setprio 0
	s_setprio 1
	v_mfma_f32_16x16x32_bf16 v[116:119], v[144:147], v[160:163], v[116:119]
	v_mfma_f32_16x16x32_bf16 v[112:115], v[152:155], v[160:163], v[112:115]
	v_mfma_f32_16x16x32_bf16 v[100:103], v[144:147], v[168:171], v[100:103]
	v_mfma_f32_16x16x32_bf16 v[96:99], v[152:155], v[168:171], v[96:99]
	v_mfma_f32_16x16x32_bf16 v[84:87], v[144:147], v[192:195], v[84:87]
	v_mfma_f32_16x16x32_bf16 v[80:83], v[152:155], v[192:195], v[80:83]
	v_mfma_f32_16x16x32_bf16 v[68:71], v[144:147], v[200:203], v[68:71]
	v_mfma_f32_16x16x32_bf16 v[64:67], v[152:155], v[200:203], v[64:67]
	v_mfma_f32_16x16x32_bf16 v[116:119], v[148:151], v[164:167], v[116:119]
	v_mfma_f32_16x16x32_bf16 v[112:115], v[156:159], v[164:167], v[112:115]
	v_mfma_f32_16x16x32_bf16 v[100:103], v[148:151], v[172:175], v[100:103]
	v_mfma_f32_16x16x32_bf16 v[96:99], v[156:159], v[172:175], v[96:99]
	v_mfma_f32_16x16x32_bf16 v[84:87], v[148:151], v[196:199], v[84:87]
	v_mfma_f32_16x16x32_bf16 v[80:83], v[156:159], v[196:199], v[80:83]
	v_mfma_f32_16x16x32_bf16 v[68:71], v[148:151], v[204:207], v[68:71]
	v_mfma_f32_16x16x32_bf16 v[64:67], v[156:159], v[204:207], v[64:67]
	s_setprio 0
	s_barrier
	s_add_i32 s46, s59, s31
	v_lshl_add_u64 v[208:209], v[208:209], 0, s[20:21]
	s_mov_b32 m0, s46
	ds_read_b128 v[160:163], v218 offset:49152
	ds_read_b128 v[164:167], v218 offset:50176
	ds_read_b128 v[168:171], v218 offset:51200
	ds_read_b128 v[172:175], v218 offset:52224
	ds_read_b128 v[192:195], v218 offset:53248
	ds_read_b128 v[196:199], v218 offset:54272
	ds_read_b128 v[200:203], v218 offset:55296
	ds_read_b128 v[204:207], v218 offset:56320
	global_load_lds_dwordx4 v[208:209], off
	s_add_i32 m0, s46, 0x2000
	s_add_u32 s44, s44, 0x80080
	v_lshl_add_u64 v[208:209], v[210:211], 0, s[20:21]
	s_addc_u32 s45, s45, 0
	s_add_i32 s46, s60, s31
	global_load_lds_dwordx4 v[208:209], off
	v_lshl_add_u64 v[208:209], s[44:45], 0, v[178:179]
	s_mov_b32 m0, s46
	s_nop 0
	global_load_lds_dwordx4 v[208:209], off
	v_lshl_add_u64 v[208:209], s[44:45], 0, v[182:183]
	s_add_i32 m0, s46, 0x2000
	s_nop 0
	global_load_lds_dwordx4 v[208:209], off
	v_lshl_add_u64 v[208:209], v[222:223], 0, s[20:21]
	s_mov_b32 m0, s52
	s_nop 0
	global_load_lds_dwordx4 v[208:209], off
	v_lshl_add_u64 v[208:209], v[224:225], 0, s[20:21]
	s_mov_b32 m0, s53
	s_nop 0
	global_load_lds_dwordx4 v[208:209], off
	s_waitcnt vmcnt(8)
	s_waitcnt lgkmcnt(0)
	s_setprio 1
	s_barrier
	v_mfma_f32_16x16x32_bf16 v[60:63], v[128:131], v[160:163], v[60:63]
	v_mfma_f32_16x16x32_bf16 v[56:59], v[136:139], v[160:163], v[56:59]
	v_mfma_f32_16x16x32_bf16 v[44:47], v[128:131], v[168:171], v[44:47]
	v_mfma_f32_16x16x32_bf16 v[40:43], v[136:139], v[168:171], v[40:43]
	v_mfma_f32_16x16x32_bf16 v[28:31], v[128:131], v[192:195], v[28:31]
	v_mfma_f32_16x16x32_bf16 v[24:27], v[136:139], v[192:195], v[24:27]
	v_mfma_f32_16x16x32_bf16 v[12:15], v[128:131], v[200:203], v[12:15]
	v_mfma_f32_16x16x32_bf16 v[8:11], v[136:139], v[200:203], v[8:11]
	v_mfma_f32_16x16x32_bf16 v[60:63], v[132:135], v[164:167], v[60:63]
	v_mfma_f32_16x16x32_bf16 v[56:59], v[140:143], v[164:167], v[56:59]
	v_mfma_f32_16x16x32_bf16 v[44:47], v[132:135], v[172:175], v[44:47]
	v_mfma_f32_16x16x32_bf16 v[40:43], v[140:143], v[172:175], v[40:43]
	v_mfma_f32_16x16x32_bf16 v[28:31], v[132:135], v[196:199], v[28:31]
	v_mfma_f32_16x16x32_bf16 v[24:27], v[140:143], v[196:199], v[24:27]
	v_mfma_f32_16x16x32_bf16 v[12:15], v[132:135], v[204:207], v[12:15]
	v_mfma_f32_16x16x32_bf16 v[8:11], v[140:143], v[204:207], v[8:11]
	s_setprio 0
	s_setprio 1
	v_mfma_f32_16x16x32_bf16 v[52:55], v[144:147], v[160:163], v[52:55]
	v_mfma_f32_16x16x32_bf16 v[48:51], v[152:155], v[160:163], v[48:51]
	v_mfma_f32_16x16x32_bf16 v[36:39], v[144:147], v[168:171], v[36:39]
	v_mfma_f32_16x16x32_bf16 v[32:35], v[152:155], v[168:171], v[32:35]
	v_mfma_f32_16x16x32_bf16 v[20:23], v[144:147], v[192:195], v[20:23]
	v_mfma_f32_16x16x32_bf16 v[16:19], v[152:155], v[192:195], v[16:19]
	v_mfma_f32_16x16x32_bf16 v[4:7], v[144:147], v[200:203], v[4:7]
	v_mfma_f32_16x16x32_bf16 v[0:3], v[152:155], v[200:203], v[0:3]
	v_mfma_f32_16x16x32_bf16 v[52:55], v[148:151], v[164:167], v[52:55]
	v_mfma_f32_16x16x32_bf16 v[48:51], v[156:159], v[164:167], v[48:51]
	v_mfma_f32_16x16x32_bf16 v[36:39], v[148:151], v[172:175], v[36:39]
	v_mfma_f32_16x16x32_bf16 v[32:35], v[156:159], v[172:175], v[32:35]
	v_mfma_f32_16x16x32_bf16 v[20:23], v[148:151], v[196:199], v[20:23]
	v_mfma_f32_16x16x32_bf16 v[16:19], v[156:159], v[196:199], v[16:19]
	v_mfma_f32_16x16x32_bf16 v[4:7], v[148:151], v[204:207], v[4:7]
	v_mfma_f32_16x16x32_bf16 v[0:3], v[156:159], v[204:207], v[0:3]
	s_setprio 0
	s_barrier
	s_add_i32 s58, s58, 2
	s_add_u32 s42, s42, 0x100
	s_addc_u32 s43, s43, 0
	s_add_u32 s25, s25, 0x100
	s_addc_u32 s35, s35, 0
	s_cmp_gt_u32 s58, 29
	s_cbranch_scc0 .LBB0_543
	s_and_b64 vcc, exec, s[22:23]
	s_cbranch_vccz .LBB0_546
	s_barrier

.LBB0_635:
	s_ashr_i32 s67, s66, 31
	s_lshl_b64 s[12:13], s[66:67], 20
	s_add_u32 s70, s55, s12
	s_addc_u32 s71, s57, s13
	s_and_b64 s[6:7], s[6:7], exec
	s_cselect_b32 s1, s71, s11
	s_cselect_b32 s3, s70, s10
	s_add_u32 s6, s8, 0x80080
	s_addc_u32 s7, s9, 0
	s_add_u32 s12, s10, 0x100
	s_addc_u32 s13, s11, 0
	s_mov_b32 s15, -2
	s_waitcnt vmcnt(0)
	ds_read_b128 v[148:151], v197
	ds_read_b128 v[170:173], v197 offset:1024
	ds_read_b128 v[174:177], v197 offset:2048
	ds_read_b128 v[178:181], v197 offset:3072
	ds_read_b128 v[182:185], v198
	ds_read_b128 v[186:189], v198 offset:1024
	ds_read_b128 v[202:205], v198 offset:2048
	ds_read_b128 v[206:209], v198 offset:3072
	s_add_u32 s8, s6, 0xfff80080
	s_addc_u32 s9, s7, -1
	s_cmp_eq_u32 s15, 28
	s_cselect_b32 s11, s69, s9
	s_cselect_b32 s10, s68, s8
	s_cselect_b32 s9, s1, s13
	s_cselect_b32 s8, s3, s12
	v_lshl_add_u64 v[134:135], s[6:7], 0, v[162:163]
	s_add_i32 m0, s72, 0xc000
	ds_read_b128 v[214:217], v199
	ds_read_b128 v[218:221], v199 offset:1024
	ds_read_b128 v[222:225], v199 offset:2048
	ds_read_b128 v[226:229], v199 offset:3072
	ds_read_b128 v[230:233], v199 offset:4096
	ds_read_b128 v[234:237], v199 offset:5120
	ds_read_b128 v[238:241], v199 offset:6144
	ds_read_b128 v[242:245], v199 offset:7168
	global_load_lds_dwordx4 v[134:135], off
	v_lshl_add_u64 v[134:135], s[6:7], 0, v[164:165]
	s_add_i32 m0, s72, 0xe000
	s_nop 0
	global_load_lds_dwordx4 v[134:135], off
	s_waitcnt vmcnt(8)
	s_waitcnt lgkmcnt(0)
	s_setprio 1
	s_barrier
	v_mfma_f32_16x16x32_bf16 v[112:115], v[148:151], v[214:217], 0
	v_mfma_f32_16x16x32_bf16 v[80:83], v[174:177], v[214:217], 0
	v_mfma_f32_16x16x32_bf16 v[116:119], v[148:151], v[222:225], 0
	v_mfma_f32_16x16x32_bf16 v[88:91], v[174:177], v[222:225], 0
	v_mfma_f32_16x16x32_bf16 v[124:127], v[148:151], v[230:233], 0
	v_mfma_f32_16x16x32_bf16 v[92:95], v[174:177], v[230:233], 0
	v_mfma_f32_16x16x32_bf16 v[120:123], v[148:151], v[238:241], 0
	v_mfma_f32_16x16x32_bf16 v[84:87], v[174:177], v[238:241], 0
	v_mfma_f32_16x16x32_bf16 v[112:115], v[170:173], v[218:221], v[112:115]
	v_mfma_f32_16x16x32_bf16 v[80:83], v[178:181], v[218:221], v[80:83]
	v_mfma_f32_16x16x32_bf16 v[116:119], v[170:173], v[226:229], v[116:119]
	v_mfma_f32_16x16x32_bf16 v[88:91], v[178:181], v[226:229], v[88:91]
	v_mfma_f32_16x16x32_bf16 v[124:127], v[170:173], v[234:237], v[124:127]
	v_mfma_f32_16x16x32_bf16 v[92:95], v[178:181], v[234:237], v[92:95]
	v_mfma_f32_16x16x32_bf16 v[120:123], v[170:173], v[242:245], v[120:123]
	v_mfma_f32_16x16x32_bf16 v[84:87], v[178:181], v[242:245], v[84:87]
	s_setprio 0
	s_setprio 1
	v_mfma_f32_16x16x32_bf16 v[108:111], v[182:185], v[214:217], 0
	v_mfma_f32_16x16x32_bf16 v[76:79], v[202:205], v[214:217], 0
	v_mfma_f32_16x16x32_bf16 v[104:107], v[182:185], v[222:225], 0
	v_mfma_f32_16x16x32_bf16 v[72:75], v[202:205], v[222:225], 0
	v_mfma_f32_16x16x32_bf16 v[100:103], v[182:185], v[230:233], 0
	v_mfma_f32_16x16x32_bf16 v[68:71], v[202:205], v[230:233], 0
	v_mfma_f32_16x16x32_bf16 v[96:99], v[182:185], v[238:241], 0
	v_mfma_f32_16x16x32_bf16 v[64:67], v[202:205], v[238:241], 0
	v_mfma_f32_16x16x32_bf16 v[108:111], v[186:189], v[218:221], v[108:111]
	v_mfma_f32_16x16x32_bf16 v[76:79], v[206:209], v[218:221], v[76:79]
	v_mfma_f32_16x16x32_bf16 v[104:107], v[186:189], v[226:229], v[104:107]
	v_mfma_f32_16x16x32_bf16 v[72:75], v[206:209], v[226:229], v[72:75]
	v_mfma_f32_16x16x32_bf16 v[100:103], v[186:189], v[234:237], v[100:103]
	v_mfma_f32_16x16x32_bf16 v[68:71], v[206:209], v[234:237], v[68:71]
	v_mfma_f32_16x16x32_bf16 v[96:99], v[186:189], v[242:245], v[96:99]
	v_mfma_f32_16x16x32_bf16 v[64:67], v[206:209], v[242:245], v[64:67]
	s_setprio 0
	s_barrier
	s_add_i32 s16, s94, s63
	v_lshl_add_u64 v[134:135], s[8:9], 0, v[154:155]
	s_mov_b32 m0, s16
	ds_read_b128 v[214:217], v199 offset:16384
	ds_read_b128 v[218:221], v199 offset:17408
	ds_read_b128 v[222:225], v199 offset:18432
	ds_read_b128 v[226:229], v199 offset:19456
	ds_read_b128 v[230:233], v199 offset:20480
	ds_read_b128 v[234:237], v199 offset:21504
	ds_read_b128 v[238:241], v199 offset:22528
	ds_read_b128 v[242:245], v199 offset:23552
	global_load_lds_dwordx4 v[134:135], off
	s_add_i32 m0, s16, 0x2000
	s_add_u32 s16, s8, 0x80000
	v_lshl_add_u64 v[190:191], s[8:9], 0, v[158:159]
	s_addc_u32 s17, s9, 0
	s_add_i32 s18, s95, s63
	global_load_lds_dwordx4 v[190:191], off
	v_lshl_add_u64 v[210:211], s[16:17], 0, v[154:155]
	s_mov_b32 m0, s18
	v_lshl_add_u64 v[246:247], s[10:11], 0, v[156:157]
	global_load_lds_dwordx4 v[210:211], off
	v_lshl_add_u64 v[210:211], s[16:17], 0, v[158:159]
	s_add_i32 m0, s18, 0x2000
	s_nop 0
	global_load_lds_dwordx4 v[210:211], off
	v_lshl_add_u64 v[210:211], s[10:11], 0, v[152:153]
	s_mov_b32 m0, s72
	s_nop 0
	global_load_lds_dwordx4 v[210:211], off
	s_mov_b32 m0, s73
	s_nop 0
	global_load_lds_dwordx4 v[246:247], off
	s_waitcnt vmcnt(8)
	s_waitcnt lgkmcnt(0)
	s_setprio 1
	s_barrier
	v_mfma_f32_16x16x32_bf16 v[48:51], v[148:151], v[214:217], 0
	v_mfma_f32_16x16x32_bf16 v[16:19], v[174:177], v[214:217], 0
	v_mfma_f32_16x16x32_bf16 v[52:55], v[148:151], v[222:225], 0
	v_mfma_f32_16x16x32_bf16 v[24:27], v[174:177], v[222:225], 0
	v_mfma_f32_16x16x32_bf16 v[60:63], v[148:151], v[230:233], 0
	v_mfma_f32_16x16x32_bf16 v[28:31], v[174:177], v[230:233], 0
	v_mfma_f32_16x16x32_bf16 v[56:59], v[148:151], v[238:241], 0
	v_mfma_f32_16x16x32_bf16 v[20:23], v[174:177], v[238:241], 0
	v_mfma_f32_16x16x32_bf16 v[48:51], v[170:173], v[218:221], v[48:51]
	v_mfma_f32_16x16x32_bf16 v[16:19], v[178:181], v[218:221], v[16:19]
	v_mfma_f32_16x16x32_bf16 v[52:55], v[170:173], v[226:229], v[52:55]
	v_mfma_f32_16x16x32_bf16 v[24:27], v[178:181], v[226:229], v[24:27]
	v_mfma_f32_16x16x32_bf16 v[60:63], v[170:173], v[234:237], v[60:63]
	v_mfma_f32_16x16x32_bf16 v[28:31], v[178:181], v[234:237], v[28:31]
	v_mfma_f32_16x16x32_bf16 v[56:59], v[170:173], v[242:245], v[56:59]
	v_mfma_f32_16x16x32_bf16 v[20:23], v[178:181], v[242:245], v[20:23]
	s_setprio 0
	s_setprio 1
	v_mfma_f32_16x16x32_bf16 v[44:47], v[182:185], v[214:217], 0
	v_mfma_f32_16x16x32_bf16 v[12:15], v[202:205], v[214:217], 0
	v_mfma_f32_16x16x32_bf16 v[40:43], v[182:185], v[222:225], 0
	v_mfma_f32_16x16x32_bf16 v[8:11], v[202:205], v[222:225], 0
	v_mfma_f32_16x16x32_bf16 v[36:39], v[182:185], v[230:233], 0
	v_mfma_f32_16x16x32_bf16 v[4:7], v[202:205], v[230:233], 0
	v_mfma_f32_16x16x32_bf16 v[32:35], v[182:185], v[238:241], 0
	v_mfma_f32_16x16x32_bf16 v[0:3], v[202:205], v[238:241], 0
	v_mfma_f32_16x16x32_bf16 v[44:47], v[186:189], v[218:221], v[44:47]
	v_mfma_f32_16x16x32_bf16 v[12:15], v[206:209], v[218:221], v[12:15]
	v_mfma_f32_16x16x32_bf16 v[40:43], v[186:189], v[226:229], v[40:43]
	v_mfma_f32_16x16x32_bf16 v[8:11], v[206:209], v[226:229], v[8:11]
	v_mfma_f32_16x16x32_bf16 v[36:39], v[186:189], v[234:237], v[36:39]
	v_mfma_f32_16x16x32_bf16 v[4:7], v[206:209], v[234:237], v[4:7]
	v_mfma_f32_16x16x32_bf16 v[32:35], v[186:189], v[242:245], v[32:35]
	v_mfma_f32_16x16x32_bf16 v[0:3], v[206:209], v[242:245], v[0:3]
	s_setprio 0
	s_barrier
	s_add_i32 s16, 0, 0x18000
	s_add_i32 s17, 0, 0x1c000
	v_add_u32_e32 v178, s16, v196
	v_add_u32_e32 v201, s17, v196
	ds_read_b128 v[148:151], v178
	ds_read_b128 v[170:173], v178 offset:1024
	ds_read_b128 v[174:177], v178 offset:2048
	ds_read_b128 v[178:181], v178 offset:3072
	ds_read_b128 v[182:185], v201
	ds_read_b128 v[186:189], v201 offset:1024
	ds_read_b128 v[202:205], v201 offset:2048
	ds_read_b128 v[206:209], v201 offset:3072
	s_add_u32 s10, s10, 0x80000
	s_addc_u32 s11, s11, 0
	s_mov_b32 m0, s74
	v_lshl_add_u64 v[248:249], s[10:11], 0, v[152:153]
	ds_read_b128 v[214:217], v199 offset:32768
	ds_read_b128 v[218:221], v199 offset:33792
	ds_read_b128 v[222:225], v199 offset:34816
	ds_read_b128 v[226:229], v199 offset:35840
	ds_read_b128 v[230:233], v199 offset:36864
	ds_read_b128 v[234:237], v199 offset:37888
	ds_read_b128 v[238:241], v199 offset:38912
	ds_read_b128 v[242:245], v199 offset:39936
	global_load_lds_dwordx4 v[248:249], off
	v_lshl_add_u64 v[248:249], s[10:11], 0, v[156:157]
	s_mov_b32 m0, s75
	s_nop 0
	global_load_lds_dwordx4 v[248:249], off
	s_waitcnt vmcnt(8)
	s_waitcnt lgkmcnt(0)
	s_setprio 1
	s_barrier
	v_mfma_f32_16x16x32_bf16 v[112:115], v[148:151], v[214:217], v[112:115]
	v_mfma_f32_16x16x32_bf16 v[80:83], v[174:177], v[214:217], v[80:83]
	v_mfma_f32_16x16x32_bf16 v[116:119], v[148:151], v[222:225], v[116:119]
	v_mfma_f32_16x16x32_bf16 v[88:91], v[174:177], v[222:225], v[88:91]
	v_mfma_f32_16x16x32_bf16 v[124:127], v[148:151], v[230:233], v[124:127]
	v_mfma_f32_16x16x32_bf16 v[92:95], v[174:177], v[230:233], v[92:95]
	v_mfma_f32_16x16x32_bf16 v[120:123], v[148:151], v[238:241], v[120:123]
	v_mfma_f32_16x16x32_bf16 v[84:87], v[174:177], v[238:241], v[84:87]
	v_mfma_f32_16x16x32_bf16 v[112:115], v[170:173], v[218:221], v[112:115]
	v_mfma_f32_16x16x32_bf16 v[80:83], v[178:181], v[218:221], v[80:83]
	v_mfma_f32_16x16x32_bf16 v[116:119], v[170:173], v[226:229], v[116:119]
	v_mfma_f32_16x16x32_bf16 v[88:91], v[178:181], v[226:229], v[88:91]
	v_mfma_f32_16x16x32_bf16 v[124:127], v[170:173], v[234:237], v[124:127]
	v_mfma_f32_16x16x32_bf16 v[92:95], v[178:181], v[234:237], v[92:95]
	v_mfma_f32_16x16x32_bf16 v[120:123], v[170:173], v[242:245], v[120:123]
	v_mfma_f32_16x16x32_bf16 v[84:87], v[178:181], v[242:245], v[84:87]
	s_setprio 0
	s_setprio 1
	v_mfma_f32_16x16x32_bf16 v[108:111], v[182:185], v[214:217], v[108:111]
	v_mfma_f32_16x16x32_bf16 v[76:79], v[202:205], v[214:217], v[76:79]
	v_mfma_f32_16x16x32_bf16 v[104:107], v[182:185], v[222:225], v[104:107]
	v_mfma_f32_16x16x32_bf16 v[72:75], v[202:205], v[222:225], v[72:75]
	v_mfma_f32_16x16x32_bf16 v[100:103], v[182:185], v[230:233], v[100:103]
	v_mfma_f32_16x16x32_bf16 v[68:71], v[202:205], v[230:233], v[68:71]
	v_mfma_f32_16x16x32_bf16 v[96:99], v[182:185], v[238:241], v[96:99]
	v_mfma_f32_16x16x32_bf16 v[64:67], v[202:205], v[238:241], v[64:67]
	v_mfma_f32_16x16x32_bf16 v[108:111], v[186:189], v[218:221], v[108:111]
	v_mfma_f32_16x16x32_bf16 v[76:79], v[206:209], v[218:221], v[76:79]
	v_mfma_f32_16x16x32_bf16 v[104:107], v[186:189], v[226:229], v[104:107]
	v_mfma_f32_16x16x32_bf16 v[72:75], v[206:209], v[226:229], v[72:75]
	v_mfma_f32_16x16x32_bf16 v[100:103], v[186:189], v[234:237], v[100:103]
	v_mfma_f32_16x16x32_bf16 v[68:71], v[206:209], v[234:237], v[68:71]
	v_mfma_f32_16x16x32_bf16 v[96:99], v[186:189], v[242:245], v[96:99]
	v_mfma_f32_16x16x32_bf16 v[64:67], v[206:209], v[242:245], v[64:67]
	s_setprio 0
	s_barrier
	s_add_i32 s10, s16, s63
	v_lshl_add_u64 v[134:135], v[134:135], 0, s[40:41]
	s_mov_b32 m0, s10
	ds_read_b128 v[214:217], v199 offset:49152
	ds_read_b128 v[218:221], v199 offset:50176
	ds_read_b128 v[222:225], v199 offset:51200
	ds_read_b128 v[226:229], v199 offset:52224
	ds_read_b128 v[230:233], v199 offset:53248
	ds_read_b128 v[234:237], v199 offset:54272
	ds_read_b128 v[238:241], v199 offset:55296
	ds_read_b128 v[242:245], v199 offset:56320
	global_load_lds_dwordx4 v[134:135], off
	s_add_i32 m0, s10, 0x2000
	s_add_u32 s8, s8, 0x80080
	v_lshl_add_u64 v[134:135], v[190:191], 0, s[40:41]
	s_addc_u32 s9, s9, 0
	s_add_i32 s10, s17, s63
	global_load_lds_dwordx4 v[134:135], off
	v_lshl_add_u64 v[134:135], s[8:9], 0, v[154:155]
	s_mov_b32 m0, s10
	s_nop 0
	global_load_lds_dwordx4 v[134:135], off
	v_lshl_add_u64 v[134:135], s[8:9], 0, v[158:159]
	s_add_i32 m0, s10, 0x2000
	s_nop 0
	global_load_lds_dwordx4 v[134:135], off
	v_lshl_add_u64 v[134:135], v[210:211], 0, s[40:41]
	s_mov_b32 m0, s82
	s_nop 0
	global_load_lds_dwordx4 v[134:135], off
	v_lshl_add_u64 v[134:135], v[246:247], 0, s[40:41]
	s_mov_b32 m0, s83
	s_nop 0
	global_load_lds_dwordx4 v[134:135], off
	s_waitcnt vmcnt(8)
	s_waitcnt lgkmcnt(0)
	s_setprio 1
	s_barrier
	v_mfma_f32_16x16x32_bf16 v[48:51], v[148:151], v[214:217], v[48:51]
	v_mfma_f32_16x16x32_bf16 v[16:19], v[174:177], v[214:217], v[16:19]
	v_mfma_f32_16x16x32_bf16 v[52:55], v[148:151], v[222:225], v[52:55]
	v_mfma_f32_16x16x32_bf16 v[24:27], v[174:177], v[222:225], v[24:27]
	v_mfma_f32_16x16x32_bf16 v[60:63], v[148:151], v[230:233], v[60:63]
	v_mfma_f32_16x16x32_bf16 v[28:31], v[174:177], v[230:233], v[28:31]
	v_mfma_f32_16x16x32_bf16 v[56:59], v[148:151], v[238:241], v[56:59]
	v_mfma_f32_16x16x32_bf16 v[20:23], v[174:177], v[238:241], v[20:23]
	v_mfma_f32_16x16x32_bf16 v[48:51], v[170:173], v[218:221], v[48:51]
	v_mfma_f32_16x16x32_bf16 v[16:19], v[178:181], v[218:221], v[16:19]
	v_mfma_f32_16x16x32_bf16 v[52:55], v[170:173], v[226:229], v[52:55]
	v_mfma_f32_16x16x32_bf16 v[24:27], v[178:181], v[226:229], v[24:27]
	v_mfma_f32_16x16x32_bf16 v[60:63], v[170:173], v[234:237], v[60:63]
	v_mfma_f32_16x16x32_bf16 v[28:31], v[178:181], v[234:237], v[28:31]
	v_mfma_f32_16x16x32_bf16 v[56:59], v[170:173], v[242:245], v[56:59]
	v_mfma_f32_16x16x32_bf16 v[20:23], v[178:181], v[242:245], v[20:23]
	s_setprio 0
	s_setprio 1
	v_mfma_f32_16x16x32_bf16 v[44:47], v[182:185], v[214:217], v[44:47]
	v_mfma_f32_16x16x32_bf16 v[12:15], v[202:205], v[214:217], v[12:15]
	v_mfma_f32_16x16x32_bf16 v[40:43], v[182:185], v[222:225], v[40:43]
	v_mfma_f32_16x16x32_bf16 v[8:11], v[202:205], v[222:225], v[8:11]
	v_mfma_f32_16x16x32_bf16 v[36:39], v[182:185], v[230:233], v[36:39]
	v_mfma_f32_16x16x32_bf16 v[4:7], v[202:205], v[230:233], v[4:7]
	v_mfma_f32_16x16x32_bf16 v[32:35], v[182:185], v[238:241], v[32:35]
	v_mfma_f32_16x16x32_bf16 v[0:3], v[202:205], v[238:241], v[0:3]
	v_mfma_f32_16x16x32_bf16 v[44:47], v[186:189], v[218:221], v[44:47]
	v_mfma_f32_16x16x32_bf16 v[12:15], v[206:209], v[218:221], v[12:15]
	v_mfma_f32_16x16x32_bf16 v[40:43], v[186:189], v[226:229], v[40:43]
	v_mfma_f32_16x16x32_bf16 v[8:11], v[206:209], v[226:229], v[8:11]
	v_mfma_f32_16x16x32_bf16 v[36:39], v[186:189], v[234:237], v[36:39]
	v_mfma_f32_16x16x32_bf16 v[4:7], v[206:209], v[234:237], v[4:7]
	v_mfma_f32_16x16x32_bf16 v[32:35], v[186:189], v[242:245], v[32:35]
	v_mfma_f32_16x16x32_bf16 v[0:3], v[206:209], v[242:245], v[0:3]
	s_setprio 0
	s_barrier
	s_add_i32 s15, s15, 2
	s_add_u32 s6, s6, 0x100
	s_addc_u32 s7, s7, 0
	s_add_u32 s12, s12, 0x100
	s_addc_u32 s13, s13, 0
	s_cmp_gt_u32 s15, 29
.LBB0_636:
	ds_read_b128 v[148:151], v197
	ds_read_b128 v[170:173], v197 offset:1024
	ds_read_b128 v[174:177], v197 offset:2048
	ds_read_b128 v[178:181], v197 offset:3072
	ds_read_b128 v[182:185], v198
	ds_read_b128 v[186:189], v198 offset:1024
	ds_read_b128 v[202:205], v198 offset:2048
	ds_read_b128 v[206:209], v198 offset:3072
	s_add_u32 s8, s6, 0xfff80080
	s_addc_u32 s9, s7, -1
	s_cmp_eq_u32 s15, 28
	s_cselect_b32 s11, s69, s9
	s_cselect_b32 s10, s68, s8
	s_cselect_b32 s9, s1, s13
	s_cselect_b32 s8, s3, s12
	v_lshl_add_u64 v[134:135], s[6:7], 0, v[162:163]
	s_add_i32 m0, s72, 0xc000
	ds_read_b128 v[214:217], v199
	ds_read_b128 v[218:221], v199 offset:1024
	ds_read_b128 v[222:225], v199 offset:2048
	ds_read_b128 v[226:229], v199 offset:3072
	ds_read_b128 v[230:233], v199 offset:4096
	ds_read_b128 v[234:237], v199 offset:5120
	ds_read_b128 v[238:241], v199 offset:6144
	ds_read_b128 v[242:245], v199 offset:7168
	global_load_lds_dwordx4 v[134:135], off
	v_lshl_add_u64 v[134:135], s[6:7], 0, v[164:165]
	s_add_i32 m0, s72, 0xe000
	s_nop 0
	global_load_lds_dwordx4 v[134:135], off
	s_waitcnt vmcnt(8)
	s_waitcnt lgkmcnt(0)
	s_setprio 1
	s_barrier
	v_mfma_f32_16x16x32_bf16 v[112:115], v[148:151], v[214:217], v[112:115]
	v_mfma_f32_16x16x32_bf16 v[80:83], v[174:177], v[214:217], v[80:83]
	v_mfma_f32_16x16x32_bf16 v[116:119], v[148:151], v[222:225], v[116:119]
	v_mfma_f32_16x16x32_bf16 v[88:91], v[174:177], v[222:225], v[88:91]
	v_mfma_f32_16x16x32_bf16 v[124:127], v[148:151], v[230:233], v[124:127]
	v_mfma_f32_16x16x32_bf16 v[92:95], v[174:177], v[230:233], v[92:95]
	v_mfma_f32_16x16x32_bf16 v[120:123], v[148:151], v[238:241], v[120:123]
	v_mfma_f32_16x16x32_bf16 v[84:87], v[174:177], v[238:241], v[84:87]
	v_mfma_f32_16x16x32_bf16 v[112:115], v[170:173], v[218:221], v[112:115]
	v_mfma_f32_16x16x32_bf16 v[80:83], v[178:181], v[218:221], v[80:83]
	v_mfma_f32_16x16x32_bf16 v[116:119], v[170:173], v[226:229], v[116:119]
	v_mfma_f32_16x16x32_bf16 v[88:91], v[178:181], v[226:229], v[88:91]
	v_mfma_f32_16x16x32_bf16 v[124:127], v[170:173], v[234:237], v[124:127]
	v_mfma_f32_16x16x32_bf16 v[92:95], v[178:181], v[234:237], v[92:95]
	v_mfma_f32_16x16x32_bf16 v[120:123], v[170:173], v[242:245], v[120:123]
	v_mfma_f32_16x16x32_bf16 v[84:87], v[178:181], v[242:245], v[84:87]
	s_setprio 0
	s_setprio 1
	v_mfma_f32_16x16x32_bf16 v[108:111], v[182:185], v[214:217], v[108:111]
	v_mfma_f32_16x16x32_bf16 v[76:79], v[202:205], v[214:217], v[76:79]
	v_mfma_f32_16x16x32_bf16 v[104:107], v[182:185], v[222:225], v[104:107]
	v_mfma_f32_16x16x32_bf16 v[72:75], v[202:205], v[222:225], v[72:75]
	v_mfma_f32_16x16x32_bf16 v[100:103], v[182:185], v[230:233], v[100:103]
	v_mfma_f32_16x16x32_bf16 v[68:71], v[202:205], v[230:233], v[68:71]
	v_mfma_f32_16x16x32_bf16 v[96:99], v[182:185], v[238:241], v[96:99]
	v_mfma_f32_16x16x32_bf16 v[64:67], v[202:205], v[238:241], v[64:67]
	v_mfma_f32_16x16x32_bf16 v[108:111], v[186:189], v[218:221], v[108:111]
	v_mfma_f32_16x16x32_bf16 v[76:79], v[206:209], v[218:221], v[76:79]
	v_mfma_f32_16x16x32_bf16 v[104:107], v[186:189], v[226:229], v[104:107]
	v_mfma_f32_16x16x32_bf16 v[72:75], v[206:209], v[226:229], v[72:75]
	v_mfma_f32_16x16x32_bf16 v[100:103], v[186:189], v[234:237], v[100:103]
	v_mfma_f32_16x16x32_bf16 v[68:71], v[206:209], v[234:237], v[68:71]
	v_mfma_f32_16x16x32_bf16 v[96:99], v[186:189], v[242:245], v[96:99]
	v_mfma_f32_16x16x32_bf16 v[64:67], v[206:209], v[242:245], v[64:67]
	s_setprio 0
	s_barrier
	s_add_i32 s16, s94, s63
	v_lshl_add_u64 v[134:135], s[8:9], 0, v[154:155]
	s_mov_b32 m0, s16
	ds_read_b128 v[214:217], v199 offset:16384
	ds_read_b128 v[218:221], v199 offset:17408
	ds_read_b128 v[222:225], v199 offset:18432
	ds_read_b128 v[226:229], v199 offset:19456
	ds_read_b128 v[230:233], v199 offset:20480
	ds_read_b128 v[234:237], v199 offset:21504
	ds_read_b128 v[238:241], v199 offset:22528
	ds_read_b128 v[242:245], v199 offset:23552
	global_load_lds_dwordx4 v[134:135], off
	s_add_i32 m0, s16, 0x2000
	s_add_u32 s16, s8, 0x80000
	v_lshl_add_u64 v[190:191], s[8:9], 0, v[158:159]
	s_addc_u32 s17, s9, 0
	s_add_i32 s18, s95, s63
	global_load_lds_dwordx4 v[190:191], off
	v_lshl_add_u64 v[210:211], s[16:17], 0, v[154:155]
	s_mov_b32 m0, s18
	v_lshl_add_u64 v[246:247], s[10:11], 0, v[156:157]
	global_load_lds_dwordx4 v[210:211], off
	v_lshl_add_u64 v[210:211], s[16:17], 0, v[158:159]
	s_add_i32 m0, s18, 0x2000
	s_nop 0
	global_load_lds_dwordx4 v[210:211], off
	v_lshl_add_u64 v[210:211], s[10:11], 0, v[152:153]
	s_mov_b32 m0, s72
	s_nop 0
	global_load_lds_dwordx4 v[210:211], off
	s_mov_b32 m0, s73
	s_nop 0
	global_load_lds_dwordx4 v[246:247], off
	s_waitcnt vmcnt(8)
	s_waitcnt lgkmcnt(0)
	s_setprio 1
	s_barrier
	v_mfma_f32_16x16x32_bf16 v[48:51], v[148:151], v[214:217], v[48:51]
	v_mfma_f32_16x16x32_bf16 v[16:19], v[174:177], v[214:217], v[16:19]
	v_mfma_f32_16x16x32_bf16 v[52:55], v[148:151], v[222:225], v[52:55]
	v_mfma_f32_16x16x32_bf16 v[24:27], v[174:177], v[222:225], v[24:27]
	v_mfma_f32_16x16x32_bf16 v[60:63], v[148:151], v[230:233], v[60:63]
	v_mfma_f32_16x16x32_bf16 v[28:31], v[174:177], v[230:233], v[28:31]
	v_mfma_f32_16x16x32_bf16 v[56:59], v[148:151], v[238:241], v[56:59]
	v_mfma_f32_16x16x32_bf16 v[20:23], v[174:177], v[238:241], v[20:23]
	v_mfma_f32_16x16x32_bf16 v[48:51], v[170:173], v[218:221], v[48:51]
	v_mfma_f32_16x16x32_bf16 v[16:19], v[178:181], v[218:221], v[16:19]
	v_mfma_f32_16x16x32_bf16 v[52:55], v[170:173], v[226:229], v[52:55]
	v_mfma_f32_16x16x32_bf16 v[24:27], v[178:181], v[226:229], v[24:27]
	v_mfma_f32_16x16x32_bf16 v[60:63], v[170:173], v[234:237], v[60:63]
	v_mfma_f32_16x16x32_bf16 v[28:31], v[178:181], v[234:237], v[28:31]
	v_mfma_f32_16x16x32_bf16 v[56:59], v[170:173], v[242:245], v[56:59]
	v_mfma_f32_16x16x32_bf16 v[20:23], v[178:181], v[242:245], v[20:23]
	s_setprio 0
	s_setprio 1
	v_mfma_f32_16x16x32_bf16 v[44:47], v[182:185], v[214:217], v[44:47]
	v_mfma_f32_16x16x32_bf16 v[12:15], v[202:205], v[214:217], v[12:15]
	v_mfma_f32_16x16x32_bf16 v[40:43], v[182:185], v[222:225], v[40:43]
	v_mfma_f32_16x16x32_bf16 v[8:11], v[202:205], v[222:225], v[8:11]
	v_mfma_f32_16x16x32_bf16 v[36:39], v[182:185], v[230:233], v[36:39]
	v_mfma_f32_16x16x32_bf16 v[4:7], v[202:205], v[230:233], v[4:7]
	v_mfma_f32_16x16x32_bf16 v[32:35], v[182:185], v[238:241], v[32:35]
	v_mfma_f32_16x16x32_bf16 v[0:3], v[202:205], v[238:241], v[0:3]
	v_mfma_f32_16x16x32_bf16 v[44:47], v[186:189], v[218:221], v[44:47]
	v_mfma_f32_16x16x32_bf16 v[12:15], v[206:209], v[218:221], v[12:15]
	v_mfma_f32_16x16x32_bf16 v[40:43], v[186:189], v[226:229], v[40:43]
	v_mfma_f32_16x16x32_bf16 v[8:11], v[206:209], v[226:229], v[8:11]
	v_mfma_f32_16x16x32_bf16 v[36:39], v[186:189], v[234:237], v[36:39]
	v_mfma_f32_16x16x32_bf16 v[4:7], v[206:209], v[234:237], v[4:7]
	v_mfma_f32_16x16x32_bf16 v[32:35], v[186:189], v[242:245], v[32:35]
	v_mfma_f32_16x16x32_bf16 v[0:3], v[206:209], v[242:245], v[0:3]
	s_setprio 0
	s_barrier
	s_add_i32 s16, 0, 0x18000
	s_add_i32 s17, 0, 0x1c000
	v_add_u32_e32 v178, s16, v196
	v_add_u32_e32 v201, s17, v196
	ds_read_b128 v[148:151], v178
	ds_read_b128 v[170:173], v178 offset:1024
	ds_read_b128 v[174:177], v178 offset:2048
	ds_read_b128 v[178:181], v178 offset:3072
	ds_read_b128 v[182:185], v201
	ds_read_b128 v[186:189], v201 offset:1024
	ds_read_b128 v[202:205], v201 offset:2048
	ds_read_b128 v[206:209], v201 offset:3072
	s_add_u32 s10, s10, 0x80000
	s_addc_u32 s11, s11, 0
	s_mov_b32 m0, s74
	v_lshl_add_u64 v[248:249], s[10:11], 0, v[152:153]
	ds_read_b128 v[214:217], v199 offset:32768
	ds_read_b128 v[218:221], v199 offset:33792
	ds_read_b128 v[222:225], v199 offset:34816
	ds_read_b128 v[226:229], v199 offset:35840
	ds_read_b128 v[230:233], v199 offset:36864
	ds_read_b128 v[234:237], v199 offset:37888
	ds_read_b128 v[238:241], v199 offset:38912
	ds_read_b128 v[242:245], v199 offset:39936
	global_load_lds_dwordx4 v[248:249], off
	v_lshl_add_u64 v[248:249], s[10:11], 0, v[156:157]
	s_mov_b32 m0, s75
	s_nop 0
	global_load_lds_dwordx4 v[248:249], off
	s_waitcnt vmcnt(8)
	s_waitcnt lgkmcnt(0)
	s_setprio 1
	s_barrier
	v_mfma_f32_16x16x32_bf16 v[112:115], v[148:151], v[214:217], v[112:115]
	v_mfma_f32_16x16x32_bf16 v[80:83], v[174:177], v[214:217], v[80:83]
	v_mfma_f32_16x16x32_bf16 v[116:119], v[148:151], v[222:225], v[116:119]
	v_mfma_f32_16x16x32_bf16 v[88:91], v[174:177], v[222:225], v[88:91]
	v_mfma_f32_16x16x32_bf16 v[124:127], v[148:151], v[230:233], v[124:127]
	v_mfma_f32_16x16x32_bf16 v[92:95], v[174:177], v[230:233], v[92:95]
	v_mfma_f32_16x16x32_bf16 v[120:123], v[148:151], v[238:241], v[120:123]
	v_mfma_f32_16x16x32_bf16 v[84:87], v[174:177], v[238:241], v[84:87]
	v_mfma_f32_16x16x32_bf16 v[112:115], v[170:173], v[218:221], v[112:115]
	v_mfma_f32_16x16x32_bf16 v[80:83], v[178:181], v[218:221], v[80:83]
	v_mfma_f32_16x16x32_bf16 v[116:119], v[170:173], v[226:229], v[116:119]
	v_mfma_f32_16x16x32_bf16 v[88:91], v[178:181], v[226:229], v[88:91]
	v_mfma_f32_16x16x32_bf16 v[124:127], v[170:173], v[234:237], v[124:127]
	v_mfma_f32_16x16x32_bf16 v[92:95], v[178:181], v[234:237], v[92:95]
	v_mfma_f32_16x16x32_bf16 v[120:123], v[170:173], v[242:245], v[120:123]
	v_mfma_f32_16x16x32_bf16 v[84:87], v[178:181], v[242:245], v[84:87]
	s_setprio 0
	s_setprio 1
	v_mfma_f32_16x16x32_bf16 v[108:111], v[182:185], v[214:217], v[108:111]
	v_mfma_f32_16x16x32_bf16 v[76:79], v[202:205], v[214:217], v[76:79]
	v_mfma_f32_16x16x32_bf16 v[104:107], v[182:185], v[222:225], v[104:107]
	v_mfma_f32_16x16x32_bf16 v[72:75], v[202:205], v[222:225], v[72:75]
	v_mfma_f32_16x16x32_bf16 v[100:103], v[182:185], v[230:233], v[100:103]
	v_mfma_f32_16x16x32_bf16 v[68:71], v[202:205], v[230:233], v[68:71]
	v_mfma_f32_16x16x32_bf16 v[96:99], v[182:185], v[238:241], v[96:99]
	v_mfma_f32_16x16x32_bf16 v[64:67], v[202:205], v[238:241], v[64:67]
	v_mfma_f32_16x16x32_bf16 v[108:111], v[186:189], v[218:221], v[108:111]
	v_mfma_f32_16x16x32_bf16 v[76:79], v[206:209], v[218:221], v[76:79]
	v_mfma_f32_16x16x32_bf16 v[104:107], v[186:189], v[226:229], v[104:107]
	v_mfma_f32_16x16x32_bf16 v[72:75], v[206:209], v[226:229], v[72:75]
	v_mfma_f32_16x16x32_bf16 v[100:103], v[186:189], v[234:237], v[100:103]
	v_mfma_f32_16x16x32_bf16 v[68:71], v[206:209], v[234:237], v[68:71]
	v_mfma_f32_16x16x32_bf16 v[96:99], v[186:189], v[242:245], v[96:99]
	v_mfma_f32_16x16x32_bf16 v[64:67], v[206:209], v[242:245], v[64:67]
	s_setprio 0
	s_barrier
	s_add_i32 s10, s16, s63
	v_lshl_add_u64 v[134:135], v[134:135], 0, s[40:41]
	s_mov_b32 m0, s10
	ds_read_b128 v[214:217], v199 offset:49152
	ds_read_b128 v[218:221], v199 offset:50176
	ds_read_b128 v[222:225], v199 offset:51200
	ds_read_b128 v[226:229], v199 offset:52224
	ds_read_b128 v[230:233], v199 offset:53248
	ds_read_b128 v[234:237], v199 offset:54272
	ds_read_b128 v[238:241], v199 offset:55296
	ds_read_b128 v[242:245], v199 offset:56320
	global_load_lds_dwordx4 v[134:135], off
	s_add_i32 m0, s10, 0x2000
	s_add_u32 s8, s8, 0x80080
	v_lshl_add_u64 v[134:135], v[190:191], 0, s[40:41]
	s_addc_u32 s9, s9, 0
	s_add_i32 s10, s17, s63
	global_load_lds_dwordx4 v[134:135], off
	v_lshl_add_u64 v[134:135], s[8:9], 0, v[154:155]
	s_mov_b32 m0, s10
	s_nop 0
	global_load_lds_dwordx4 v[134:135], off
	v_lshl_add_u64 v[134:135], s[8:9], 0, v[158:159]
	s_add_i32 m0, s10, 0x2000
	s_nop 0
	global_load_lds_dwordx4 v[134:135], off
	v_lshl_add_u64 v[134:135], v[210:211], 0, s[40:41]
	s_mov_b32 m0, s82
	s_nop 0
	global_load_lds_dwordx4 v[134:135], off
	v_lshl_add_u64 v[134:135], v[246:247], 0, s[40:41]
	s_mov_b32 m0, s83
	s_nop 0
	global_load_lds_dwordx4 v[134:135], off
	s_waitcnt vmcnt(8)
	s_waitcnt lgkmcnt(0)
	s_setprio 1
	s_barrier
	v_mfma_f32_16x16x32_bf16 v[48:51], v[148:151], v[214:217], v[48:51]
	v_mfma_f32_16x16x32_bf16 v[16:19], v[174:177], v[214:217], v[16:19]
	v_mfma_f32_16x16x32_bf16 v[52:55], v[148:151], v[222:225], v[52:55]
	v_mfma_f32_16x16x32_bf16 v[24:27], v[174:177], v[222:225], v[24:27]
	v_mfma_f32_16x16x32_bf16 v[60:63], v[148:151], v[230:233], v[60:63]
	v_mfma_f32_16x16x32_bf16 v[28:31], v[174:177], v[230:233], v[28:31]
	v_mfma_f32_16x16x32_bf16 v[56:59], v[148:151], v[238:241], v[56:59]
	v_mfma_f32_16x16x32_bf16 v[20:23], v[174:177], v[238:241], v[20:23]
	v_mfma_f32_16x16x32_bf16 v[48:51], v[170:173], v[218:221], v[48:51]
	v_mfma_f32_16x16x32_bf16 v[16:19], v[178:181], v[218:221], v[16:19]
	v_mfma_f32_16x16x32_bf16 v[52:55], v[170:173], v[226:229], v[52:55]
	v_mfma_f32_16x16x32_bf16 v[24:27], v[178:181], v[226:229], v[24:27]
	v_mfma_f32_16x16x32_bf16 v[60:63], v[170:173], v[234:237], v[60:63]
	v_mfma_f32_16x16x32_bf16 v[28:31], v[178:181], v[234:237], v[28:31]
	v_mfma_f32_16x16x32_bf16 v[56:59], v[170:173], v[242:245], v[56:59]
	v_mfma_f32_16x16x32_bf16 v[20:23], v[178:181], v[242:245], v[20:23]
	s_setprio 0
	s_setprio 1
	v_mfma_f32_16x16x32_bf16 v[44:47], v[182:185], v[214:217], v[44:47]
	v_mfma_f32_16x16x32_bf16 v[12:15], v[202:205], v[214:217], v[12:15]
	v_mfma_f32_16x16x32_bf16 v[40:43], v[182:185], v[222:225], v[40:43]
	v_mfma_f32_16x16x32_bf16 v[8:11], v[202:205], v[222:225], v[8:11]
	v_mfma_f32_16x16x32_bf16 v[36:39], v[182:185], v[230:233], v[36:39]
	v_mfma_f32_16x16x32_bf16 v[4:7], v[202:205], v[230:233], v[4:7]
	v_mfma_f32_16x16x32_bf16 v[32:35], v[182:185], v[238:241], v[32:35]
	v_mfma_f32_16x16x32_bf16 v[0:3], v[202:205], v[238:241], v[0:3]
	v_mfma_f32_16x16x32_bf16 v[44:47], v[186:189], v[218:221], v[44:47]
	v_mfma_f32_16x16x32_bf16 v[12:15], v[206:209], v[218:221], v[12:15]
	v_mfma_f32_16x16x32_bf16 v[40:43], v[186:189], v[226:229], v[40:43]
	v_mfma_f32_16x16x32_bf16 v[8:11], v[206:209], v[226:229], v[8:11]
	v_mfma_f32_16x16x32_bf16 v[36:39], v[186:189], v[234:237], v[36:39]
	v_mfma_f32_16x16x32_bf16 v[4:7], v[206:209], v[234:237], v[4:7]
	v_mfma_f32_16x16x32_bf16 v[32:35], v[186:189], v[242:245], v[32:35]
	v_mfma_f32_16x16x32_bf16 v[0:3], v[206:209], v[242:245], v[0:3]
	s_setprio 0
	s_barrier
	s_add_i32 s15, s15, 2
	s_add_u32 s6, s6, 0x100
	s_addc_u32 s7, s7, 0
	s_add_u32 s12, s12, 0x100
	s_addc_u32 s13, s13, 0
	s_cmp_gt_u32 s15, 29
	s_cbranch_scc0 .LBB0_636
	s_and_b64 vcc, exec, s[42:43]
	s_cbranch_vccz .LBB0_639
	s_barrier

.LBB0_843:
	ds_read_b128 v[128:131], v184
	ds_read_b128 v[132:135], v184 offset:1024
	ds_read_b128 v[136:139], v184 offset:2048
	ds_read_b128 v[140:143], v184 offset:3072
	ds_read_b128 v[144:147], v185
	ds_read_b128 v[148:151], v185 offset:1024
	ds_read_b128 v[168:171], v185 offset:2048
	ds_read_b128 v[172:175], v185 offset:3072
	s_add_u32 s34, s30, 0x100
	s_addc_u32 s35, s31, 0
	s_cmpk_eq_i32 s59, 0x52
	s_cselect_b32 s39, s7, s35
	s_cselect_b32 s38, s6, s34
	s_cselect_b32 s37, s27, s58
	s_cselect_b32 s36, s26, s3
	v_lshl_add_u64 v[218:219], s[30:31], 0, v[160:161]
	s_add_i32 m0, s45, 0xc000
	ds_read_b128 v[176:179], v186
	ds_read_b128 v[188:191], v186 offset:1024
	ds_read_b128 v[192:195], v186 offset:2048
	ds_read_b128 v[196:199], v186 offset:3072
	ds_read_b128 v[200:203], v186 offset:4096
	ds_read_b128 v[204:207], v186 offset:5120
	ds_read_b128 v[208:211], v186 offset:6144
	ds_read_b128 v[214:217], v186 offset:7168
	global_load_lds_dwordx4 v[218:219], off
	v_lshl_add_u64 v[218:219], s[30:31], 0, v[162:163]
	s_add_i32 m0, s45, 0xe000
	s_nop 0
	global_load_lds_dwordx4 v[218:219], off
	s_waitcnt vmcnt(8)
	s_waitcnt lgkmcnt(0)
	s_setprio 1
	s_barrier
	v_mfma_f32_16x16x32_bf16 v[124:127], v[128:131], v[176:179], v[124:127]
	v_mfma_f32_16x16x32_bf16 v[120:123], v[136:139], v[176:179], v[120:123]
	v_mfma_f32_16x16x32_bf16 v[108:111], v[128:131], v[192:195], v[108:111]
	v_mfma_f32_16x16x32_bf16 v[104:107], v[136:139], v[192:195], v[104:107]
	v_mfma_f32_16x16x32_bf16 v[92:95], v[128:131], v[200:203], v[92:95]
	v_mfma_f32_16x16x32_bf16 v[88:91], v[136:139], v[200:203], v[88:91]
	v_mfma_f32_16x16x32_bf16 v[76:79], v[128:131], v[208:211], v[76:79]
	v_mfma_f32_16x16x32_bf16 v[72:75], v[136:139], v[208:211], v[72:75]
	v_mfma_f32_16x16x32_bf16 v[124:127], v[132:135], v[188:191], v[124:127]
	v_mfma_f32_16x16x32_bf16 v[120:123], v[140:143], v[188:191], v[120:123]
	v_mfma_f32_16x16x32_bf16 v[108:111], v[132:135], v[196:199], v[108:111]
	v_mfma_f32_16x16x32_bf16 v[104:107], v[140:143], v[196:199], v[104:107]
	v_mfma_f32_16x16x32_bf16 v[92:95], v[132:135], v[204:207], v[92:95]
	v_mfma_f32_16x16x32_bf16 v[88:91], v[140:143], v[204:207], v[88:91]
	v_mfma_f32_16x16x32_bf16 v[76:79], v[132:135], v[214:217], v[76:79]
	v_mfma_f32_16x16x32_bf16 v[72:75], v[140:143], v[214:217], v[72:75]
	s_setprio 0
	s_setprio 1
	v_mfma_f32_16x16x32_bf16 v[116:119], v[144:147], v[176:179], v[116:119]
	v_mfma_f32_16x16x32_bf16 v[112:115], v[168:171], v[176:179], v[112:115]
	v_mfma_f32_16x16x32_bf16 v[100:103], v[144:147], v[192:195], v[100:103]
	v_mfma_f32_16x16x32_bf16 v[96:99], v[168:171], v[192:195], v[96:99]
	v_mfma_f32_16x16x32_bf16 v[84:87], v[144:147], v[200:203], v[84:87]
	v_mfma_f32_16x16x32_bf16 v[80:83], v[168:171], v[200:203], v[80:83]
	v_mfma_f32_16x16x32_bf16 v[68:71], v[144:147], v[208:211], v[68:71]
	v_mfma_f32_16x16x32_bf16 v[64:67], v[168:171], v[208:211], v[64:67]
	v_mfma_f32_16x16x32_bf16 v[116:119], v[148:151], v[188:191], v[116:119]
	v_mfma_f32_16x16x32_bf16 v[112:115], v[172:175], v[188:191], v[112:115]
	v_mfma_f32_16x16x32_bf16 v[100:103], v[148:151], v[196:199], v[100:103]
	v_mfma_f32_16x16x32_bf16 v[96:99], v[172:175], v[196:199], v[96:99]
	v_mfma_f32_16x16x32_bf16 v[84:87], v[148:151], v[204:207], v[84:87]
	v_mfma_f32_16x16x32_bf16 v[80:83], v[172:175], v[204:207], v[80:83]
	v_mfma_f32_16x16x32_bf16 v[68:71], v[148:151], v[214:217], v[68:71]
	v_mfma_f32_16x16x32_bf16 v[64:67], v[172:175], v[214:217], v[64:67]
	s_setprio 0
	s_barrier
	s_add_i32 s30, s54, s44
	v_lshl_add_u64 v[218:219], s[36:37], 0, v[154:155]
	s_mov_b32 m0, s30
	ds_read_b128 v[176:179], v186 offset:16384
	ds_read_b128 v[188:191], v186 offset:17408
	ds_read_b128 v[192:195], v186 offset:18432
	ds_read_b128 v[196:199], v186 offset:19456
	ds_read_b128 v[200:203], v186 offset:20480
	ds_read_b128 v[204:207], v186 offset:21504
	ds_read_b128 v[208:211], v186 offset:22528
	ds_read_b128 v[214:217], v186 offset:23552
	global_load_lds_dwordx4 v[218:219], off
	s_add_i32 m0, s30, 0x2000
	s_add_u32 s30, s36, 0x158000
	v_lshl_add_u64 v[220:221], s[36:37], 0, v[158:159]
	s_addc_u32 s31, s37, 0
	s_add_i32 s60, s55, s44
	global_load_lds_dwordx4 v[220:221], off
	v_lshl_add_u64 v[222:223], s[30:31], 0, v[154:155]
	s_mov_b32 m0, s60
	v_lshl_add_u64 v[224:225], s[38:39], 0, v[156:157]
	global_load_lds_dwordx4 v[222:223], off
	v_lshl_add_u64 v[222:223], s[30:31], 0, v[158:159]
	s_add_i32 m0, s60, 0x2000
	s_nop 0
	global_load_lds_dwordx4 v[222:223], off
	v_lshl_add_u64 v[222:223], s[38:39], 0, v[152:153]
	s_mov_b32 m0, s45
	s_nop 0
	global_load_lds_dwordx4 v[222:223], off
	s_mov_b32 m0, s46
	s_nop 0
	global_load_lds_dwordx4 v[224:225], off
	s_waitcnt vmcnt(8)
	s_waitcnt lgkmcnt(0)
	s_setprio 1
	s_barrier
	v_mfma_f32_16x16x32_bf16 v[60:63], v[128:131], v[176:179], v[60:63]
	v_mfma_f32_16x16x32_bf16 v[56:59], v[136:139], v[176:179], v[56:59]
	v_mfma_f32_16x16x32_bf16 v[44:47], v[128:131], v[192:195], v[44:47]
	v_mfma_f32_16x16x32_bf16 v[40:43], v[136:139], v[192:195], v[40:43]
	v_mfma_f32_16x16x32_bf16 v[28:31], v[128:131], v[200:203], v[28:31]
	v_mfma_f32_16x16x32_bf16 v[24:27], v[136:139], v[200:203], v[24:27]
	v_mfma_f32_16x16x32_bf16 v[12:15], v[128:131], v[208:211], v[12:15]
	v_mfma_f32_16x16x32_bf16 v[8:11], v[136:139], v[208:211], v[8:11]
	v_mfma_f32_16x16x32_bf16 v[60:63], v[132:135], v[188:191], v[60:63]
	v_mfma_f32_16x16x32_bf16 v[56:59], v[140:143], v[188:191], v[56:59]
	v_mfma_f32_16x16x32_bf16 v[44:47], v[132:135], v[196:199], v[44:47]
	v_mfma_f32_16x16x32_bf16 v[40:43], v[140:143], v[196:199], v[40:43]
	v_mfma_f32_16x16x32_bf16 v[28:31], v[132:135], v[204:207], v[28:31]
	v_mfma_f32_16x16x32_bf16 v[24:27], v[140:143], v[204:207], v[24:27]
	v_mfma_f32_16x16x32_bf16 v[12:15], v[132:135], v[214:217], v[12:15]
	v_mfma_f32_16x16x32_bf16 v[8:11], v[140:143], v[214:217], v[8:11]
	s_setprio 0
	s_setprio 1
	v_mfma_f32_16x16x32_bf16 v[52:55], v[144:147], v[176:179], v[52:55]
	v_mfma_f32_16x16x32_bf16 v[48:51], v[168:171], v[176:179], v[48:51]
	v_mfma_f32_16x16x32_bf16 v[36:39], v[144:147], v[192:195], v[36:39]
	v_mfma_f32_16x16x32_bf16 v[32:35], v[168:171], v[192:195], v[32:35]
	v_mfma_f32_16x16x32_bf16 v[20:23], v[144:147], v[200:203], v[20:23]
	v_mfma_f32_16x16x32_bf16 v[16:19], v[168:171], v[200:203], v[16:19]
	v_mfma_f32_16x16x32_bf16 v[4:7], v[144:147], v[208:211], v[4:7]
	v_mfma_f32_16x16x32_bf16 v[0:3], v[168:171], v[208:211], v[0:3]
	v_mfma_f32_16x16x32_bf16 v[52:55], v[148:151], v[188:191], v[52:55]
	v_mfma_f32_16x16x32_bf16 v[48:51], v[172:175], v[188:191], v[48:51]
	v_mfma_f32_16x16x32_bf16 v[36:39], v[148:151], v[196:199], v[36:39]
	v_mfma_f32_16x16x32_bf16 v[32:35], v[172:175], v[196:199], v[32:35]
	v_mfma_f32_16x16x32_bf16 v[20:23], v[148:151], v[204:207], v[20:23]
	v_mfma_f32_16x16x32_bf16 v[16:19], v[172:175], v[204:207], v[16:19]
	v_mfma_f32_16x16x32_bf16 v[4:7], v[148:151], v[214:217], v[4:7]
	v_mfma_f32_16x16x32_bf16 v[0:3], v[172:175], v[214:217], v[0:3]
	s_setprio 0
	s_barrier
	s_add_i32 s60, 0, 0x18000
	s_add_i32 s61, 0, 0x1c000
	v_add_u32_e32 v140, s60, v182
	v_add_u32_e32 v172, s61, v182
	ds_read_b128 v[128:131], v140
	ds_read_b128 v[132:135], v140 offset:1024
	ds_read_b128 v[136:139], v140 offset:2048
	ds_read_b128 v[140:143], v140 offset:3072
	ds_read_b128 v[144:147], v172
	ds_read_b128 v[148:151], v172 offset:1024
	ds_read_b128 v[168:171], v172 offset:2048
	ds_read_b128 v[172:175], v172 offset:3072
	s_add_u32 s30, s38, 0x158000
	s_addc_u32 s31, s39, 0
	s_mov_b32 m0, s47
	v_lshl_add_u64 v[226:227], s[30:31], 0, v[152:153]
	ds_read_b128 v[176:179], v186 offset:32768
	ds_read_b128 v[188:191], v186 offset:33792
	ds_read_b128 v[192:195], v186 offset:34816
	ds_read_b128 v[196:199], v186 offset:35840
	ds_read_b128 v[200:203], v186 offset:36864
	ds_read_b128 v[204:207], v186 offset:37888
	ds_read_b128 v[208:211], v186 offset:38912
	ds_read_b128 v[214:217], v186 offset:39936
	global_load_lds_dwordx4 v[226:227], off
	v_lshl_add_u64 v[226:227], s[30:31], 0, v[156:157]
	s_mov_b32 m0, s48
	s_nop 0
	global_load_lds_dwordx4 v[226:227], off
	s_waitcnt vmcnt(8)
	s_waitcnt lgkmcnt(0)
	s_setprio 1
	s_barrier
	v_mfma_f32_16x16x32_bf16 v[124:127], v[128:131], v[176:179], v[124:127]
	v_mfma_f32_16x16x32_bf16 v[120:123], v[136:139], v[176:179], v[120:123]
	v_mfma_f32_16x16x32_bf16 v[108:111], v[128:131], v[192:195], v[108:111]
	v_mfma_f32_16x16x32_bf16 v[104:107], v[136:139], v[192:195], v[104:107]
	v_mfma_f32_16x16x32_bf16 v[92:95], v[128:131], v[200:203], v[92:95]
	v_mfma_f32_16x16x32_bf16 v[88:91], v[136:139], v[200:203], v[88:91]
	v_mfma_f32_16x16x32_bf16 v[76:79], v[128:131], v[208:211], v[76:79]
	v_mfma_f32_16x16x32_bf16 v[72:75], v[136:139], v[208:211], v[72:75]
	v_mfma_f32_16x16x32_bf16 v[124:127], v[132:135], v[188:191], v[124:127]
	v_mfma_f32_16x16x32_bf16 v[120:123], v[140:143], v[188:191], v[120:123]
	v_mfma_f32_16x16x32_bf16 v[108:111], v[132:135], v[196:199], v[108:111]
	v_mfma_f32_16x16x32_bf16 v[104:107], v[140:143], v[196:199], v[104:107]
	v_mfma_f32_16x16x32_bf16 v[92:95], v[132:135], v[204:207], v[92:95]
	v_mfma_f32_16x16x32_bf16 v[88:91], v[140:143], v[204:207], v[88:91]
	v_mfma_f32_16x16x32_bf16 v[76:79], v[132:135], v[214:217], v[76:79]
	v_mfma_f32_16x16x32_bf16 v[72:75], v[140:143], v[214:217], v[72:75]
	s_setprio 0
	s_setprio 1
	v_mfma_f32_16x16x32_bf16 v[116:119], v[144:147], v[176:179], v[116:119]
	v_mfma_f32_16x16x32_bf16 v[112:115], v[168:171], v[176:179], v[112:115]
	v_mfma_f32_16x16x32_bf16 v[100:103], v[144:147], v[192:195], v[100:103]
	v_mfma_f32_16x16x32_bf16 v[96:99], v[168:171], v[192:195], v[96:99]
	v_mfma_f32_16x16x32_bf16 v[84:87], v[144:147], v[200:203], v[84:87]
	v_mfma_f32_16x16x32_bf16 v[80:83], v[168:171], v[200:203], v[80:83]
	v_mfma_f32_16x16x32_bf16 v[68:71], v[144:147], v[208:211], v[68:71]
	v_mfma_f32_16x16x32_bf16 v[64:67], v[168:171], v[208:211], v[64:67]
	v_mfma_f32_16x16x32_bf16 v[116:119], v[148:151], v[188:191], v[116:119]
	v_mfma_f32_16x16x32_bf16 v[112:115], v[172:175], v[188:191], v[112:115]
	v_mfma_f32_16x16x32_bf16 v[100:103], v[148:151], v[196:199], v[100:103]
	v_mfma_f32_16x16x32_bf16 v[96:99], v[172:175], v[196:199], v[96:99]
	v_mfma_f32_16x16x32_bf16 v[84:87], v[148:151], v[204:207], v[84:87]
	v_mfma_f32_16x16x32_bf16 v[80:83], v[172:175], v[204:207], v[80:83]
	v_mfma_f32_16x16x32_bf16 v[68:71], v[148:151], v[214:217], v[68:71]
	v_mfma_f32_16x16x32_bf16 v[64:67], v[172:175], v[214:217], v[64:67]
	s_setprio 0
	s_barrier
	s_add_i32 s30, s60, s44
	v_lshl_add_u64 v[218:219], v[218:219], 0, s[20:21]
	s_mov_b32 m0, s30
	ds_read_b128 v[176:179], v186 offset:49152
	ds_read_b128 v[188:191], v186 offset:50176
	ds_read_b128 v[192:195], v186 offset:51200
	ds_read_b128 v[196:199], v186 offset:52224
	ds_read_b128 v[200:203], v186 offset:53248
	ds_read_b128 v[204:207], v186 offset:54272
	ds_read_b128 v[208:211], v186 offset:55296
	ds_read_b128 v[214:217], v186 offset:56320
	global_load_lds_dwordx4 v[218:219], off
	s_add_i32 m0, s30, 0x2000
	s_add_u32 s30, s36, 0x158080
	v_lshl_add_u64 v[218:219], v[220:221], 0, s[20:21]
	s_addc_u32 s31, s37, 0
	s_add_i32 s36, s61, s44
	global_load_lds_dwordx4 v[218:219], off
	v_lshl_add_u64 v[218:219], s[30:31], 0, v[154:155]
	s_mov_b32 m0, s36
	s_nop 0
	global_load_lds_dwordx4 v[218:219], off
	v_lshl_add_u64 v[218:219], s[30:31], 0, v[158:159]
	s_add_i32 m0, s36, 0x2000
	s_nop 0
	global_load_lds_dwordx4 v[218:219], off
	v_lshl_add_u64 v[218:219], v[222:223], 0, s[20:21]
	s_mov_b32 m0, s51
	s_nop 0
	global_load_lds_dwordx4 v[218:219], off
	v_lshl_add_u64 v[218:219], v[224:225], 0, s[20:21]
	s_mov_b32 m0, s52
	s_nop 0
	global_load_lds_dwordx4 v[218:219], off
	s_waitcnt vmcnt(8)
	s_waitcnt lgkmcnt(0)
	s_setprio 1
	s_barrier
	v_mfma_f32_16x16x32_bf16 v[60:63], v[128:131], v[176:179], v[60:63]
	v_mfma_f32_16x16x32_bf16 v[56:59], v[136:139], v[176:179], v[56:59]
	v_mfma_f32_16x16x32_bf16 v[44:47], v[128:131], v[192:195], v[44:47]
	v_mfma_f32_16x16x32_bf16 v[40:43], v[136:139], v[192:195], v[40:43]
	v_mfma_f32_16x16x32_bf16 v[28:31], v[128:131], v[200:203], v[28:31]
	v_mfma_f32_16x16x32_bf16 v[24:27], v[136:139], v[200:203], v[24:27]
	v_mfma_f32_16x16x32_bf16 v[12:15], v[128:131], v[208:211], v[12:15]
	v_mfma_f32_16x16x32_bf16 v[8:11], v[136:139], v[208:211], v[8:11]
	v_mfma_f32_16x16x32_bf16 v[60:63], v[132:135], v[188:191], v[60:63]
	v_mfma_f32_16x16x32_bf16 v[56:59], v[140:143], v[188:191], v[56:59]
	v_mfma_f32_16x16x32_bf16 v[44:47], v[132:135], v[196:199], v[44:47]
	v_mfma_f32_16x16x32_bf16 v[40:43], v[140:143], v[196:199], v[40:43]
	v_mfma_f32_16x16x32_bf16 v[28:31], v[132:135], v[204:207], v[28:31]
	v_mfma_f32_16x16x32_bf16 v[24:27], v[140:143], v[204:207], v[24:27]
	v_mfma_f32_16x16x32_bf16 v[12:15], v[132:135], v[214:217], v[12:15]
	v_mfma_f32_16x16x32_bf16 v[8:11], v[140:143], v[214:217], v[8:11]
	s_setprio 0
	s_setprio 1
	v_mfma_f32_16x16x32_bf16 v[52:55], v[144:147], v[176:179], v[52:55]
	v_mfma_f32_16x16x32_bf16 v[48:51], v[168:171], v[176:179], v[48:51]
	v_mfma_f32_16x16x32_bf16 v[36:39], v[144:147], v[192:195], v[36:39]
	v_mfma_f32_16x16x32_bf16 v[32:35], v[168:171], v[192:195], v[32:35]
	v_mfma_f32_16x16x32_bf16 v[20:23], v[144:147], v[200:203], v[20:23]
	v_mfma_f32_16x16x32_bf16 v[16:19], v[168:171], v[200:203], v[16:19]
	v_mfma_f32_16x16x32_bf16 v[4:7], v[144:147], v[208:211], v[4:7]
	v_mfma_f32_16x16x32_bf16 v[0:3], v[168:171], v[208:211], v[0:3]
	v_mfma_f32_16x16x32_bf16 v[52:55], v[148:151], v[188:191], v[52:55]
	v_mfma_f32_16x16x32_bf16 v[48:51], v[172:175], v[188:191], v[48:51]
	v_mfma_f32_16x16x32_bf16 v[36:39], v[148:151], v[196:199], v[36:39]
	v_mfma_f32_16x16x32_bf16 v[32:35], v[172:175], v[196:199], v[32:35]
	v_mfma_f32_16x16x32_bf16 v[20:23], v[148:151], v[204:207], v[20:23]
	v_mfma_f32_16x16x32_bf16 v[16:19], v[172:175], v[204:207], v[16:19]
	v_mfma_f32_16x16x32_bf16 v[4:7], v[148:151], v[214:217], v[4:7]
	v_mfma_f32_16x16x32_bf16 v[0:3], v[172:175], v[214:217], v[0:3]
	s_setprio 0
	s_barrier
	s_add_i32 s59, s59, 2
	s_add_u32 s3, s3, 0x100
	s_addc_u32 s58, s58, 0
	s_cmpk_gt_u32 s59, 0x53
	s_mov_b64 s[30:31], s[34:35]
	s_cbranch_scc0 .LBB0_843
	s_and_b64 vcc, exec, s[24:25]
	s_cbranch_vccz .LBB0_846
	s_barrier

.LBB0_875:
	s_mov_b32 s1, -2
	s_mov_b64 s[4:5], s[22:23]
	ds_read_b128 v[128:131], v188
	ds_read_b128 v[132:135], v188 offset:1024
	ds_read_b128 v[136:139], v188 offset:2048
	ds_read_b128 v[140:143], v188 offset:3072
	ds_read_b128 v[144:147], v189
	ds_read_b128 v[148:151], v189 offset:1024
	ds_read_b128 v[166:169], v189 offset:2048
	ds_read_b128 v[170:173], v189 offset:3072
	s_add_u32 s40, s38, 0x100
	s_addc_u32 s41, s39, 0
	s_cmpk_eq_i32 s1, 0x52
	s_cselect_b32 s45, s37, s41
	s_cselect_b32 s44, s36, s40
	s_cselect_b32 s43, s17, s5
	s_cselect_b32 s42, s16, s4
	v_lshl_add_u64 v[182:183], s[38:39], 0, v[160:161]
	s_add_i32 m0, s48, 0xc000
	ds_read_b128 v[174:177], v190
	ds_read_b128 v[178:181], v190 offset:1024
	ds_read_b128 v[194:197], v190 offset:2048
	ds_read_b128 v[198:201], v190 offset:3072
	ds_read_b128 v[202:205], v190 offset:4096
	ds_read_b128 v[206:209], v190 offset:5120
	ds_read_b128 v[210:213], v190 offset:6144
	ds_read_b128 v[214:217], v190 offset:7168
	global_load_lds_dwordx4 v[182:183], off
	v_lshl_add_u64 v[182:183], s[38:39], 0, v[162:163]
	s_add_i32 m0, s48, 0xe000
	s_nop 0
	global_load_lds_dwordx4 v[182:183], off
	s_waitcnt vmcnt(8)
	s_waitcnt lgkmcnt(0)
	s_setprio 1
	s_barrier
	v_mfma_f32_16x16x32_bf16 v[124:127], v[128:131], v[174:177], 0
	v_mfma_f32_16x16x32_bf16 v[120:123], v[136:139], v[174:177], 0
	v_mfma_f32_16x16x32_bf16 v[108:111], v[128:131], v[194:197], 0
	v_mfma_f32_16x16x32_bf16 v[104:107], v[136:139], v[194:197], 0
	v_mfma_f32_16x16x32_bf16 v[92:95], v[128:131], v[202:205], 0
	v_mfma_f32_16x16x32_bf16 v[88:91], v[136:139], v[202:205], 0
	v_mfma_f32_16x16x32_bf16 v[76:79], v[128:131], v[210:213], 0
	v_mfma_f32_16x16x32_bf16 v[72:75], v[136:139], v[210:213], 0
	v_mfma_f32_16x16x32_bf16 v[124:127], v[132:135], v[178:181], v[124:127]
	v_mfma_f32_16x16x32_bf16 v[120:123], v[140:143], v[178:181], v[120:123]
	v_mfma_f32_16x16x32_bf16 v[108:111], v[132:135], v[198:201], v[108:111]
	v_mfma_f32_16x16x32_bf16 v[104:107], v[140:143], v[198:201], v[104:107]
	v_mfma_f32_16x16x32_bf16 v[92:95], v[132:135], v[206:209], v[92:95]
	v_mfma_f32_16x16x32_bf16 v[88:91], v[140:143], v[206:209], v[88:91]
	v_mfma_f32_16x16x32_bf16 v[76:79], v[132:135], v[214:217], v[76:79]
	v_mfma_f32_16x16x32_bf16 v[72:75], v[140:143], v[214:217], v[72:75]
	s_setprio 0
	s_setprio 1
	v_mfma_f32_16x16x32_bf16 v[116:119], v[144:147], v[174:177], 0
	v_mfma_f32_16x16x32_bf16 v[112:115], v[166:169], v[174:177], 0
	v_mfma_f32_16x16x32_bf16 v[100:103], v[144:147], v[194:197], 0
	v_mfma_f32_16x16x32_bf16 v[96:99], v[166:169], v[194:197], 0
	v_mfma_f32_16x16x32_bf16 v[84:87], v[144:147], v[202:205], 0
	v_mfma_f32_16x16x32_bf16 v[80:83], v[166:169], v[202:205], 0
	v_mfma_f32_16x16x32_bf16 v[68:71], v[144:147], v[210:213], 0
	v_mfma_f32_16x16x32_bf16 v[64:67], v[166:169], v[210:213], 0
	v_mfma_f32_16x16x32_bf16 v[116:119], v[148:151], v[178:181], v[116:119]
	v_mfma_f32_16x16x32_bf16 v[112:115], v[170:173], v[178:181], v[112:115]
	v_mfma_f32_16x16x32_bf16 v[100:103], v[148:151], v[198:201], v[100:103]
	v_mfma_f32_16x16x32_bf16 v[96:99], v[170:173], v[198:201], v[96:99]
	v_mfma_f32_16x16x32_bf16 v[84:87], v[148:151], v[206:209], v[84:87]
	v_mfma_f32_16x16x32_bf16 v[80:83], v[170:173], v[206:209], v[80:83]
	v_mfma_f32_16x16x32_bf16 v[68:71], v[148:151], v[214:217], v[68:71]
	v_mfma_f32_16x16x32_bf16 v[64:67], v[170:173], v[214:217], v[64:67]
	s_setprio 0
	s_barrier
	s_add_i32 s3, s70, s33
	v_lshl_add_u64 v[182:183], s[42:43], 0, v[154:155]
	s_mov_b32 m0, s3
	ds_read_b128 v[174:177], v190 offset:16384
	ds_read_b128 v[178:181], v190 offset:17408
	ds_read_b128 v[194:197], v190 offset:18432
	ds_read_b128 v[198:201], v190 offset:19456
	ds_read_b128 v[202:205], v190 offset:20480
	ds_read_b128 v[206:209], v190 offset:21504
	ds_read_b128 v[210:213], v190 offset:22528
	ds_read_b128 v[214:217], v190 offset:23552
	global_load_lds_dwordx4 v[182:183], off
	s_add_i32 m0, s3, 0x2000
	s_add_u32 s38, s42, 0x158000
	v_lshl_add_u64 v[218:219], s[42:43], 0, v[158:159]
	s_addc_u32 s39, s43, 0
	s_add_i32 s3, s71, s33
	global_load_lds_dwordx4 v[218:219], off
	v_lshl_add_u64 v[220:221], s[38:39], 0, v[154:155]
	s_mov_b32 m0, s3
	v_lshl_add_u64 v[222:223], s[44:45], 0, v[156:157]
	global_load_lds_dwordx4 v[220:221], off
	v_lshl_add_u64 v[220:221], s[38:39], 0, v[158:159]
	s_add_i32 m0, s3, 0x2000
	s_nop 0
	global_load_lds_dwordx4 v[220:221], off
	v_lshl_add_u64 v[220:221], s[44:45], 0, v[152:153]
	s_mov_b32 m0, s48
	s_nop 0
	global_load_lds_dwordx4 v[220:221], off
	s_mov_b32 m0, s49
	s_nop 0
	global_load_lds_dwordx4 v[222:223], off
	s_waitcnt vmcnt(8)
	s_waitcnt lgkmcnt(0)
	s_setprio 1
	s_barrier
	v_mfma_f32_16x16x32_bf16 v[60:63], v[128:131], v[174:177], 0
	v_mfma_f32_16x16x32_bf16 v[56:59], v[136:139], v[174:177], 0
	v_mfma_f32_16x16x32_bf16 v[44:47], v[128:131], v[194:197], 0
	v_mfma_f32_16x16x32_bf16 v[40:43], v[136:139], v[194:197], 0
	v_mfma_f32_16x16x32_bf16 v[28:31], v[128:131], v[202:205], 0
	v_mfma_f32_16x16x32_bf16 v[24:27], v[136:139], v[202:205], 0
	v_mfma_f32_16x16x32_bf16 v[12:15], v[128:131], v[210:213], 0
	v_mfma_f32_16x16x32_bf16 v[8:11], v[136:139], v[210:213], 0
	v_mfma_f32_16x16x32_bf16 v[60:63], v[132:135], v[178:181], v[60:63]
	v_mfma_f32_16x16x32_bf16 v[56:59], v[140:143], v[178:181], v[56:59]
	v_mfma_f32_16x16x32_bf16 v[44:47], v[132:135], v[198:201], v[44:47]
	v_mfma_f32_16x16x32_bf16 v[40:43], v[140:143], v[198:201], v[40:43]
	v_mfma_f32_16x16x32_bf16 v[28:31], v[132:135], v[206:209], v[28:31]
	v_mfma_f32_16x16x32_bf16 v[24:27], v[140:143], v[206:209], v[24:27]
	v_mfma_f32_16x16x32_bf16 v[12:15], v[132:135], v[214:217], v[12:15]
	v_mfma_f32_16x16x32_bf16 v[8:11], v[140:143], v[214:217], v[8:11]
	s_setprio 0
	s_setprio 1
	v_mfma_f32_16x16x32_bf16 v[52:55], v[144:147], v[174:177], 0
	v_mfma_f32_16x16x32_bf16 v[48:51], v[166:169], v[174:177], 0
	v_mfma_f32_16x16x32_bf16 v[36:39], v[144:147], v[194:197], 0
	v_mfma_f32_16x16x32_bf16 v[32:35], v[166:169], v[194:197], 0
	v_mfma_f32_16x16x32_bf16 v[20:23], v[144:147], v[202:205], 0
	v_mfma_f32_16x16x32_bf16 v[16:19], v[166:169], v[202:205], 0
	v_mfma_f32_16x16x32_bf16 v[4:7], v[144:147], v[210:213], 0
	v_mfma_f32_16x16x32_bf16 v[0:3], v[166:169], v[210:213], 0
	v_mfma_f32_16x16x32_bf16 v[52:55], v[148:151], v[178:181], v[52:55]
	v_mfma_f32_16x16x32_bf16 v[48:51], v[170:173], v[178:181], v[48:51]
	v_mfma_f32_16x16x32_bf16 v[36:39], v[148:151], v[198:201], v[36:39]
	v_mfma_f32_16x16x32_bf16 v[32:35], v[170:173], v[198:201], v[32:35]
	v_mfma_f32_16x16x32_bf16 v[20:23], v[148:151], v[206:209], v[20:23]
	v_mfma_f32_16x16x32_bf16 v[16:19], v[170:173], v[206:209], v[16:19]
	v_mfma_f32_16x16x32_bf16 v[4:7], v[148:151], v[214:217], v[4:7]
	v_mfma_f32_16x16x32_bf16 v[0:3], v[170:173], v[214:217], v[0:3]
	s_setprio 0
	s_barrier
	s_add_i32 s3, 0, 0x18000
	s_add_i32 s73, 0, 0x1c000
	v_add_u32_e32 v140, s3, v187
	v_add_u32_e32 v170, s73, v187
	ds_read_b128 v[128:131], v140
	ds_read_b128 v[132:135], v140 offset:1024
	ds_read_b128 v[136:139], v140 offset:2048
	ds_read_b128 v[140:143], v140 offset:3072
	ds_read_b128 v[144:147], v170
	ds_read_b128 v[148:151], v170 offset:1024
	ds_read_b128 v[166:169], v170 offset:2048
	ds_read_b128 v[170:173], v170 offset:3072
	s_add_u32 s38, s44, 0x158000
	s_addc_u32 s39, s45, 0
	s_mov_b32 m0, s51
	v_lshl_add_u64 v[224:225], s[38:39], 0, v[152:153]
	ds_read_b128 v[174:177], v190 offset:32768
	ds_read_b128 v[178:181], v190 offset:33792
	ds_read_b128 v[194:197], v190 offset:34816
	ds_read_b128 v[198:201], v190 offset:35840
	ds_read_b128 v[202:205], v190 offset:36864
	ds_read_b128 v[206:209], v190 offset:37888
	ds_read_b128 v[210:213], v190 offset:38912
	ds_read_b128 v[214:217], v190 offset:39936
	global_load_lds_dwordx4 v[224:225], off
	v_lshl_add_u64 v[224:225], s[38:39], 0, v[156:157]
	s_mov_b32 m0, s52
	s_nop 0
	global_load_lds_dwordx4 v[224:225], off
	s_waitcnt vmcnt(8)
	s_waitcnt lgkmcnt(0)
	s_setprio 1
	s_barrier
	v_mfma_f32_16x16x32_bf16 v[124:127], v[128:131], v[174:177], v[124:127]
	v_mfma_f32_16x16x32_bf16 v[120:123], v[136:139], v[174:177], v[120:123]
	v_mfma_f32_16x16x32_bf16 v[108:111], v[128:131], v[194:197], v[108:111]
	v_mfma_f32_16x16x32_bf16 v[104:107], v[136:139], v[194:197], v[104:107]
	v_mfma_f32_16x16x32_bf16 v[92:95], v[128:131], v[202:205], v[92:95]
	v_mfma_f32_16x16x32_bf16 v[88:91], v[136:139], v[202:205], v[88:91]
	v_mfma_f32_16x16x32_bf16 v[76:79], v[128:131], v[210:213], v[76:79]
	v_mfma_f32_16x16x32_bf16 v[72:75], v[136:139], v[210:213], v[72:75]
	v_mfma_f32_16x16x32_bf16 v[124:127], v[132:135], v[178:181], v[124:127]
	v_mfma_f32_16x16x32_bf16 v[120:123], v[140:143], v[178:181], v[120:123]
	v_mfma_f32_16x16x32_bf16 v[108:111], v[132:135], v[198:201], v[108:111]
	v_mfma_f32_16x16x32_bf16 v[104:107], v[140:143], v[198:201], v[104:107]
	v_mfma_f32_16x16x32_bf16 v[92:95], v[132:135], v[206:209], v[92:95]
	v_mfma_f32_16x16x32_bf16 v[88:91], v[140:143], v[206:209], v[88:91]
	v_mfma_f32_16x16x32_bf16 v[76:79], v[132:135], v[214:217], v[76:79]
	v_mfma_f32_16x16x32_bf16 v[72:75], v[140:143], v[214:217], v[72:75]
	s_setprio 0
	s_setprio 1
	v_mfma_f32_16x16x32_bf16 v[116:119], v[144:147], v[174:177], v[116:119]
	v_mfma_f32_16x16x32_bf16 v[112:115], v[166:169], v[174:177], v[112:115]
	v_mfma_f32_16x16x32_bf16 v[100:103], v[144:147], v[194:197], v[100:103]
	v_mfma_f32_16x16x32_bf16 v[96:99], v[166:169], v[194:197], v[96:99]
	v_mfma_f32_16x16x32_bf16 v[84:87], v[144:147], v[202:205], v[84:87]
	v_mfma_f32_16x16x32_bf16 v[80:83], v[166:169], v[202:205], v[80:83]
	v_mfma_f32_16x16x32_bf16 v[68:71], v[144:147], v[210:213], v[68:71]
	v_mfma_f32_16x16x32_bf16 v[64:67], v[166:169], v[210:213], v[64:67]
	v_mfma_f32_16x16x32_bf16 v[116:119], v[148:151], v[178:181], v[116:119]
	v_mfma_f32_16x16x32_bf16 v[112:115], v[170:173], v[178:181], v[112:115]
	v_mfma_f32_16x16x32_bf16 v[100:103], v[148:151], v[198:201], v[100:103]
	v_mfma_f32_16x16x32_bf16 v[96:99], v[170:173], v[198:201], v[96:99]
	v_mfma_f32_16x16x32_bf16 v[84:87], v[148:151], v[206:209], v[84:87]
	v_mfma_f32_16x16x32_bf16 v[80:83], v[170:173], v[206:209], v[80:83]
	v_mfma_f32_16x16x32_bf16 v[68:71], v[148:151], v[214:217], v[68:71]
	v_mfma_f32_16x16x32_bf16 v[64:67], v[170:173], v[214:217], v[64:67]
	s_setprio 0
	s_barrier
	s_add_i32 s3, s3, s33
	v_lshl_add_u64 v[182:183], v[182:183], 0, s[24:25]
	s_mov_b32 m0, s3
	ds_read_b128 v[174:177], v190 offset:49152
	ds_read_b128 v[178:181], v190 offset:50176
	ds_read_b128 v[194:197], v190 offset:51200
	ds_read_b128 v[198:201], v190 offset:52224
	ds_read_b128 v[202:205], v190 offset:53248
	ds_read_b128 v[206:209], v190 offset:54272
	ds_read_b128 v[210:213], v190 offset:55296
	ds_read_b128 v[214:217], v190 offset:56320
	global_load_lds_dwordx4 v[182:183], off
	s_add_i32 m0, s3, 0x2000
	s_add_u32 s38, s42, 0x158080
	v_lshl_add_u64 v[182:183], v[218:219], 0, s[24:25]
	s_addc_u32 s39, s43, 0
	s_add_i32 s3, s73, s33
	global_load_lds_dwordx4 v[182:183], off
	v_lshl_add_u64 v[182:183], s[38:39], 0, v[154:155]
	s_mov_b32 m0, s3
	s_nop 0
	global_load_lds_dwordx4 v[182:183], off
	v_lshl_add_u64 v[182:183], s[38:39], 0, v[158:159]
	s_add_i32 m0, s3, 0x2000
	s_nop 0
	global_load_lds_dwordx4 v[182:183], off
	v_lshl_add_u64 v[182:183], v[220:221], 0, s[24:25]
	s_mov_b32 m0, s56
	s_nop 0
	global_load_lds_dwordx4 v[182:183], off
	v_lshl_add_u64 v[182:183], v[222:223], 0, s[24:25]
	s_mov_b32 m0, s57
	s_nop 0
	global_load_lds_dwordx4 v[182:183], off
	s_waitcnt vmcnt(8)
	s_waitcnt lgkmcnt(0)
	s_setprio 1
	s_barrier
	v_mfma_f32_16x16x32_bf16 v[60:63], v[128:131], v[174:177], v[60:63]
	v_mfma_f32_16x16x32_bf16 v[56:59], v[136:139], v[174:177], v[56:59]
	v_mfma_f32_16x16x32_bf16 v[44:47], v[128:131], v[194:197], v[44:47]
	v_mfma_f32_16x16x32_bf16 v[40:43], v[136:139], v[194:197], v[40:43]
	v_mfma_f32_16x16x32_bf16 v[28:31], v[128:131], v[202:205], v[28:31]
	v_mfma_f32_16x16x32_bf16 v[24:27], v[136:139], v[202:205], v[24:27]
	v_mfma_f32_16x16x32_bf16 v[12:15], v[128:131], v[210:213], v[12:15]
	v_mfma_f32_16x16x32_bf16 v[8:11], v[136:139], v[210:213], v[8:11]
	v_mfma_f32_16x16x32_bf16 v[60:63], v[132:135], v[178:181], v[60:63]
	v_mfma_f32_16x16x32_bf16 v[56:59], v[140:143], v[178:181], v[56:59]
	v_mfma_f32_16x16x32_bf16 v[44:47], v[132:135], v[198:201], v[44:47]
	v_mfma_f32_16x16x32_bf16 v[40:43], v[140:143], v[198:201], v[40:43]
	v_mfma_f32_16x16x32_bf16 v[28:31], v[132:135], v[206:209], v[28:31]
	v_mfma_f32_16x16x32_bf16 v[24:27], v[140:143], v[206:209], v[24:27]
	v_mfma_f32_16x16x32_bf16 v[12:15], v[132:135], v[214:217], v[12:15]
	v_mfma_f32_16x16x32_bf16 v[8:11], v[140:143], v[214:217], v[8:11]
	s_setprio 0
	s_setprio 1
	v_mfma_f32_16x16x32_bf16 v[52:55], v[144:147], v[174:177], v[52:55]
	v_mfma_f32_16x16x32_bf16 v[48:51], v[166:169], v[174:177], v[48:51]
	v_mfma_f32_16x16x32_bf16 v[36:39], v[144:147], v[194:197], v[36:39]
	v_mfma_f32_16x16x32_bf16 v[32:35], v[166:169], v[194:197], v[32:35]
	v_mfma_f32_16x16x32_bf16 v[20:23], v[144:147], v[202:205], v[20:23]
	v_mfma_f32_16x16x32_bf16 v[16:19], v[166:169], v[202:205], v[16:19]
	v_mfma_f32_16x16x32_bf16 v[4:7], v[144:147], v[210:213], v[4:7]
	v_mfma_f32_16x16x32_bf16 v[0:3], v[166:169], v[210:213], v[0:3]
	v_mfma_f32_16x16x32_bf16 v[52:55], v[148:151], v[178:181], v[52:55]
	v_mfma_f32_16x16x32_bf16 v[48:51], v[170:173], v[178:181], v[48:51]
	v_mfma_f32_16x16x32_bf16 v[36:39], v[148:151], v[198:201], v[36:39]
	v_mfma_f32_16x16x32_bf16 v[32:35], v[170:173], v[198:201], v[32:35]
	v_mfma_f32_16x16x32_bf16 v[20:23], v[148:151], v[206:209], v[20:23]
	v_mfma_f32_16x16x32_bf16 v[16:19], v[170:173], v[206:209], v[16:19]
	v_mfma_f32_16x16x32_bf16 v[4:7], v[148:151], v[214:217], v[4:7]
	v_mfma_f32_16x16x32_bf16 v[0:3], v[170:173], v[214:217], v[0:3]
	s_setprio 0
	s_barrier
	s_add_i32 s1, s1, 2
	s_add_u32 s4, s4, 0x100
	s_addc_u32 s5, s5, 0
	s_cmpk_gt_u32 s1, 0x53
	s_mov_b64 s[38:39], s[40:41]
.LBB0_876:
	ds_read_b128 v[128:131], v188
	ds_read_b128 v[132:135], v188 offset:1024
	ds_read_b128 v[136:139], v188 offset:2048
	ds_read_b128 v[140:143], v188 offset:3072
	ds_read_b128 v[144:147], v189
	ds_read_b128 v[148:151], v189 offset:1024
	ds_read_b128 v[166:169], v189 offset:2048
	ds_read_b128 v[170:173], v189 offset:3072
	s_add_u32 s40, s38, 0x100
	s_addc_u32 s41, s39, 0
	s_cmpk_eq_i32 s1, 0x52
	s_cselect_b32 s45, s37, s41
	s_cselect_b32 s44, s36, s40
	s_cselect_b32 s43, s17, s5
	s_cselect_b32 s42, s16, s4
	v_lshl_add_u64 v[182:183], s[38:39], 0, v[160:161]
	s_add_i32 m0, s48, 0xc000
	ds_read_b128 v[174:177], v190
	ds_read_b128 v[178:181], v190 offset:1024
	ds_read_b128 v[194:197], v190 offset:2048
	ds_read_b128 v[198:201], v190 offset:3072
	ds_read_b128 v[202:205], v190 offset:4096
	ds_read_b128 v[206:209], v190 offset:5120
	ds_read_b128 v[210:213], v190 offset:6144
	ds_read_b128 v[214:217], v190 offset:7168
	global_load_lds_dwordx4 v[182:183], off
	v_lshl_add_u64 v[182:183], s[38:39], 0, v[162:163]
	s_add_i32 m0, s48, 0xe000
	s_nop 0
	global_load_lds_dwordx4 v[182:183], off
	s_waitcnt vmcnt(8)
	s_waitcnt lgkmcnt(0)
	s_setprio 1
	s_barrier
	v_mfma_f32_16x16x32_bf16 v[124:127], v[128:131], v[174:177], v[124:127]
	v_mfma_f32_16x16x32_bf16 v[120:123], v[136:139], v[174:177], v[120:123]
	v_mfma_f32_16x16x32_bf16 v[108:111], v[128:131], v[194:197], v[108:111]
	v_mfma_f32_16x16x32_bf16 v[104:107], v[136:139], v[194:197], v[104:107]
	v_mfma_f32_16x16x32_bf16 v[92:95], v[128:131], v[202:205], v[92:95]
	v_mfma_f32_16x16x32_bf16 v[88:91], v[136:139], v[202:205], v[88:91]
	v_mfma_f32_16x16x32_bf16 v[76:79], v[128:131], v[210:213], v[76:79]
	v_mfma_f32_16x16x32_bf16 v[72:75], v[136:139], v[210:213], v[72:75]
	v_mfma_f32_16x16x32_bf16 v[124:127], v[132:135], v[178:181], v[124:127]
	v_mfma_f32_16x16x32_bf16 v[120:123], v[140:143], v[178:181], v[120:123]
	v_mfma_f32_16x16x32_bf16 v[108:111], v[132:135], v[198:201], v[108:111]
	v_mfma_f32_16x16x32_bf16 v[104:107], v[140:143], v[198:201], v[104:107]
	v_mfma_f32_16x16x32_bf16 v[92:95], v[132:135], v[206:209], v[92:95]
	v_mfma_f32_16x16x32_bf16 v[88:91], v[140:143], v[206:209], v[88:91]
	v_mfma_f32_16x16x32_bf16 v[76:79], v[132:135], v[214:217], v[76:79]
	v_mfma_f32_16x16x32_bf16 v[72:75], v[140:143], v[214:217], v[72:75]
	s_setprio 0
	s_setprio 1
	v_mfma_f32_16x16x32_bf16 v[116:119], v[144:147], v[174:177], v[116:119]
	v_mfma_f32_16x16x32_bf16 v[112:115], v[166:169], v[174:177], v[112:115]
	v_mfma_f32_16x16x32_bf16 v[100:103], v[144:147], v[194:197], v[100:103]
	v_mfma_f32_16x16x32_bf16 v[96:99], v[166:169], v[194:197], v[96:99]
	v_mfma_f32_16x16x32_bf16 v[84:87], v[144:147], v[202:205], v[84:87]
	v_mfma_f32_16x16x32_bf16 v[80:83], v[166:169], v[202:205], v[80:83]
	v_mfma_f32_16x16x32_bf16 v[68:71], v[144:147], v[210:213], v[68:71]
	v_mfma_f32_16x16x32_bf16 v[64:67], v[166:169], v[210:213], v[64:67]
	v_mfma_f32_16x16x32_bf16 v[116:119], v[148:151], v[178:181], v[116:119]
	v_mfma_f32_16x16x32_bf16 v[112:115], v[170:173], v[178:181], v[112:115]
	v_mfma_f32_16x16x32_bf16 v[100:103], v[148:151], v[198:201], v[100:103]
	v_mfma_f32_16x16x32_bf16 v[96:99], v[170:173], v[198:201], v[96:99]
	v_mfma_f32_16x16x32_bf16 v[84:87], v[148:151], v[206:209], v[84:87]
	v_mfma_f32_16x16x32_bf16 v[80:83], v[170:173], v[206:209], v[80:83]
	v_mfma_f32_16x16x32_bf16 v[68:71], v[148:151], v[214:217], v[68:71]
	v_mfma_f32_16x16x32_bf16 v[64:67], v[170:173], v[214:217], v[64:67]
	s_setprio 0
	s_barrier
	s_add_i32 s3, s70, s33
	v_lshl_add_u64 v[182:183], s[42:43], 0, v[154:155]
	s_mov_b32 m0, s3
	ds_read_b128 v[174:177], v190 offset:16384
	ds_read_b128 v[178:181], v190 offset:17408
	ds_read_b128 v[194:197], v190 offset:18432
	ds_read_b128 v[198:201], v190 offset:19456
	ds_read_b128 v[202:205], v190 offset:20480
	ds_read_b128 v[206:209], v190 offset:21504
	ds_read_b128 v[210:213], v190 offset:22528
	ds_read_b128 v[214:217], v190 offset:23552
	global_load_lds_dwordx4 v[182:183], off
	s_add_i32 m0, s3, 0x2000
	s_add_u32 s38, s42, 0x158000
	v_lshl_add_u64 v[218:219], s[42:43], 0, v[158:159]
	s_addc_u32 s39, s43, 0
	s_add_i32 s3, s71, s33
	global_load_lds_dwordx4 v[218:219], off
	v_lshl_add_u64 v[220:221], s[38:39], 0, v[154:155]
	s_mov_b32 m0, s3
	v_lshl_add_u64 v[222:223], s[44:45], 0, v[156:157]
	global_load_lds_dwordx4 v[220:221], off
	v_lshl_add_u64 v[220:221], s[38:39], 0, v[158:159]
	s_add_i32 m0, s3, 0x2000
	s_nop 0
	global_load_lds_dwordx4 v[220:221], off
	v_lshl_add_u64 v[220:221], s[44:45], 0, v[152:153]
	s_mov_b32 m0, s48
	s_nop 0
	global_load_lds_dwordx4 v[220:221], off
	s_mov_b32 m0, s49
	s_nop 0
	global_load_lds_dwordx4 v[222:223], off
	s_waitcnt vmcnt(8)
	s_waitcnt lgkmcnt(0)
	s_setprio 1
	s_barrier
	v_mfma_f32_16x16x32_bf16 v[60:63], v[128:131], v[174:177], v[60:63]
	v_mfma_f32_16x16x32_bf16 v[56:59], v[136:139], v[174:177], v[56:59]
	v_mfma_f32_16x16x32_bf16 v[44:47], v[128:131], v[194:197], v[44:47]
	v_mfma_f32_16x16x32_bf16 v[40:43], v[136:139], v[194:197], v[40:43]
	v_mfma_f32_16x16x32_bf16 v[28:31], v[128:131], v[202:205], v[28:31]
	v_mfma_f32_16x16x32_bf16 v[24:27], v[136:139], v[202:205], v[24:27]
	v_mfma_f32_16x16x32_bf16 v[12:15], v[128:131], v[210:213], v[12:15]
	v_mfma_f32_16x16x32_bf16 v[8:11], v[136:139], v[210:213], v[8:11]
	v_mfma_f32_16x16x32_bf16 v[60:63], v[132:135], v[178:181], v[60:63]
	v_mfma_f32_16x16x32_bf16 v[56:59], v[140:143], v[178:181], v[56:59]
	v_mfma_f32_16x16x32_bf16 v[44:47], v[132:135], v[198:201], v[44:47]
	v_mfma_f32_16x16x32_bf16 v[40:43], v[140:143], v[198:201], v[40:43]
	v_mfma_f32_16x16x32_bf16 v[28:31], v[132:135], v[206:209], v[28:31]
	v_mfma_f32_16x16x32_bf16 v[24:27], v[140:143], v[206:209], v[24:27]
	v_mfma_f32_16x16x32_bf16 v[12:15], v[132:135], v[214:217], v[12:15]
	v_mfma_f32_16x16x32_bf16 v[8:11], v[140:143], v[214:217], v[8:11]
	s_setprio 0
	s_setprio 1
	v_mfma_f32_16x16x32_bf16 v[52:55], v[144:147], v[174:177], v[52:55]
	v_mfma_f32_16x16x32_bf16 v[48:51], v[166:169], v[174:177], v[48:51]
	v_mfma_f32_16x16x32_bf16 v[36:39], v[144:147], v[194:197], v[36:39]
	v_mfma_f32_16x16x32_bf16 v[32:35], v[166:169], v[194:197], v[32:35]
	v_mfma_f32_16x16x32_bf16 v[20:23], v[144:147], v[202:205], v[20:23]
	v_mfma_f32_16x16x32_bf16 v[16:19], v[166:169], v[202:205], v[16:19]
	v_mfma_f32_16x16x32_bf16 v[4:7], v[144:147], v[210:213], v[4:7]
	v_mfma_f32_16x16x32_bf16 v[0:3], v[166:169], v[210:213], v[0:3]
	v_mfma_f32_16x16x32_bf16 v[52:55], v[148:151], v[178:181], v[52:55]
	v_mfma_f32_16x16x32_bf16 v[48:51], v[170:173], v[178:181], v[48:51]
	v_mfma_f32_16x16x32_bf16 v[36:39], v[148:151], v[198:201], v[36:39]
	v_mfma_f32_16x16x32_bf16 v[32:35], v[170:173], v[198:201], v[32:35]
	v_mfma_f32_16x16x32_bf16 v[20:23], v[148:151], v[206:209], v[20:23]
	v_mfma_f32_16x16x32_bf16 v[16:19], v[170:173], v[206:209], v[16:19]
	v_mfma_f32_16x16x32_bf16 v[4:7], v[148:151], v[214:217], v[4:7]
	v_mfma_f32_16x16x32_bf16 v[0:3], v[170:173], v[214:217], v[0:3]
	s_setprio 0
	s_barrier
	s_add_i32 s3, 0, 0x18000
	s_add_i32 s73, 0, 0x1c000
	v_add_u32_e32 v140, s3, v187
	v_add_u32_e32 v170, s73, v187
	ds_read_b128 v[128:131], v140
	ds_read_b128 v[132:135], v140 offset:1024
	ds_read_b128 v[136:139], v140 offset:2048
	ds_read_b128 v[140:143], v140 offset:3072
	ds_read_b128 v[144:147], v170
	ds_read_b128 v[148:151], v170 offset:1024
	ds_read_b128 v[166:169], v170 offset:2048
	ds_read_b128 v[170:173], v170 offset:3072
	s_add_u32 s38, s44, 0x158000
	s_addc_u32 s39, s45, 0
	s_mov_b32 m0, s51
	v_lshl_add_u64 v[224:225], s[38:39], 0, v[152:153]
	ds_read_b128 v[174:177], v190 offset:32768
	ds_read_b128 v[178:181], v190 offset:33792
	ds_read_b128 v[194:197], v190 offset:34816
	ds_read_b128 v[198:201], v190 offset:35840
	ds_read_b128 v[202:205], v190 offset:36864
	ds_read_b128 v[206:209], v190 offset:37888
	ds_read_b128 v[210:213], v190 offset:38912
	ds_read_b128 v[214:217], v190 offset:39936
	global_load_lds_dwordx4 v[224:225], off
	v_lshl_add_u64 v[224:225], s[38:39], 0, v[156:157]
	s_mov_b32 m0, s52
	s_nop 0
	global_load_lds_dwordx4 v[224:225], off
	s_waitcnt vmcnt(8)
	s_waitcnt lgkmcnt(0)
	s_setprio 1
	s_barrier
	v_mfma_f32_16x16x32_bf16 v[124:127], v[128:131], v[174:177], v[124:127]
	v_mfma_f32_16x16x32_bf16 v[120:123], v[136:139], v[174:177], v[120:123]
	v_mfma_f32_16x16x32_bf16 v[108:111], v[128:131], v[194:197], v[108:111]
	v_mfma_f32_16x16x32_bf16 v[104:107], v[136:139], v[194:197], v[104:107]
	v_mfma_f32_16x16x32_bf16 v[92:95], v[128:131], v[202:205], v[92:95]
	v_mfma_f32_16x16x32_bf16 v[88:91], v[136:139], v[202:205], v[88:91]
	v_mfma_f32_16x16x32_bf16 v[76:79], v[128:131], v[210:213], v[76:79]
	v_mfma_f32_16x16x32_bf16 v[72:75], v[136:139], v[210:213], v[72:75]
	v_mfma_f32_16x16x32_bf16 v[124:127], v[132:135], v[178:181], v[124:127]
	v_mfma_f32_16x16x32_bf16 v[120:123], v[140:143], v[178:181], v[120:123]
	v_mfma_f32_16x16x32_bf16 v[108:111], v[132:135], v[198:201], v[108:111]
	v_mfma_f32_16x16x32_bf16 v[104:107], v[140:143], v[198:201], v[104:107]
	v_mfma_f32_16x16x32_bf16 v[92:95], v[132:135], v[206:209], v[92:95]
	v_mfma_f32_16x16x32_bf16 v[88:91], v[140:143], v[206:209], v[88:91]
	v_mfma_f32_16x16x32_bf16 v[76:79], v[132:135], v[214:217], v[76:79]
	v_mfma_f32_16x16x32_bf16 v[72:75], v[140:143], v[214:217], v[72:75]
	s_setprio 0
	s_setprio 1
	v_mfma_f32_16x16x32_bf16 v[116:119], v[144:147], v[174:177], v[116:119]
	v_mfma_f32_16x16x32_bf16 v[112:115], v[166:169], v[174:177], v[112:115]
	v_mfma_f32_16x16x32_bf16 v[100:103], v[144:147], v[194:197], v[100:103]
	v_mfma_f32_16x16x32_bf16 v[96:99], v[166:169], v[194:197], v[96:99]
	v_mfma_f32_16x16x32_bf16 v[84:87], v[144:147], v[202:205], v[84:87]
	v_mfma_f32_16x16x32_bf16 v[80:83], v[166:169], v[202:205], v[80:83]
	v_mfma_f32_16x16x32_bf16 v[68:71], v[144:147], v[210:213], v[68:71]
	v_mfma_f32_16x16x32_bf16 v[64:67], v[166:169], v[210:213], v[64:67]
	v_mfma_f32_16x16x32_bf16 v[116:119], v[148:151], v[178:181], v[116:119]
	v_mfma_f32_16x16x32_bf16 v[112:115], v[170:173], v[178:181], v[112:115]
	v_mfma_f32_16x16x32_bf16 v[100:103], v[148:151], v[198:201], v[100:103]
	v_mfma_f32_16x16x32_bf16 v[96:99], v[170:173], v[198:201], v[96:99]
	v_mfma_f32_16x16x32_bf16 v[84:87], v[148:151], v[206:209], v[84:87]
	v_mfma_f32_16x16x32_bf16 v[80:83], v[170:173], v[206:209], v[80:83]
	v_mfma_f32_16x16x32_bf16 v[68:71], v[148:151], v[214:217], v[68:71]
	v_mfma_f32_16x16x32_bf16 v[64:67], v[170:173], v[214:217], v[64:67]
	s_setprio 0
	s_barrier
	s_add_i32 s3, s3, s33
	v_lshl_add_u64 v[182:183], v[182:183], 0, s[24:25]
	s_mov_b32 m0, s3
	ds_read_b128 v[174:177], v190 offset:49152
	ds_read_b128 v[178:181], v190 offset:50176
	ds_read_b128 v[194:197], v190 offset:51200
	ds_read_b128 v[198:201], v190 offset:52224
	ds_read_b128 v[202:205], v190 offset:53248
	ds_read_b128 v[206:209], v190 offset:54272
	ds_read_b128 v[210:213], v190 offset:55296
	ds_read_b128 v[214:217], v190 offset:56320
	global_load_lds_dwordx4 v[182:183], off
	s_add_i32 m0, s3, 0x2000
	s_add_u32 s38, s42, 0x158080
	v_lshl_add_u64 v[182:183], v[218:219], 0, s[24:25]
	s_addc_u32 s39, s43, 0
	s_add_i32 s3, s73, s33
	global_load_lds_dwordx4 v[182:183], off
	v_lshl_add_u64 v[182:183], s[38:39], 0, v[154:155]
	s_mov_b32 m0, s3
	s_nop 0
	global_load_lds_dwordx4 v[182:183], off
	v_lshl_add_u64 v[182:183], s[38:39], 0, v[158:159]
	s_add_i32 m0, s3, 0x2000
	s_nop 0
	global_load_lds_dwordx4 v[182:183], off
	v_lshl_add_u64 v[182:183], v[220:221], 0, s[24:25]
	s_mov_b32 m0, s56
	s_nop 0
	global_load_lds_dwordx4 v[182:183], off
	v_lshl_add_u64 v[182:183], v[222:223], 0, s[24:25]
	s_mov_b32 m0, s57
	s_nop 0
	global_load_lds_dwordx4 v[182:183], off
	s_waitcnt vmcnt(8)
	s_waitcnt lgkmcnt(0)
	s_setprio 1
	s_barrier
	v_mfma_f32_16x16x32_bf16 v[60:63], v[128:131], v[174:177], v[60:63]
	v_mfma_f32_16x16x32_bf16 v[56:59], v[136:139], v[174:177], v[56:59]
	v_mfma_f32_16x16x32_bf16 v[44:47], v[128:131], v[194:197], v[44:47]
	v_mfma_f32_16x16x32_bf16 v[40:43], v[136:139], v[194:197], v[40:43]
	v_mfma_f32_16x16x32_bf16 v[28:31], v[128:131], v[202:205], v[28:31]
	v_mfma_f32_16x16x32_bf16 v[24:27], v[136:139], v[202:205], v[24:27]
	v_mfma_f32_16x16x32_bf16 v[12:15], v[128:131], v[210:213], v[12:15]
	v_mfma_f32_16x16x32_bf16 v[8:11], v[136:139], v[210:213], v[8:11]
	v_mfma_f32_16x16x32_bf16 v[60:63], v[132:135], v[178:181], v[60:63]
	v_mfma_f32_16x16x32_bf16 v[56:59], v[140:143], v[178:181], v[56:59]
	v_mfma_f32_16x16x32_bf16 v[44:47], v[132:135], v[198:201], v[44:47]
	v_mfma_f32_16x16x32_bf16 v[40:43], v[140:143], v[198:201], v[40:43]
	v_mfma_f32_16x16x32_bf16 v[28:31], v[132:135], v[206:209], v[28:31]
	v_mfma_f32_16x16x32_bf16 v[24:27], v[140:143], v[206:209], v[24:27]
	v_mfma_f32_16x16x32_bf16 v[12:15], v[132:135], v[214:217], v[12:15]
	v_mfma_f32_16x16x32_bf16 v[8:11], v[140:143], v[214:217], v[8:11]
	s_setprio 0
	s_setprio 1
	v_mfma_f32_16x16x32_bf16 v[52:55], v[144:147], v[174:177], v[52:55]
	v_mfma_f32_16x16x32_bf16 v[48:51], v[166:169], v[174:177], v[48:51]
	v_mfma_f32_16x16x32_bf16 v[36:39], v[144:147], v[194:197], v[36:39]
	v_mfma_f32_16x16x32_bf16 v[32:35], v[166:169], v[194:197], v[32:35]
	v_mfma_f32_16x16x32_bf16 v[20:23], v[144:147], v[202:205], v[20:23]
	v_mfma_f32_16x16x32_bf16 v[16:19], v[166:169], v[202:205], v[16:19]
	v_mfma_f32_16x16x32_bf16 v[4:7], v[144:147], v[210:213], v[4:7]
	v_mfma_f32_16x16x32_bf16 v[0:3], v[166:169], v[210:213], v[0:3]
	v_mfma_f32_16x16x32_bf16 v[52:55], v[148:151], v[178:181], v[52:55]
	v_mfma_f32_16x16x32_bf16 v[48:51], v[170:173], v[178:181], v[48:51]
	v_mfma_f32_16x16x32_bf16 v[36:39], v[148:151], v[198:201], v[36:39]
	v_mfma_f32_16x16x32_bf16 v[32:35], v[170:173], v[198:201], v[32:35]
	v_mfma_f32_16x16x32_bf16 v[20:23], v[148:151], v[206:209], v[20:23]
	v_mfma_f32_16x16x32_bf16 v[16:19], v[170:173], v[206:209], v[16:19]
	v_mfma_f32_16x16x32_bf16 v[4:7], v[148:151], v[214:217], v[4:7]
	v_mfma_f32_16x16x32_bf16 v[0:3], v[170:173], v[214:217], v[0:3]
	s_setprio 0
	s_barrier
	s_add_i32 s1, s1, 2
	s_add_u32 s4, s4, 0x100
	s_addc_u32 s5, s5, 0
	s_cmpk_gt_u32 s1, 0x53
	s_mov_b64 s[38:39], s[40:41]
	s_cbranch_scc0 .LBB0_876
	s_and_b64 vcc, exec, s[26:27]
	s_cbranch_vccz .LBB0_879
	s_barrier
